# GEMM epilogues: first global loads (row stats / conv weights / residual) issued before the leading half's align barrier
# speedup vs baseline: 1.0053x; 1.0011x over previous
; #define PG8_STAGE(bufoff, gbase, voff) do { _Pragma("unroll") for (int _i = 0; _i < 2; ++_i) \
;         __builtin_amdgcn_global_load_lds((const unsigned*)((const char*)(gbase) + (voff)[_i]), (LAS unsigned*)(lds + (bufoff) + ldsw + _i * 8192), 16, 0, 0); } while (0)
; #define PG8_LDA(dst, b, h) do { _Pragma("unroll") for (int m = 0; m < 4; ++m) _Pragma("unroll") for (int k = 0; k < 2; ++k) dst[m][k] = *(const LAS bf16x8*)(lds + PG8_SA(b, h) + aoff + m * 2048 + k * 1024); } while (0)
; #define PG8_LDB(dst, b, h) do { _Pragma("unroll") for (int n = 0; n < 2; ++n) _Pragma("unroll") for (int k = 0; k < 2; ++k) dst[n][k] = *(const LAS bf16x8*)(lds + PG8_SB(b, h) + boff + n * 2048 + k * 1024); } while (0)
; #define PG8_MMA(ai, bj, At, Bt) do { __builtin_amdgcn_s_setprio(1); _Pragma("unroll") for (int m = 0; m < 4; ++m) _Pragma("unroll") for (int n = 0; n < 2; ++n) _Pragma("unroll") for (int k = 0; k < 2; ++k) \
;         acc[ai][bj][m][n] = __builtin_amdgcn_mfma_f32_16x16x32_bf16(Bt[n][k], At[m][k], acc[ai][bj][m][n], 0, 0, 0); __builtin_amdgcn_s_setprio(0); } while (0)
; #define PG8_WAIT_V(n) asm volatile("s_waitcnt vmcnt(" #n ")" ::: "memory")
; #define PG8_WAIT_L(n) asm volatile("s_waitcnt lgkmcnt(" #n ")" ::: "memory")
; #define PG8_BAR __builtin_amdgcn_s_barrier()
; #define PG8_SCHED __builtin_amdgcn_sched_barrier(0)
; template <class Epi, bool SEG>
; __device__ __forceinline__ void gemm_phase(LAS unsigned char* lds, const Gemm g, const int G, const int cidx, const Epi& E) {
;     ...
;             PG8_LDB(B0, 0, 0); PG8_LDB(B1, 0, 1); PG8_SCHED; PG8_LDA(At, 0, 0); PG8_STAGE(PG8_SA(1, 1), a1 + hstepA, voffA);
;             PG8_WAIT_V(8); PG8_WAIT_L(0); PG8_BAR; PG8_MMA(0, 0, At, B0); PG8_MMA(0, 1, At, B1); PG8_BAR; PG8_SCHED;
;             PG8_LDA(At, 0, 1); PG8_STAGE(PG8_SB(0, 0), b2, voffB); PG8_STAGE(PG8_SB(0, 1), b2 + hstepB, voffB); PG8_STAGE(PG8_SA(0, 0), a2, voffA);
;             PG8_WAIT_V(8); PG8_WAIT_L(0); PG8_BAR; PG8_MMA(1, 0, At, B0); PG8_MMA(1, 1, At, B1); PG8_BAR; PG8_SCHED;
;             PG8_LDB(B0, 1, 0); PG8_LDB(B1, 1, 1); PG8_SCHED; PG8_LDA(At, 1, 0); PG8_STAGE(PG8_SA(0, 1), a2 + hstepA, voffA);
;             PG8_WAIT_V(8); PG8_WAIT_L(0); PG8_BAR; PG8_MMA(0, 0, At, B0); PG8_MMA(0, 1, At, B1); PG8_BAR; PG8_SCHED;
.LBB0_294:
	s_add_u32 s48, s46, 0xfffc0080
	s_addc_u32 s49, s47, -1
	s_add_i32 s63, 0, 0x10000
	s_cmp_eq_u32 s62, 12
	s_cselect_b32 s51, s7, s49
	s_cselect_b32 s50, s23, s48
	s_cselect_b32 s49, s21, s61
	s_cselect_b32 s48, s59, s60
	s_add_i32 s66, 0, 0x14000
	v_add_u32_e32 v146, s63, v175
	v_add_u32_e32 v170, s66, v175
	ds_read_b128 v[134:137], v146
	ds_read_b128 v[138:141], v146 offset:1024
	ds_read_b128 v[142:145], v146 offset:2048
	ds_read_b128 v[146:149], v146 offset:3072
	ds_read_b128 v[158:161], v170
	ds_read_b128 v[162:165], v170 offset:1024
	ds_read_b128 v[166:169], v170 offset:2048
	ds_read_b128 v[170:173], v170 offset:3072
	v_lshl_add_u64 v[200:201], s[46:47], 0, v[154:155]
	s_add_i32 m0, s39, 0xc000
	ds_read_b128 v[180:183], v179
	ds_read_b128 v[184:187], v179 offset:1024
	ds_read_b128 v[188:191], v179 offset:2048
	ds_read_b128 v[192:195], v179 offset:3072
	ds_read_b128 v[196:199], v179 offset:4096
	ds_read_b128 v[212:215], v179 offset:5120
	ds_read_b128 v[216:219], v179 offset:6144
	ds_read_b128 v[220:223], v179 offset:7168
	global_load_lds_dwordx4 v[200:201], off
	v_lshl_add_u64 v[200:201], s[46:47], 0, v[156:157]
	s_add_i32 m0, s39, 0xe000
	s_nop 0
	global_load_lds_dwordx4 v[200:201], off
	s_waitcnt vmcnt(8)
	s_waitcnt lgkmcnt(0)
	s_setprio 1
	s_barrier
	v_mfma_f32_16x16x32_bf16 v[130:133], v[134:137], v[180:183], v[130:133]
	v_mfma_f32_16x16x32_bf16 v[126:129], v[142:145], v[180:183], v[126:129]
	v_mfma_f32_16x16x32_bf16 v[118:121], v[134:137], v[188:191], v[118:121]
	v_mfma_f32_16x16x32_bf16 v[110:113], v[142:145], v[188:191], v[110:113]
	v_mfma_f32_16x16x32_bf16 v[102:105], v[134:137], v[196:199], v[102:105]
	v_mfma_f32_16x16x32_bf16 v[94:97], v[142:145], v[196:199], v[94:97]
	v_mfma_f32_16x16x32_bf16 v[86:89], v[134:137], v[216:219], v[86:89]
	v_mfma_f32_16x16x32_bf16 v[78:81], v[142:145], v[216:219], v[78:81]
	v_mfma_f32_16x16x32_bf16 v[130:133], v[138:141], v[184:187], v[130:133]
	v_mfma_f32_16x16x32_bf16 v[126:129], v[146:149], v[184:187], v[126:129]
	v_mfma_f32_16x16x32_bf16 v[118:121], v[138:141], v[192:195], v[118:121]
	v_mfma_f32_16x16x32_bf16 v[110:113], v[146:149], v[192:195], v[110:113]
	v_mfma_f32_16x16x32_bf16 v[102:105], v[138:141], v[212:215], v[102:105]
	v_mfma_f32_16x16x32_bf16 v[94:97], v[146:149], v[212:215], v[94:97]
	v_mfma_f32_16x16x32_bf16 v[86:89], v[138:141], v[220:223], v[86:89]
	v_mfma_f32_16x16x32_bf16 v[78:81], v[146:149], v[220:223], v[78:81]
	s_setprio 0
	s_setprio 1
	v_mfma_f32_16x16x32_bf16 v[122:125], v[158:161], v[180:183], v[122:125]
	v_mfma_f32_16x16x32_bf16 v[114:117], v[166:169], v[180:183], v[114:117]
	v_mfma_f32_16x16x32_bf16 v[106:109], v[158:161], v[188:191], v[106:109]
	v_mfma_f32_16x16x32_bf16 v[98:101], v[166:169], v[188:191], v[98:101]
	v_mfma_f32_16x16x32_bf16 v[90:93], v[158:161], v[196:199], v[90:93]
	v_mfma_f32_16x16x32_bf16 v[82:85], v[166:169], v[196:199], v[82:85]
	v_mfma_f32_16x16x32_bf16 v[74:77], v[158:161], v[216:219], v[74:77]
	v_mfma_f32_16x16x32_bf16 v[70:73], v[166:169], v[216:219], v[70:73]
	v_mfma_f32_16x16x32_bf16 v[122:125], v[162:165], v[184:187], v[122:125]
	v_mfma_f32_16x16x32_bf16 v[114:117], v[170:173], v[184:187], v[114:117]
	v_mfma_f32_16x16x32_bf16 v[106:109], v[162:165], v[192:195], v[106:109]
	v_mfma_f32_16x16x32_bf16 v[98:101], v[170:173], v[192:195], v[98:101]
	v_mfma_f32_16x16x32_bf16 v[90:93], v[162:165], v[212:215], v[90:93]
	v_mfma_f32_16x16x32_bf16 v[82:85], v[170:173], v[212:215], v[82:85]
	v_mfma_f32_16x16x32_bf16 v[74:77], v[162:165], v[220:223], v[74:77]
	v_mfma_f32_16x16x32_bf16 v[70:73], v[170:173], v[220:223], v[70:73]
	s_barrier
	s_setprio 0
	s_add_i32 s63, s63, s1
	v_lshl_add_u64 v[200:201], s[48:49], 0, v[0:1]
	s_mov_b32 m0, s63
	ds_read_b128 v[180:183], v179 offset:16384
	ds_read_b128 v[184:187], v179 offset:17408
	ds_read_b128 v[188:191], v179 offset:18432
	ds_read_b128 v[192:195], v179 offset:19456
	ds_read_b128 v[196:199], v179 offset:20480
	ds_read_b128 v[212:215], v179 offset:21504
	ds_read_b128 v[216:219], v179 offset:22528
	ds_read_b128 v[220:223], v179 offset:23552
	global_load_lds_dwordx4 v[200:201], off
	s_add_i32 m0, s63, 0x2000
	s_add_u32 s64, s48, 0x40000
	v_lshl_add_u64 v[224:225], s[48:49], 0, v[14:15]
	s_addc_u32 s65, s49, 0
	s_add_i32 s63, s66, s1
	global_load_lds_dwordx4 v[224:225], off
	v_lshl_add_u64 v[226:227], s[64:65], 0, v[0:1]
	s_mov_b32 m0, s63
	v_lshl_add_u64 v[228:229], s[50:51], 0, v[150:151]
	global_load_lds_dwordx4 v[226:227], off
	v_lshl_add_u64 v[226:227], s[64:65], 0, v[14:15]
	s_add_i32 m0, s63, 0x2000
	s_nop 0
	global_load_lds_dwordx4 v[226:227], off
	v_lshl_add_u64 v[226:227], s[50:51], 0, v[152:153]
	s_mov_b32 m0, s39
	s_nop 0
	global_load_lds_dwordx4 v[226:227], off
	s_mov_b32 m0, s52
	s_nop 0
	global_load_lds_dwordx4 v[228:229], off
	s_waitcnt vmcnt(8)
	s_waitcnt lgkmcnt(0)
	s_setprio 1
	s_barrier
; #define PG8_STAGE(bufoff, gbase, voff) do { _Pragma("unroll") for (int _i = 0; _i < 2; ++_i) \
;         __builtin_amdgcn_global_load_lds((const unsigned*)((const char*)(gbase) + (voff)[_i]), (LAS unsigned*)(lds + (bufoff) + ldsw + _i * 8192), 16, 0, 0); } while (0)
; #define PG8_LDA(dst, b, h) do { _Pragma("unroll") for (int m = 0; m < 4; ++m) _Pragma("unroll") for (int k = 0; k < 2; ++k) dst[m][k] = *(const LAS bf16x8*)(lds + PG8_SA(b, h) + aoff + m * 2048 + k * 1024); } while (0)
; #define PG8_LDB(dst, b, h) do { _Pragma("unroll") for (int n = 0; n < 2; ++n) _Pragma("unroll") for (int k = 0; k < 2; ++k) dst[n][k] = *(const LAS bf16x8*)(lds + PG8_SB(b, h) + boff + n * 2048 + k * 1024); } while (0)
; #define PG8_MMA(ai, bj, At, Bt) do { __builtin_amdgcn_s_setprio(1); _Pragma("unroll") for (int m = 0; m < 4; ++m) _Pragma("unroll") for (int n = 0; n < 2; ++n) _Pragma("unroll") for (int k = 0; k < 2; ++k) \
;         acc[ai][bj][m][n] = __builtin_amdgcn_mfma_f32_16x16x32_bf16(Bt[n][k], At[m][k], acc[ai][bj][m][n], 0, 0, 0); __builtin_amdgcn_s_setprio(0); } while (0)
; #define PG8_WAIT_V(n) asm volatile("s_waitcnt vmcnt(" #n ")" ::: "memory")
; #define PG8_WAIT_L(n) asm volatile("s_waitcnt lgkmcnt(" #n ")" ::: "memory")
; #define PG8_BAR __builtin_amdgcn_s_barrier()
; #define PG8_SCHED __builtin_amdgcn_sched_barrier(0)
; template <class Epi, bool SEG>
; __device__ __forceinline__ void gemm_phase(LAS unsigned char* lds, const Gemm g, const int G, const int cidx, const Epi& E) {
;     ...
;             PG8_LDA(At, 0, 1); PG8_STAGE(PG8_SB(0, 0), b2, voffB); PG8_STAGE(PG8_SB(0, 1), b2 + hstepB, voffB); PG8_STAGE(PG8_SA(0, 0), a2, voffA);
;             PG8_WAIT_V(8); PG8_WAIT_L(0); PG8_BAR; PG8_MMA(1, 0, At, B0); PG8_MMA(1, 1, At, B1); PG8_BAR; PG8_SCHED;
;             PG8_LDB(B0, 1, 0); PG8_LDB(B1, 1, 1); PG8_SCHED; PG8_LDA(At, 1, 0); PG8_STAGE(PG8_SA(0, 1), a2 + hstepA, voffA);
;             PG8_WAIT_V(8); PG8_WAIT_L(0); PG8_BAR; PG8_MMA(0, 0, At, B0); PG8_MMA(0, 1, At, B1); PG8_BAR; PG8_SCHED;
;             PG8_LDA(At, 1, 1); PG8_STAGE(PG8_SB(1, 0), b3, voffB); PG8_STAGE(PG8_SB(1, 1), b3 + hstepB, voffB); PG8_STAGE(PG8_SA(1, 0), a3, voffA);
	v_mfma_f32_16x16x32_bf16 v[66:69], v[134:137], v[180:183], v[66:69]
	v_mfma_f32_16x16x32_bf16 v[62:65], v[142:145], v[180:183], v[62:65]
	v_mfma_f32_16x16x32_bf16 v[54:57], v[134:137], v[188:191], v[54:57]
	v_mfma_f32_16x16x32_bf16 v[46:49], v[142:145], v[188:191], v[46:49]
	v_mfma_f32_16x16x32_bf16 v[38:41], v[134:137], v[196:199], v[38:41]
	v_mfma_f32_16x16x32_bf16 v[30:33], v[142:145], v[196:199], v[30:33]
	v_mfma_f32_16x16x32_bf16 v[22:25], v[134:137], v[216:219], v[22:25]
	v_mfma_f32_16x16x32_bf16 v[10:13], v[142:145], v[216:219], v[10:13]
	v_mfma_f32_16x16x32_bf16 v[66:69], v[138:141], v[184:187], v[66:69]
	v_mfma_f32_16x16x32_bf16 v[62:65], v[146:149], v[184:187], v[62:65]
	v_mfma_f32_16x16x32_bf16 v[54:57], v[138:141], v[192:195], v[54:57]
	v_mfma_f32_16x16x32_bf16 v[46:49], v[146:149], v[192:195], v[46:49]
	v_mfma_f32_16x16x32_bf16 v[38:41], v[138:141], v[212:215], v[38:41]
	v_mfma_f32_16x16x32_bf16 v[30:33], v[146:149], v[212:215], v[30:33]
	v_mfma_f32_16x16x32_bf16 v[22:25], v[138:141], v[220:223], v[22:25]
	v_mfma_f32_16x16x32_bf16 v[10:13], v[146:149], v[220:223], v[10:13]
	s_setprio 0
	s_setprio 1
	v_mfma_f32_16x16x32_bf16 v[58:61], v[158:161], v[180:183], v[58:61]
	v_mfma_f32_16x16x32_bf16 v[50:53], v[166:169], v[180:183], v[50:53]
	v_mfma_f32_16x16x32_bf16 v[42:45], v[158:161], v[188:191], v[42:45]
	v_mfma_f32_16x16x32_bf16 v[34:37], v[166:169], v[188:191], v[34:37]
	v_mfma_f32_16x16x32_bf16 v[26:29], v[158:161], v[196:199], v[26:29]
	v_mfma_f32_16x16x32_bf16 v[18:21], v[166:169], v[196:199], v[18:21]
	v_mfma_f32_16x16x32_bf16 v[6:9], v[158:161], v[216:219], v[6:9]
	v_mfma_f32_16x16x32_bf16 v[2:5], v[166:169], v[216:219], v[2:5]
	v_mfma_f32_16x16x32_bf16 v[58:61], v[162:165], v[184:187], v[58:61]
	v_mfma_f32_16x16x32_bf16 v[50:53], v[170:173], v[184:187], v[50:53]
	v_mfma_f32_16x16x32_bf16 v[42:45], v[162:165], v[192:195], v[42:45]
	v_mfma_f32_16x16x32_bf16 v[34:37], v[170:173], v[192:195], v[34:37]
	v_mfma_f32_16x16x32_bf16 v[26:29], v[162:165], v[212:215], v[26:29]
	v_mfma_f32_16x16x32_bf16 v[18:21], v[170:173], v[212:215], v[18:21]
	v_mfma_f32_16x16x32_bf16 v[6:9], v[162:165], v[220:223], v[6:9]
	v_mfma_f32_16x16x32_bf16 v[2:5], v[170:173], v[220:223], v[2:5]
	s_barrier
	s_setprio 0
	s_add_i32 s63, 0, 0x18000
	s_add_i32 s64, 0, 0x1c000
	v_add_u32_e32 v146, s63, v175
	v_add_u32_e32 v170, s64, v175
	ds_read_b128 v[134:137], v146
	ds_read_b128 v[138:141], v146 offset:1024
	ds_read_b128 v[142:145], v146 offset:2048
	ds_read_b128 v[146:149], v146 offset:3072
	ds_read_b128 v[158:161], v170
	ds_read_b128 v[162:165], v170 offset:1024
	ds_read_b128 v[166:169], v170 offset:2048
	ds_read_b128 v[170:173], v170 offset:3072
	s_add_u32 s50, s50, 0x40000
	s_addc_u32 s51, s51, 0
	s_mov_b32 m0, s53
	v_lshl_add_u64 v[244:245], s[50:51], 0, v[152:153]
	ds_read_b128 v[180:183], v179 offset:32768
	ds_read_b128 v[184:187], v179 offset:33792
	ds_read_b128 v[188:191], v179 offset:34816
	ds_read_b128 v[192:195], v179 offset:35840
	ds_read_b128 v[196:199], v179 offset:36864
	ds_read_b128 v[212:215], v179 offset:37888
	ds_read_b128 v[216:219], v179 offset:38912
	ds_read_b128 v[220:223], v179 offset:39936
	global_load_lds_dwordx4 v[244:245], off
	v_lshl_add_u64 v[244:245], s[50:51], 0, v[150:151]
	s_mov_b32 m0, s54
	s_nop 0
	global_load_lds_dwordx4 v[244:245], off
	s_waitcnt vmcnt(8)
	s_waitcnt lgkmcnt(0)
	s_setprio 1
	s_barrier
	v_mfma_f32_16x16x32_bf16 v[130:133], v[134:137], v[180:183], v[130:133]
	v_mfma_f32_16x16x32_bf16 v[126:129], v[142:145], v[180:183], v[126:129]
	v_mfma_f32_16x16x32_bf16 v[118:121], v[134:137], v[188:191], v[118:121]
	v_mfma_f32_16x16x32_bf16 v[110:113], v[142:145], v[188:191], v[110:113]
	v_mfma_f32_16x16x32_bf16 v[102:105], v[134:137], v[196:199], v[102:105]
	v_mfma_f32_16x16x32_bf16 v[94:97], v[142:145], v[196:199], v[94:97]
	v_mfma_f32_16x16x32_bf16 v[86:89], v[134:137], v[216:219], v[86:89]
	v_mfma_f32_16x16x32_bf16 v[78:81], v[142:145], v[216:219], v[78:81]
	v_mfma_f32_16x16x32_bf16 v[130:133], v[138:141], v[184:187], v[130:133]
	v_mfma_f32_16x16x32_bf16 v[126:129], v[146:149], v[184:187], v[126:129]
	v_mfma_f32_16x16x32_bf16 v[118:121], v[138:141], v[192:195], v[118:121]
	v_mfma_f32_16x16x32_bf16 v[110:113], v[146:149], v[192:195], v[110:113]
	v_mfma_f32_16x16x32_bf16 v[102:105], v[138:141], v[212:215], v[102:105]
	v_mfma_f32_16x16x32_bf16 v[94:97], v[146:149], v[212:215], v[94:97]
	v_mfma_f32_16x16x32_bf16 v[86:89], v[138:141], v[220:223], v[86:89]
	v_mfma_f32_16x16x32_bf16 v[78:81], v[146:149], v[220:223], v[78:81]
	s_setprio 0
	s_setprio 1
	v_mfma_f32_16x16x32_bf16 v[122:125], v[158:161], v[180:183], v[122:125]
	v_mfma_f32_16x16x32_bf16 v[114:117], v[166:169], v[180:183], v[114:117]
	v_mfma_f32_16x16x32_bf16 v[106:109], v[158:161], v[188:191], v[106:109]
	v_mfma_f32_16x16x32_bf16 v[98:101], v[166:169], v[188:191], v[98:101]
	v_mfma_f32_16x16x32_bf16 v[90:93], v[158:161], v[196:199], v[90:93]
	v_mfma_f32_16x16x32_bf16 v[82:85], v[166:169], v[196:199], v[82:85]
	v_mfma_f32_16x16x32_bf16 v[74:77], v[158:161], v[216:219], v[74:77]
	v_mfma_f32_16x16x32_bf16 v[70:73], v[166:169], v[216:219], v[70:73]
	v_mfma_f32_16x16x32_bf16 v[122:125], v[162:165], v[184:187], v[122:125]
	v_mfma_f32_16x16x32_bf16 v[114:117], v[170:173], v[184:187], v[114:117]
	v_mfma_f32_16x16x32_bf16 v[106:109], v[162:165], v[192:195], v[106:109]
	v_mfma_f32_16x16x32_bf16 v[98:101], v[170:173], v[192:195], v[98:101]
	v_mfma_f32_16x16x32_bf16 v[90:93], v[162:165], v[212:215], v[90:93]
	v_mfma_f32_16x16x32_bf16 v[82:85], v[170:173], v[212:215], v[82:85]
	v_mfma_f32_16x16x32_bf16 v[74:77], v[162:165], v[220:223], v[74:77]
	v_mfma_f32_16x16x32_bf16 v[70:73], v[170:173], v[220:223], v[70:73]
	s_barrier
; #define PG8_STAGE(bufoff, gbase, voff) do { _Pragma("unroll") for (int _i = 0; _i < 2; ++_i) \
;         __builtin_amdgcn_global_load_lds((const unsigned*)((const char*)(gbase) + (voff)[_i]), (LAS unsigned*)(lds + (bufoff) + ldsw + _i * 8192), 16, 0, 0); } while (0)
; #define PG8_LDA(dst, b, h) do { _Pragma("unroll") for (int m = 0; m < 4; ++m) _Pragma("unroll") for (int k = 0; k < 2; ++k) dst[m][k] = *(const LAS bf16x8*)(lds + PG8_SA(b, h) + aoff + m * 2048 + k * 1024); } while (0)
; #define PG8_MMA(ai, bj, At, Bt) do { __builtin_amdgcn_s_setprio(1); _Pragma("unroll") for (int m = 0; m < 4; ++m) _Pragma("unroll") for (int n = 0; n < 2; ++n) _Pragma("unroll") for (int k = 0; k < 2; ++k) \
;         acc[ai][bj][m][n] = __builtin_amdgcn_mfma_f32_16x16x32_bf16(Bt[n][k], At[m][k], acc[ai][bj][m][n], 0, 0, 0); __builtin_amdgcn_s_setprio(0); } while (0)
; #define PG8_WAIT_V(n) asm volatile("s_waitcnt vmcnt(" #n ")" ::: "memory")
; #define PG8_WAIT_L(n) asm volatile("s_waitcnt lgkmcnt(" #n ")" ::: "memory")
; #define PG8_BAR __builtin_amdgcn_s_barrier()
; #define PG8_SCHED __builtin_amdgcn_sched_barrier(0)
;     __device__ __forceinline__ void operator()(f32x4 (&acc)[2][2][4][2], const Unit& u, int wr, int wc, int fr, int fq) const {
;     ...
;         if (SCALE) { f32x4 q[8];
; #pragma unroll
;             for (int i = 0; i < 8; ++i) q[i] = *(const f32x4*)(ss + (size_t)(row0 + (i >> 2) * HALF + (i & 3) * 16) * 4);
; template <class Epi, bool SEG>
; __device__ __forceinline__ void gemm_phase(LAS unsigned char* lds, const Gemm g, const int G, const int cidx, const Epi& E) {
;     ...
;             PG8_LDA(At, 1, 1); PG8_STAGE(PG8_SB(1, 0), b3, voffB); PG8_STAGE(PG8_SB(1, 1), b3 + hstepB, voffB); PG8_STAGE(PG8_SA(1, 0), a3, voffA);
;             PG8_WAIT_V(8); PG8_WAIT_L(0); PG8_BAR; PG8_MMA(1, 0, At, B0); PG8_MMA(1, 1, At, B1); PG8_BAR; PG8_SCHED;
;         }
;         if (wr == 0) PG8_BAR;
	s_setprio 0
	s_add_i32 s50, s63, s1
	v_lshl_add_u64 v[200:201], v[200:201], 0, s[28:29]
	s_mov_b32 m0, s50
	ds_read_b128 v[180:183], v179 offset:49152
	ds_read_b128 v[184:187], v179 offset:50176
	ds_read_b128 v[188:191], v179 offset:51200
	ds_read_b128 v[192:195], v179 offset:52224
	ds_read_b128 v[196:199], v179 offset:53248
	ds_read_b128 v[212:215], v179 offset:54272
	ds_read_b128 v[216:219], v179 offset:55296
	ds_read_b128 v[220:223], v179 offset:56320
	global_load_lds_dwordx4 v[200:201], off
	s_add_i32 m0, s50, 0x2000
	s_add_u32 s48, s48, 0x40080
	v_lshl_add_u64 v[200:201], v[224:225], 0, s[28:29]
	s_addc_u32 s49, s49, 0
	s_add_i32 s50, s64, s1
	global_load_lds_dwordx4 v[200:201], off
	v_lshl_add_u64 v[200:201], s[48:49], 0, v[0:1]
	s_mov_b32 m0, s50
	s_nop 0
	global_load_lds_dwordx4 v[200:201], off
	v_lshl_add_u64 v[200:201], s[48:49], 0, v[14:15]
	s_add_i32 m0, s50, 0x2000
	s_nop 0
	global_load_lds_dwordx4 v[200:201], off
	v_lshl_add_u64 v[200:201], v[226:227], 0, s[28:29]
	s_mov_b32 m0, s55
	s_nop 0
	global_load_lds_dwordx4 v[200:201], off
	v_lshl_add_u64 v[200:201], v[228:229], 0, s[28:29]
	s_mov_b32 m0, s56
	s_nop 0
	global_load_lds_dwordx4 v[200:201], off
	s_waitcnt vmcnt(8)
	s_waitcnt lgkmcnt(0)
	s_setprio 1
	s_barrier
	v_mfma_f32_16x16x32_bf16 v[66:69], v[134:137], v[180:183], v[66:69]
	v_mfma_f32_16x16x32_bf16 v[62:65], v[142:145], v[180:183], v[62:65]
	v_mfma_f32_16x16x32_bf16 v[54:57], v[134:137], v[188:191], v[54:57]
	v_mfma_f32_16x16x32_bf16 v[46:49], v[142:145], v[188:191], v[46:49]
	v_mfma_f32_16x16x32_bf16 v[38:41], v[134:137], v[196:199], v[38:41]
	v_mfma_f32_16x16x32_bf16 v[30:33], v[142:145], v[196:199], v[30:33]
	v_mfma_f32_16x16x32_bf16 v[22:25], v[134:137], v[216:219], v[22:25]
	v_mfma_f32_16x16x32_bf16 v[10:13], v[142:145], v[216:219], v[10:13]
	v_mfma_f32_16x16x32_bf16 v[66:69], v[138:141], v[184:187], v[66:69]
	v_mfma_f32_16x16x32_bf16 v[62:65], v[146:149], v[184:187], v[62:65]
	v_mfma_f32_16x16x32_bf16 v[54:57], v[138:141], v[192:195], v[54:57]
	v_mfma_f32_16x16x32_bf16 v[46:49], v[146:149], v[192:195], v[46:49]
	v_mfma_f32_16x16x32_bf16 v[38:41], v[138:141], v[212:215], v[38:41]
	v_mfma_f32_16x16x32_bf16 v[30:33], v[146:149], v[212:215], v[30:33]
	v_mfma_f32_16x16x32_bf16 v[22:25], v[138:141], v[220:223], v[22:25]
	v_mfma_f32_16x16x32_bf16 v[10:13], v[146:149], v[220:223], v[10:13]
	s_setprio 0
	s_setprio 1
	v_mfma_f32_16x16x32_bf16 v[58:61], v[158:161], v[180:183], v[58:61]
	v_mfma_f32_16x16x32_bf16 v[50:53], v[166:169], v[180:183], v[50:53]
	v_mfma_f32_16x16x32_bf16 v[42:45], v[158:161], v[188:191], v[42:45]
	v_mfma_f32_16x16x32_bf16 v[34:37], v[166:169], v[188:191], v[34:37]
	v_mfma_f32_16x16x32_bf16 v[26:29], v[158:161], v[196:199], v[26:29]
	v_mfma_f32_16x16x32_bf16 v[18:21], v[166:169], v[196:199], v[18:21]
	v_mfma_f32_16x16x32_bf16 v[6:9], v[158:161], v[216:219], v[6:9]
	v_mfma_f32_16x16x32_bf16 v[2:5], v[166:169], v[216:219], v[2:5]
	v_mfma_f32_16x16x32_bf16 v[58:61], v[162:165], v[184:187], v[58:61]
	v_mfma_f32_16x16x32_bf16 v[50:53], v[170:173], v[184:187], v[50:53]
	v_mfma_f32_16x16x32_bf16 v[42:45], v[162:165], v[192:195], v[42:45]
	v_mfma_f32_16x16x32_bf16 v[34:37], v[170:173], v[192:195], v[34:37]
	v_mfma_f32_16x16x32_bf16 v[26:29], v[162:165], v[212:215], v[26:29]
	v_mfma_f32_16x16x32_bf16 v[18:21], v[170:173], v[212:215], v[18:21]
	v_mfma_f32_16x16x32_bf16 v[6:9], v[162:165], v[220:223], v[6:9]
	v_mfma_f32_16x16x32_bf16 v[2:5], v[170:173], v[220:223], v[2:5]
	s_barrier
	s_setprio 0
	s_add_i32 s62, s62, 2
	s_add_u32 s46, s46, 0x100
	s_addc_u32 s47, s47, 0
	s_add_u32 s60, s60, 0x100
	s_addc_u32 s61, s61, 0
	s_cmp_gt_u32 s62, 13
	s_cbranch_scc0 .LBB0_294
	v_lshl_add_u32 v172, s6, 8, v17
	v_readlane_b32 s6, v252, 28
	v_ashrrev_i32_e32 v173, 31, v172
	v_readlane_b32 s7, v252, 29
	v_or_b32_e32 v170, 16, v172
	v_ashrrev_i32_e32 v171, 31, v170
	v_lshl_add_u64 v[134:135], v[172:173], 4, s[6:7]
	global_load_dwordx4 v[180:183], v[134:135], off
	v_lshl_add_u64 v[134:135], v[170:171], 4, s[6:7]
	global_load_dwordx4 v[184:187], v[134:135], off
	v_or_b32_e32 v168, 32, v172
	v_ashrrev_i32_e32 v169, 31, v168
	v_or_b32_e32 v166, 48, v172
	v_lshl_add_u64 v[134:135], v[168:169], 4, s[6:7]
	v_ashrrev_i32_e32 v167, 31, v166
	global_load_dwordx4 v[188:191], v[134:135], off
	v_lshl_add_u64 v[134:135], v[166:167], 4, s[6:7]
	global_load_dwordx4 v[192:195], v[134:135], off
	v_add_u32_e32 v164, 0x80, v172
	v_ashrrev_i32_e32 v165, 31, v164
	v_add_u32_e32 v162, 0x90, v172
	v_lshl_add_u64 v[134:135], v[164:165], 4, s[6:7]
	v_ashrrev_i32_e32 v163, 31, v162
	global_load_dwordx4 v[146:149], v[134:135], off
	v_lshl_add_u64 v[134:135], v[162:163], 4, s[6:7]
	global_load_dwordx4 v[142:145], v[134:135], off
	v_add_u32_e32 v160, 0xa0, v172
	v_ashrrev_i32_e32 v161, 31, v160
	v_add_u32_e32 v158, 0xb0, v172
	v_lshl_add_u64 v[134:135], v[160:161], 4, s[6:7]
	v_ashrrev_i32_e32 v159, 31, v158
	global_load_dwordx4 v[138:141], v[134:135], off
	v_lshl_add_u64 v[134:135], v[158:159], 4, s[6:7]
	global_load_dwordx4 v[134:137], v[134:135], off
	s_and_b64 vcc, exec, s[18:19]
	s_cbranch_vccz .LBB0_297
	s_barrier
; __device__ __forceinline__ unsigned cvtpk(float lo, float hi) { f32x2_t v = {lo, hi}; bf16x2_t b = __builtin_convertvector(v, bf16x2_t); return __builtin_bit_cast(unsigned, b); }
;     __device__ __forceinline__ void operator()(f32x4 (&acc)[2][2][4][2], const Unit& u, int wr, int wc, int fr, int fq) const {
;     ...
;             for (int i = 0; i < 8; ++i) q[i] = *(const f32x4*)(ss + (size_t)(row0 + (i >> 2) * HALF + (i & 3) * 16) * 4);
; #pragma unroll
;             for (int i = 0; i < 8; ++i) rsv[i] = rsqrtf(((q[i][0] + q[i][1]) + (q[i][2] + q[i][3])) * (1.f / DM) + EPS); }
; #pragma unroll
;         for (int ai = 0; ai < 2; ++ai)
; #pragma unroll
;             for (int m = 0; m < 4; ++m) { const int row = row0 + ai * HALF + m * 16; bf16_t* rowp = O + (size_t)row * ldc + col0;
;                 const float rs = SCALE ? rsv[ai * 4 + m] : 1.f;
; #pragma unroll
;                 for (int bj = 0; bj < 2; ++bj) { const f32x4 v0 = acc[ai][bj][m][0] * rs, v1 = acc[ai][bj][m][1] * rs;
;                     u32x4 w; w.x = cvtpk(v0[0], v0[1]); w.y = cvtpk(v0[2], v0[3]); w.z = cvtpk(v1[0], v1[1]); w.w = cvtpk(v1[2], v1[3]);
;                     *(u32x4*)(rowp + bj * HALF) = w; } }
.LBB0_297:
	s_mov_b32 s6, 0x358637bd
	s_mov_b32 s46, 0x3a800000
	s_mov_b32 s21, 0x800000
	s_waitcnt vmcnt(0)
	v_mov_b32_e32 v196, v181
	v_mov_b32_e32 v197, v182
	v_mov_b32_e32 v181, v183
	v_mov_b32_e32 v182, v185
	v_mov_b32_e32 v183, v186
	v_mov_b32_e32 v185, v187
	v_pk_add_f32 v[180:181], v[196:197], v[180:181]
	v_pk_add_f32 v[182:183], v[182:183], v[184:185]
	v_mov_b32_e32 v185, v180
	v_mov_b32_e32 v184, v182
	v_mov_b32_e32 v180, v183
	v_pk_add_f32 v[180:181], v[184:185], v[180:181]
	v_mov_b64_e32 v[182:183], s[6:7]
	v_pk_fma_f32 v[180:181], v[180:181], s[46:47], v[182:183] op_sel_hi:[1,0,0]
	v_mov_b32_e32 v184, v193
	v_mul_f32_e32 v174, 0x4b800000, v181
	v_cmp_gt_f32_e64 s[6:7], s21, v181
	v_cmp_gt_f32_e32 vcc, s21, v180
	v_mov_b32_e32 v185, v194
	v_cndmask_b32_e64 v174, v181, v174, s[6:7]
	v_rsq_f32_e32 v174, v174
	v_mov_b32_e32 v181, v190
	v_mov_b32_e32 v193, v195
	v_pk_add_f32 v[184:185], v[184:185], v[192:193]
	v_mul_f32_e32 v176, 0x45800000, v174
	v_cndmask_b32_e64 v178, v174, v176, s[6:7]
	v_mul_f32_e32 v174, 0x4b800000, v180
	v_cndmask_b32_e32 v174, v180, v174, vcc
	v_rsq_f32_e32 v174, v174
	v_mov_b32_e32 v180, v189
	v_mov_b32_e32 v189, v191
	v_pk_add_f32 v[180:181], v[180:181], v[188:189]
	v_mov_b32_e32 v186, v184
	v_mov_b32_e32 v187, v180
	v_mov_b32_e32 v180, v185
	v_pk_add_f32 v[180:181], v[186:187], v[180:181]
	v_mul_f32_e32 v176, 0x45800000, v174
	v_pk_fma_f32 v[184:185], v[180:181], s[46:47], v[182:183] op_sel_hi:[1,0,0]
	v_cndmask_b32_e32 v174, v174, v176, vcc
	v_mul_f32_e32 v176, 0x4b800000, v185
	v_cmp_gt_f32_e64 s[6:7], s21, v185
	v_cmp_gt_f32_e32 vcc, s21, v184
	v_pk_mul_f32 v[132:133], v[132:133], v[178:179] op_sel_hi:[1,0]
	v_cndmask_b32_e64 v176, v185, v176, s[6:7]
	v_rsq_f32_e32 v176, v176
	v_mov_b32_e32 v185, v148
	v_mov_b32_e32 v148, v143
	v_mov_b32_e32 v143, v145
	v_mul_f32_e32 v180, 0x45800000, v176
	v_cndmask_b32_e64 v180, v176, v180, s[6:7]
	v_mul_f32_e32 v176, 0x4b800000, v184
	v_cndmask_b32_e32 v176, v184, v176, vcc
	v_mov_b32_e32 v184, v147
	v_mov_b32_e32 v147, v149
	v_mov_b32_e32 v149, v144
	v_pk_add_f32 v[146:147], v[184:185], v[146:147]
	v_pk_add_f32 v[142:143], v[148:149], v[142:143]
	v_mov_b32_e32 v145, v146
	v_mov_b32_e32 v144, v142
	v_mov_b32_e32 v146, v143
	v_pk_add_f32 v[142:143], v[144:145], v[146:147]
	v_rsq_f32_e32 v176, v176
	v_pk_fma_f32 v[142:143], v[142:143], s[46:47], v[182:183] op_sel_hi:[1,0,0]
	v_mov_b32_e32 v146, v139
	v_mul_f32_e32 v144, 0x4b800000, v143
	v_cmp_gt_f32_e64 s[6:7], s21, v143
	v_mov_b32_e32 v147, v140
	v_mov_b32_e32 v139, v141
	v_cndmask_b32_e64 v143, v143, v144, s[6:7]
	v_rsq_f32_e32 v143, v143
	v_mov_b32_e32 v140, v135
	v_mov_b32_e32 v141, v136
	v_mov_b32_e32 v135, v137
	v_pk_add_f32 v[138:139], v[146:147], v[138:139]
	v_pk_add_f32 v[134:135], v[140:141], v[134:135]
	v_mov_b32_e32 v137, v138
	v_mov_b32_e32 v136, v134
	v_mov_b32_e32 v138, v135
	v_pk_add_f32 v[134:135], v[136:137], v[138:139]
	v_mul_f32_e32 v181, 0x45800000, v176
	v_mul_f32_e32 v144, 0x45800000, v143
	v_pk_fma_f32 v[134:135], v[134:135], s[46:47], v[182:183] op_sel_hi:[1,0,0]
	v_cndmask_b32_e32 v176, v176, v181, vcc
	v_cmp_gt_f32_e32 vcc, s21, v142
	v_cndmask_b32_e64 v144, v143, v144, s[6:7]
	v_mul_f32_e32 v143, 0x4b800000, v142
	v_mul_f32_e32 v136, 0x4b800000, v135
	v_cmp_gt_f32_e64 s[6:7], s21, v135
	v_cndmask_b32_e32 v142, v142, v143, vcc
	v_rsq_f32_e32 v142, v142
	v_cndmask_b32_e64 v135, v135, v136, s[6:7]
	v_rsq_f32_e32 v135, v135
	v_lshl_or_b32 v138, s58, 8, v177
	v_mul_f32_e32 v143, 0x45800000, v142
	v_cndmask_b32_e32 v142, v142, v143, vcc
	v_mul_f32_e32 v136, 0x45800000, v135
	v_cmp_gt_f32_e32 vcc, s21, v134
	v_cndmask_b32_e64 v136, v135, v136, s[6:7]
	v_mul_f32_e32 v135, 0x4b800000, v134
	v_cndmask_b32_e32 v134, v134, v135, vcc
	v_rsq_f32_e32 v134, v134
	v_mul_lo_u32 v137, s15, v172
	v_mad_u64_u32 v[140:141], s[6:7], s14, v172, 0
	v_mul_f32_e32 v135, 0x45800000, v134
	v_cndmask_b32_e32 v134, v134, v135, vcc
	v_mul_lo_u32 v135, s14, v173
	v_ashrrev_i32_e32 v139, 31, v138
	v_add3_u32 v141, v141, v135, v137
	v_lshl_add_u64 v[140:141], v[140:141], 1, s[4:5]
	v_lshlrev_b64 v[138:139], 1, v[138:139]
	v_pk_mul_f32 v[130:131], v[130:131], v[178:179] op_sel_hi:[1,0]
	v_pk_mul_f32 v[146:147], v[128:129], v[178:179] op_sel_hi:[1,0]
	v_pk_mul_f32 v[128:129], v[126:127], v[178:179] op_sel_hi:[1,0]
	v_lshl_add_u64 v[140:141], v[140:141], 0, v[138:139]
	v_cvt_pk_bf16_f32 v126, v130, v131
	v_cvt_pk_bf16_f32 v127, v132, v133
	v_cvt_pk_bf16_f32 v128, v128, v129
	v_cvt_pk_bf16_f32 v129, v146, v147
	global_store_dwordx4 v[140:141], v[126:129], off
	v_pk_mul_f32 v[124:125], v[124:125], v[178:179] op_sel_hi:[1,0]
	v_pk_mul_f32 v[122:123], v[122:123], v[178:179] op_sel_hi:[1,0]
	v_pk_mul_f32 v[126:127], v[116:117], v[178:179] op_sel_hi:[1,0]
	v_pk_mul_f32 v[116:117], v[114:115], v[178:179] op_sel_hi:[1,0]
	v_cvt_pk_bf16_f32 v114, v122, v123
	v_cvt_pk_bf16_f32 v115, v124, v125
	v_cvt_pk_bf16_f32 v116, v116, v117
	v_cvt_pk_bf16_f32 v117, v126, v127
	global_store_dwordx4 v[140:141], v[114:117], off offset:256
	v_pk_mul_f32 v[118:119], v[118:119], v[174:175] op_sel_hi:[1,0]
	v_pk_mul_f32 v[108:109], v[108:109], v[174:175] op_sel_hi:[1,0]
	v_mul_lo_u32 v116, s14, v171
	v_mul_lo_u32 v117, s15, v170
	v_mad_u64_u32 v[114:115], s[6:7], s14, v170, 0
	v_add3_u32 v115, v115, v116, v117
	v_lshl_add_u64 v[114:115], v[114:115], 1, s[4:5]
	v_pk_mul_f32 v[116:117], v[120:121], v[174:175] op_sel_hi:[1,0]
	v_pk_mul_f32 v[120:121], v[112:113], v[174:175] op_sel_hi:[1,0]
	v_pk_mul_f32 v[112:113], v[110:111], v[174:175] op_sel_hi:[1,0]
	v_lshl_add_u64 v[114:115], v[114:115], 0, v[138:139]
	v_cvt_pk_bf16_f32 v110, v118, v119
; __device__ __forceinline__ unsigned cvtpk(float lo, float hi) { f32x2_t v = {lo, hi}; bf16x2_t b = __builtin_convertvector(v, bf16x2_t); return __builtin_bit_cast(unsigned, b); }
;     __device__ __forceinline__ void operator()(f32x4 (&acc)[2][2][4][2], const Unit& u, int wr, int wc, int fr, int fq) const {
;     ...
;         for (int ai = 0; ai < 2; ++ai)
; #pragma unroll
;             for (int m = 0; m < 4; ++m) { const int row = row0 + ai * HALF + m * 16; bf16_t* rowp = O + (size_t)row * ldc + col0;
;                 const float rs = SCALE ? rsv[ai * 4 + m] : 1.f;
; #pragma unroll
;                 for (int bj = 0; bj < 2; ++bj) { const f32x4 v0 = acc[ai][bj][m][0] * rs, v1 = acc[ai][bj][m][1] * rs;
;                     u32x4 w; w.x = cvtpk(v0[0], v0[1]); w.y = cvtpk(v0[2], v0[3]); w.z = cvtpk(v1[0], v1[1]); w.w = cvtpk(v1[2], v1[3]);
;                     *(u32x4*)(rowp + bj * HALF) = w; } }
	v_cvt_pk_bf16_f32 v111, v116, v117
	v_cvt_pk_bf16_f32 v112, v112, v113
	v_cvt_pk_bf16_f32 v113, v120, v121
	global_store_dwordx4 v[114:115], v[110:113], off
	v_pk_mul_f32 v[106:107], v[106:107], v[174:175] op_sel_hi:[1,0]
	v_pk_mul_f32 v[102:103], v[102:103], v[180:181] op_sel_hi:[1,0]
	v_pk_mul_f32 v[110:111], v[100:101], v[174:175] op_sel_hi:[1,0]
	v_pk_mul_f32 v[100:101], v[98:99], v[174:175] op_sel_hi:[1,0]
	v_cvt_pk_bf16_f32 v98, v106, v107
	v_cvt_pk_bf16_f32 v99, v108, v109
	v_cvt_pk_bf16_f32 v100, v100, v101
	v_cvt_pk_bf16_f32 v101, v110, v111
	global_store_dwordx4 v[114:115], v[98:101], off offset:256
	v_pk_mul_f32 v[92:93], v[92:93], v[180:181] op_sel_hi:[1,0]
	v_pk_mul_f32 v[90:91], v[90:91], v[180:181] op_sel_hi:[1,0]
	v_mul_lo_u32 v100, s14, v169
	v_mul_lo_u32 v101, s15, v168
	v_mad_u64_u32 v[98:99], s[6:7], s14, v168, 0
	v_add3_u32 v99, v99, v100, v101
	v_lshl_add_u64 v[98:99], v[98:99], 1, s[4:5]
	v_pk_mul_f32 v[100:101], v[104:105], v[180:181] op_sel_hi:[1,0]
	v_pk_mul_f32 v[104:105], v[96:97], v[180:181] op_sel_hi:[1,0]
	v_pk_mul_f32 v[96:97], v[94:95], v[180:181] op_sel_hi:[1,0]
	v_lshl_add_u64 v[98:99], v[98:99], 0, v[138:139]
	v_cvt_pk_bf16_f32 v94, v102, v103
	v_cvt_pk_bf16_f32 v95, v100, v101
	v_cvt_pk_bf16_f32 v96, v96, v97
	v_cvt_pk_bf16_f32 v97, v104, v105
	global_store_dwordx4 v[98:99], v[94:97], off
	v_pk_mul_f32 v[86:87], v[86:87], v[176:177] op_sel_hi:[1,0]
	v_pk_mul_f32 v[76:77], v[76:77], v[176:177] op_sel_hi:[1,0]
	v_pk_mul_f32 v[94:95], v[84:85], v[180:181] op_sel_hi:[1,0]
	v_pk_mul_f32 v[84:85], v[82:83], v[180:181] op_sel_hi:[1,0]
	v_cvt_pk_bf16_f32 v82, v90, v91
	v_cvt_pk_bf16_f32 v83, v92, v93
	v_cvt_pk_bf16_f32 v84, v84, v85
	v_cvt_pk_bf16_f32 v85, v94, v95
	global_store_dwordx4 v[98:99], v[82:85], off offset:256
	v_pk_mul_f32 v[74:75], v[74:75], v[176:177] op_sel_hi:[1,0]
	v_pk_mul_f32 v[68:69], v[68:69], v[144:145] op_sel_hi:[1,0]
	v_mul_lo_u32 v84, s14, v167
	v_mul_lo_u32 v85, s15, v166
	v_mad_u64_u32 v[82:83], s[6:7], s14, v166, 0
	v_add3_u32 v83, v83, v84, v85
	v_lshl_add_u64 v[82:83], v[82:83], 1, s[4:5]
	v_pk_mul_f32 v[84:85], v[88:89], v[176:177] op_sel_hi:[1,0]
	v_pk_mul_f32 v[88:89], v[80:81], v[176:177] op_sel_hi:[1,0]
	v_pk_mul_f32 v[80:81], v[78:79], v[176:177] op_sel_hi:[1,0]
	v_lshl_add_u64 v[82:83], v[82:83], 0, v[138:139]
	v_cvt_pk_bf16_f32 v78, v86, v87
	v_cvt_pk_bf16_f32 v79, v84, v85
	v_cvt_pk_bf16_f32 v80, v80, v81
	v_cvt_pk_bf16_f32 v81, v88, v89
	global_store_dwordx4 v[82:83], v[78:81], off
	v_pk_mul_f32 v[66:67], v[66:67], v[144:145] op_sel_hi:[1,0]
	v_pk_mul_f32 v[60:61], v[60:61], v[144:145] op_sel_hi:[1,0]
	v_pk_mul_f32 v[78:79], v[72:73], v[176:177] op_sel_hi:[1,0]
	v_pk_mul_f32 v[72:73], v[70:71], v[176:177] op_sel_hi:[1,0]
	v_cvt_pk_bf16_f32 v70, v74, v75
	v_cvt_pk_bf16_f32 v71, v76, v77
	v_cvt_pk_bf16_f32 v72, v72, v73
	v_cvt_pk_bf16_f32 v73, v78, v79
	global_store_dwordx4 v[82:83], v[70:73], off offset:256
	v_pk_mul_f32 v[58:59], v[58:59], v[144:145] op_sel_hi:[1,0]
	v_pk_mul_f32 v[54:55], v[54:55], v[142:143] op_sel_hi:[1,0]
	v_mul_lo_u32 v72, s14, v165
	v_mul_lo_u32 v73, s15, v164
	v_mad_u64_u32 v[70:71], s[6:7], s14, v164, 0
	v_add3_u32 v71, v71, v72, v73
	v_lshl_add_u64 v[70:71], v[70:71], 1, s[4:5]
	v_pk_mul_f32 v[72:73], v[64:65], v[144:145] op_sel_hi:[1,0]
	v_pk_mul_f32 v[64:65], v[62:63], v[144:145] op_sel_hi:[1,0]
	v_lshl_add_u64 v[70:71], v[70:71], 0, v[138:139]
	v_cvt_pk_bf16_f32 v62, v66, v67
	v_cvt_pk_bf16_f32 v63, v68, v69
	v_cvt_pk_bf16_f32 v64, v64, v65
	v_cvt_pk_bf16_f32 v65, v72, v73
	global_store_dwordx4 v[70:71], v[62:65], off
	v_pk_mul_f32 v[44:45], v[44:45], v[142:143] op_sel_hi:[1,0]
; __device__ __forceinline__ unsigned cvtpk(float lo, float hi) { f32x2_t v = {lo, hi}; bf16x2_t b = __builtin_convertvector(v, bf16x2_t); return __builtin_bit_cast(unsigned, b); }
;     __device__ __forceinline__ void operator()(f32x4 (&acc)[2][2][4][2], const Unit& u, int wr, int wc, int fr, int fq) const {
;     ...
;         for (int ai = 0; ai < 2; ++ai)
; #pragma unroll
;             for (int m = 0; m < 4; ++m) { const int row = row0 + ai * HALF + m * 16; bf16_t* rowp = O + (size_t)row * ldc + col0;
;                 const float rs = SCALE ? rsv[ai * 4 + m] : 1.f;
; #pragma unroll
;                 for (int bj = 0; bj < 2; ++bj) { const f32x4 v0 = acc[ai][bj][m][0] * rs, v1 = acc[ai][bj][m][1] * rs;
;                     u32x4 w; w.x = cvtpk(v0[0], v0[1]); w.y = cvtpk(v0[2], v0[3]); w.z = cvtpk(v1[0], v1[1]); w.w = cvtpk(v1[2], v1[3]);
;                     *(u32x4*)(rowp + bj * HALF) = w; } }
	v_pk_mul_f32 v[42:43], v[42:43], v[142:143] op_sel_hi:[1,0]
	v_pk_mul_f32 v[62:63], v[52:53], v[144:145] op_sel_hi:[1,0]
	v_pk_mul_f32 v[52:53], v[50:51], v[144:145] op_sel_hi:[1,0]
	v_cvt_pk_bf16_f32 v50, v58, v59
	v_cvt_pk_bf16_f32 v51, v60, v61
	v_cvt_pk_bf16_f32 v52, v52, v53
	v_cvt_pk_bf16_f32 v53, v62, v63
	global_store_dwordx4 v[70:71], v[50:53], off offset:256
	v_pk_mul_f32 v[38:39], v[38:39], v[136:137] op_sel_hi:[1,0]
	v_pk_mul_f32 v[28:29], v[28:29], v[136:137] op_sel_hi:[1,0]
	v_mul_lo_u32 v52, s14, v163
	v_mul_lo_u32 v53, s15, v162
	v_mad_u64_u32 v[50:51], s[6:7], s14, v162, 0
	v_add3_u32 v51, v51, v52, v53
	v_lshl_add_u64 v[50:51], v[50:51], 1, s[4:5]
	v_pk_mul_f32 v[52:53], v[56:57], v[142:143] op_sel_hi:[1,0]
	v_pk_mul_f32 v[56:57], v[48:49], v[142:143] op_sel_hi:[1,0]
	v_pk_mul_f32 v[48:49], v[46:47], v[142:143] op_sel_hi:[1,0]
	v_lshl_add_u64 v[50:51], v[50:51], 0, v[138:139]
	v_cvt_pk_bf16_f32 v46, v54, v55
	v_cvt_pk_bf16_f32 v47, v52, v53
	v_cvt_pk_bf16_f32 v48, v48, v49
	v_cvt_pk_bf16_f32 v49, v56, v57
	global_store_dwordx4 v[50:51], v[46:49], off
	v_pk_mul_f32 v[26:27], v[26:27], v[136:137] op_sel_hi:[1,0]
	v_pk_mul_f32 v[22:23], v[22:23], v[134:135] op_sel_hi:[1,0]
	v_pk_mul_f32 v[46:47], v[36:37], v[142:143] op_sel_hi:[1,0]
	v_pk_mul_f32 v[36:37], v[34:35], v[142:143] op_sel_hi:[1,0]
	v_cvt_pk_bf16_f32 v34, v42, v43
	v_cvt_pk_bf16_f32 v35, v44, v45
	v_cvt_pk_bf16_f32 v36, v36, v37
	v_cvt_pk_bf16_f32 v37, v46, v47
	global_store_dwordx4 v[50:51], v[34:37], off offset:256
	v_pk_mul_f32 v[8:9], v[8:9], v[134:135] op_sel_hi:[1,0]
	v_pk_mul_f32 v[6:7], v[6:7], v[134:135] op_sel_hi:[1,0]
	v_mul_lo_u32 v36, s14, v161
	v_mul_lo_u32 v37, s15, v160
	v_mad_u64_u32 v[34:35], s[6:7], s14, v160, 0
	v_add3_u32 v35, v35, v36, v37
	v_lshl_add_u64 v[34:35], v[34:35], 1, s[4:5]
	v_pk_mul_f32 v[36:37], v[40:41], v[136:137] op_sel_hi:[1,0]
	v_pk_mul_f32 v[40:41], v[32:33], v[136:137] op_sel_hi:[1,0]
	v_pk_mul_f32 v[32:33], v[30:31], v[136:137] op_sel_hi:[1,0]
	v_lshl_add_u64 v[34:35], v[34:35], 0, v[138:139]
	v_cvt_pk_bf16_f32 v30, v38, v39
	v_cvt_pk_bf16_f32 v31, v36, v37
	v_cvt_pk_bf16_f32 v32, v32, v33
	v_cvt_pk_bf16_f32 v33, v40, v41
	global_store_dwordx4 v[34:35], v[30:33], off
	s_andn2_b64 vcc, exec, s[40:41]
	s_nop 0
	v_pk_mul_f32 v[30:31], v[20:21], v[136:137] op_sel_hi:[1,0]
	v_pk_mul_f32 v[20:21], v[18:19], v[136:137] op_sel_hi:[1,0]
	v_cvt_pk_bf16_f32 v18, v26, v27
	v_cvt_pk_bf16_f32 v19, v28, v29
	v_cvt_pk_bf16_f32 v20, v20, v21
	v_cvt_pk_bf16_f32 v21, v30, v31
	global_store_dwordx4 v[34:35], v[18:21], off offset:256
	s_nop 1
	v_mul_lo_u32 v20, s14, v159
	v_mul_lo_u32 v21, s15, v158
	v_mad_u64_u32 v[18:19], s[6:7], s14, v158, 0
	v_add3_u32 v19, v19, v20, v21
	v_lshl_add_u64 v[18:19], v[18:19], 1, s[4:5]
	v_pk_mul_f32 v[20:21], v[24:25], v[134:135] op_sel_hi:[1,0]
	v_pk_mul_f32 v[24:25], v[12:13], v[134:135] op_sel_hi:[1,0]
	v_pk_mul_f32 v[12:13], v[10:11], v[134:135] op_sel_hi:[1,0]
	v_lshl_add_u64 v[18:19], v[18:19], 0, v[138:139]
	v_cvt_pk_bf16_f32 v10, v22, v23
	v_cvt_pk_bf16_f32 v11, v20, v21
	v_cvt_pk_bf16_f32 v12, v12, v13
	v_cvt_pk_bf16_f32 v13, v24, v25
	global_store_dwordx4 v[18:19], v[10:13], off
	s_mov_b64 s[6:7], -1
	s_nop 0
	v_pk_mul_f32 v[10:11], v[4:5], v[134:135] op_sel_hi:[1,0]
	v_pk_mul_f32 v[4:5], v[2:3], v[134:135] op_sel_hi:[1,0]
	v_cvt_pk_bf16_f32 v2, v6, v7
	v_cvt_pk_bf16_f32 v3, v8, v9
	v_cvt_pk_bf16_f32 v4, v4, v5
	v_cvt_pk_bf16_f32 v5, v10, v11
	global_store_dwordx4 v[18:19], v[2:5], off offset:256
	s_cbranch_vccnz .LBB0_290
	s_andn2_b64 vcc, exec, s[16:17]
	s_cbranch_vccnz .LBB0_289
	s_barrier
	s_branch .LBB0_289

; #define PG8_STAGE(bufoff, gbase, voff) do { _Pragma("unroll") for (int _i = 0; _i < 2; ++_i) \
;         __builtin_amdgcn_global_load_lds((const unsigned*)((const char*)(gbase) + (voff)[_i]), (LAS unsigned*)(lds + (bufoff) + ldsw + _i * 8192), 16, 0, 0); } while (0)
; #define PG8_LDA(dst, b, h) do { _Pragma("unroll") for (int m = 0; m < 4; ++m) _Pragma("unroll") for (int k = 0; k < 2; ++k) dst[m][k] = *(const LAS bf16x8*)(lds + PG8_SA(b, h) + aoff + m * 2048 + k * 1024); } while (0)
; #define PG8_LDB(dst, b, h) do { _Pragma("unroll") for (int n = 0; n < 2; ++n) _Pragma("unroll") for (int k = 0; k < 2; ++k) dst[n][k] = *(const LAS bf16x8*)(lds + PG8_SB(b, h) + boff + n * 2048 + k * 1024); } while (0)
; #define PG8_MMA(ai, bj, At, Bt) do { __builtin_amdgcn_s_setprio(1); _Pragma("unroll") for (int m = 0; m < 4; ++m) _Pragma("unroll") for (int n = 0; n < 2; ++n) _Pragma("unroll") for (int k = 0; k < 2; ++k) \
;         acc[ai][bj][m][n] = __builtin_amdgcn_mfma_f32_16x16x32_bf16(Bt[n][k], At[m][k], acc[ai][bj][m][n], 0, 0, 0); __builtin_amdgcn_s_setprio(0); } while (0)
; #define PG8_WAIT_V(n) asm volatile("s_waitcnt vmcnt(" #n ")" ::: "memory")
; #define PG8_WAIT_L(n) asm volatile("s_waitcnt lgkmcnt(" #n ")" ::: "memory")
; #define PG8_BAR __builtin_amdgcn_s_barrier()
; #define PG8_SCHED __builtin_amdgcn_sched_barrier(0)
; template <class Epi, bool SEG>
; __device__ __forceinline__ void gemm_phase(LAS unsigned char* lds, const Gemm g, const int G, const int cidx, const Epi& E) {
;     ...
;             PG8_LDB(B0, 0, 0); PG8_LDB(B1, 0, 1); PG8_SCHED; PG8_LDA(At, 0, 0); PG8_STAGE(PG8_SA(1, 1), a1 + hstepA, voffA);
;             PG8_WAIT_V(8); PG8_WAIT_L(0); PG8_BAR; PG8_MMA(0, 0, At, B0); PG8_MMA(0, 1, At, B1); PG8_BAR; PG8_SCHED;
;             PG8_LDA(At, 0, 1); PG8_STAGE(PG8_SB(0, 0), b2, voffB); PG8_STAGE(PG8_SB(0, 1), b2 + hstepB, voffB); PG8_STAGE(PG8_SA(0, 0), a2, voffA);
;             PG8_WAIT_V(8); PG8_WAIT_L(0); PG8_BAR; PG8_MMA(1, 0, At, B0); PG8_MMA(1, 1, At, B1); PG8_BAR; PG8_SCHED;
.LBB0_706:
	s_add_u32 s48, s40, 0xfffc0080
	s_addc_u32 s49, s41, -1
	s_add_i32 s59, 0, 0x10000
	s_cmp_eq_u32 s58, 12
	s_cselect_b32 s51, s19, s49
	s_cselect_b32 s50, s54, s48
	s_cselect_b32 s49, s17, s57
	s_cselect_b32 s48, s55, s56
	s_add_i32 s62, 0, 0x14000
	v_add_u32_e32 v146, s59, v228
	v_add_u32_e32 v162, s62, v228
	ds_read_b128 v[130:133], v146
	ds_read_b128 v[138:141], v146 offset:1024
	ds_read_b128 v[142:145], v146 offset:2048
	ds_read_b128 v[146:149], v146 offset:3072
	ds_read_b128 v[150:153], v162
	ds_read_b128 v[154:157], v162 offset:1024
	ds_read_b128 v[158:161], v162 offset:2048
	ds_read_b128 v[162:165], v162 offset:3072
	v_lshl_add_u64 v[216:217], s[40:41], 0, v[198:199]
	s_add_i32 m0, s30, 0xc000
	ds_read_b128 v[166:169], v244
	ds_read_b128 v[170:173], v244 offset:1024
	ds_read_b128 v[174:177], v244 offset:2048
	ds_read_b128 v[178:181], v244 offset:3072
	ds_read_b128 v[182:185], v244 offset:4096
	ds_read_b128 v[186:189], v244 offset:5120
	ds_read_b128 v[190:193], v244 offset:6144
	ds_read_b128 v[212:215], v244 offset:7168
	global_load_lds_dwordx4 v[216:217], off
	v_lshl_add_u64 v[216:217], s[40:41], 0, v[200:201]
	s_add_i32 m0, s30, 0xe000
	s_nop 0
	global_load_lds_dwordx4 v[216:217], off
	s_waitcnt vmcnt(8)
	s_waitcnt lgkmcnt(0)
	s_setprio 1
	s_barrier
	v_mfma_f32_16x16x32_bf16 v[134:137], v[130:133], v[166:169], v[134:137]
	v_mfma_f32_16x16x32_bf16 v[126:129], v[142:145], v[166:169], v[126:129]
	v_mfma_f32_16x16x32_bf16 v[114:117], v[130:133], v[174:177], v[114:117]
	v_mfma_f32_16x16x32_bf16 v[110:113], v[142:145], v[174:177], v[110:113]
	v_mfma_f32_16x16x32_bf16 v[98:101], v[130:133], v[182:185], v[98:101]
	v_mfma_f32_16x16x32_bf16 v[94:97], v[142:145], v[182:185], v[94:97]
	v_mfma_f32_16x16x32_bf16 v[82:85], v[130:133], v[190:193], v[82:85]
	v_mfma_f32_16x16x32_bf16 v[78:81], v[142:145], v[190:193], v[78:81]
	v_mfma_f32_16x16x32_bf16 v[134:137], v[138:141], v[170:173], v[134:137]
	v_mfma_f32_16x16x32_bf16 v[126:129], v[146:149], v[170:173], v[126:129]
	v_mfma_f32_16x16x32_bf16 v[114:117], v[138:141], v[178:181], v[114:117]
	v_mfma_f32_16x16x32_bf16 v[110:113], v[146:149], v[178:181], v[110:113]
	v_mfma_f32_16x16x32_bf16 v[98:101], v[138:141], v[186:189], v[98:101]
	v_mfma_f32_16x16x32_bf16 v[94:97], v[146:149], v[186:189], v[94:97]
	v_mfma_f32_16x16x32_bf16 v[82:85], v[138:141], v[212:215], v[82:85]
	v_mfma_f32_16x16x32_bf16 v[78:81], v[146:149], v[212:215], v[78:81]
	s_setprio 0
	s_setprio 1
	v_mfma_f32_16x16x32_bf16 v[122:125], v[150:153], v[166:169], v[122:125]
	v_mfma_f32_16x16x32_bf16 v[118:121], v[158:161], v[166:169], v[118:121]
	v_mfma_f32_16x16x32_bf16 v[106:109], v[150:153], v[174:177], v[106:109]
	v_mfma_f32_16x16x32_bf16 v[102:105], v[158:161], v[174:177], v[102:105]
	v_mfma_f32_16x16x32_bf16 v[90:93], v[150:153], v[182:185], v[90:93]
	v_mfma_f32_16x16x32_bf16 v[86:89], v[158:161], v[182:185], v[86:89]
	v_mfma_f32_16x16x32_bf16 v[74:77], v[150:153], v[190:193], v[74:77]
	v_mfma_f32_16x16x32_bf16 v[70:73], v[158:161], v[190:193], v[70:73]
	v_mfma_f32_16x16x32_bf16 v[122:125], v[154:157], v[170:173], v[122:125]
	v_mfma_f32_16x16x32_bf16 v[118:121], v[162:165], v[170:173], v[118:121]
	v_mfma_f32_16x16x32_bf16 v[106:109], v[154:157], v[178:181], v[106:109]
	v_mfma_f32_16x16x32_bf16 v[102:105], v[162:165], v[178:181], v[102:105]
	v_mfma_f32_16x16x32_bf16 v[90:93], v[154:157], v[186:189], v[90:93]
	v_mfma_f32_16x16x32_bf16 v[86:89], v[162:165], v[186:189], v[86:89]
	v_mfma_f32_16x16x32_bf16 v[74:77], v[154:157], v[212:215], v[74:77]
	v_mfma_f32_16x16x32_bf16 v[70:73], v[162:165], v[212:215], v[70:73]
	s_barrier
	s_setprio 0
	s_add_i32 s59, s59, s9
	v_lshl_add_u64 v[216:217], s[48:49], 0, v[0:1]
	s_mov_b32 m0, s59
	ds_read_b128 v[166:169], v244 offset:16384
	ds_read_b128 v[170:173], v244 offset:17408
	ds_read_b128 v[174:177], v244 offset:18432
	ds_read_b128 v[178:181], v244 offset:19456
	ds_read_b128 v[182:185], v244 offset:20480
	ds_read_b128 v[186:189], v244 offset:21504
	ds_read_b128 v[190:193], v244 offset:22528
	ds_read_b128 v[212:215], v244 offset:23552
	global_load_lds_dwordx4 v[216:217], off
	s_add_i32 m0, s59, 0x2000
	s_add_u32 s60, s48, 0x40000
	v_lshl_add_u64 v[218:219], s[48:49], 0, v[14:15]
	s_addc_u32 s61, s49, 0
	s_add_i32 s59, s62, s9
	global_load_lds_dwordx4 v[218:219], off
	v_lshl_add_u64 v[220:221], s[60:61], 0, v[0:1]
	s_mov_b32 m0, s59
	v_lshl_add_u64 v[222:223], s[50:51], 0, v[194:195]
	global_load_lds_dwordx4 v[220:221], off
	v_lshl_add_u64 v[220:221], s[60:61], 0, v[14:15]
	s_add_i32 m0, s59, 0x2000
	s_nop 0
	global_load_lds_dwordx4 v[220:221], off
	v_lshl_add_u64 v[220:221], s[50:51], 0, v[196:197]
	s_mov_b32 m0, s30
	s_nop 0
	global_load_lds_dwordx4 v[220:221], off
	s_mov_b32 m0, s31
	s_nop 0
	global_load_lds_dwordx4 v[222:223], off
	s_waitcnt vmcnt(8)
	s_waitcnt lgkmcnt(0)
	s_setprio 1
	s_barrier
; #define PG8_STAGE(bufoff, gbase, voff) do { _Pragma("unroll") for (int _i = 0; _i < 2; ++_i) \
;         __builtin_amdgcn_global_load_lds((const unsigned*)((const char*)(gbase) + (voff)[_i]), (LAS unsigned*)(lds + (bufoff) + ldsw + _i * 8192), 16, 0, 0); } while (0)
; #define PG8_LDA(dst, b, h) do { _Pragma("unroll") for (int m = 0; m < 4; ++m) _Pragma("unroll") for (int k = 0; k < 2; ++k) dst[m][k] = *(const LAS bf16x8*)(lds + PG8_SA(b, h) + aoff + m * 2048 + k * 1024); } while (0)
; #define PG8_LDB(dst, b, h) do { _Pragma("unroll") for (int n = 0; n < 2; ++n) _Pragma("unroll") for (int k = 0; k < 2; ++k) dst[n][k] = *(const LAS bf16x8*)(lds + PG8_SB(b, h) + boff + n * 2048 + k * 1024); } while (0)
; #define PG8_MMA(ai, bj, At, Bt) do { __builtin_amdgcn_s_setprio(1); _Pragma("unroll") for (int m = 0; m < 4; ++m) _Pragma("unroll") for (int n = 0; n < 2; ++n) _Pragma("unroll") for (int k = 0; k < 2; ++k) \
;         acc[ai][bj][m][n] = __builtin_amdgcn_mfma_f32_16x16x32_bf16(Bt[n][k], At[m][k], acc[ai][bj][m][n], 0, 0, 0); __builtin_amdgcn_s_setprio(0); } while (0)
; #define PG8_WAIT_V(n) asm volatile("s_waitcnt vmcnt(" #n ")" ::: "memory")
; #define PG8_WAIT_L(n) asm volatile("s_waitcnt lgkmcnt(" #n ")" ::: "memory")
; #define PG8_BAR __builtin_amdgcn_s_barrier()
; #define PG8_SCHED __builtin_amdgcn_sched_barrier(0)
; template <class Epi, bool SEG>
; __device__ __forceinline__ void gemm_phase(LAS unsigned char* lds, const Gemm g, const int G, const int cidx, const Epi& E) {
;     ...
;             PG8_LDA(At, 0, 1); PG8_STAGE(PG8_SB(0, 0), b2, voffB); PG8_STAGE(PG8_SB(0, 1), b2 + hstepB, voffB); PG8_STAGE(PG8_SA(0, 0), a2, voffA);
;             PG8_WAIT_V(8); PG8_WAIT_L(0); PG8_BAR; PG8_MMA(1, 0, At, B0); PG8_MMA(1, 1, At, B1); PG8_BAR; PG8_SCHED;
;             PG8_LDB(B0, 1, 0); PG8_LDB(B1, 1, 1); PG8_SCHED; PG8_LDA(At, 1, 0); PG8_STAGE(PG8_SA(0, 1), a2 + hstepA, voffA);
;             PG8_WAIT_V(8); PG8_WAIT_L(0); PG8_BAR; PG8_MMA(0, 0, At, B0); PG8_MMA(0, 1, At, B1); PG8_BAR; PG8_SCHED;
;             PG8_LDA(At, 1, 1); PG8_STAGE(PG8_SB(1, 0), b3, voffB); PG8_STAGE(PG8_SB(1, 1), b3 + hstepB, voffB); PG8_STAGE(PG8_SA(1, 0), a3, voffA);
	v_mfma_f32_16x16x32_bf16 v[66:69], v[130:133], v[166:169], v[66:69]
	v_mfma_f32_16x16x32_bf16 v[62:65], v[142:145], v[166:169], v[62:65]
	v_mfma_f32_16x16x32_bf16 v[50:53], v[130:133], v[174:177], v[50:53]
	v_mfma_f32_16x16x32_bf16 v[46:49], v[142:145], v[174:177], v[46:49]
	v_mfma_f32_16x16x32_bf16 v[34:37], v[130:133], v[182:185], v[34:37]
	v_mfma_f32_16x16x32_bf16 v[30:33], v[142:145], v[182:185], v[30:33]
	v_mfma_f32_16x16x32_bf16 v[18:21], v[130:133], v[190:193], v[18:21]
	v_mfma_f32_16x16x32_bf16 v[10:13], v[142:145], v[190:193], v[10:13]
	v_mfma_f32_16x16x32_bf16 v[66:69], v[138:141], v[170:173], v[66:69]
	v_mfma_f32_16x16x32_bf16 v[62:65], v[146:149], v[170:173], v[62:65]
	v_mfma_f32_16x16x32_bf16 v[50:53], v[138:141], v[178:181], v[50:53]
	v_mfma_f32_16x16x32_bf16 v[46:49], v[146:149], v[178:181], v[46:49]
	v_mfma_f32_16x16x32_bf16 v[34:37], v[138:141], v[186:189], v[34:37]
	v_mfma_f32_16x16x32_bf16 v[30:33], v[146:149], v[186:189], v[30:33]
	v_mfma_f32_16x16x32_bf16 v[18:21], v[138:141], v[212:215], v[18:21]
	v_mfma_f32_16x16x32_bf16 v[10:13], v[146:149], v[212:215], v[10:13]
	s_setprio 0
	s_setprio 1
	v_mfma_f32_16x16x32_bf16 v[58:61], v[150:153], v[166:169], v[58:61]
	v_mfma_f32_16x16x32_bf16 v[54:57], v[158:161], v[166:169], v[54:57]
	v_mfma_f32_16x16x32_bf16 v[42:45], v[150:153], v[174:177], v[42:45]
	v_mfma_f32_16x16x32_bf16 v[38:41], v[158:161], v[174:177], v[38:41]
	v_mfma_f32_16x16x32_bf16 v[26:29], v[150:153], v[182:185], v[26:29]
	v_mfma_f32_16x16x32_bf16 v[22:25], v[158:161], v[182:185], v[22:25]
	v_mfma_f32_16x16x32_bf16 v[6:9], v[150:153], v[190:193], v[6:9]
	v_mfma_f32_16x16x32_bf16 v[2:5], v[158:161], v[190:193], v[2:5]
	v_mfma_f32_16x16x32_bf16 v[58:61], v[154:157], v[170:173], v[58:61]
	v_mfma_f32_16x16x32_bf16 v[54:57], v[162:165], v[170:173], v[54:57]
	v_mfma_f32_16x16x32_bf16 v[42:45], v[154:157], v[178:181], v[42:45]
	v_mfma_f32_16x16x32_bf16 v[38:41], v[162:165], v[178:181], v[38:41]
	v_mfma_f32_16x16x32_bf16 v[26:29], v[154:157], v[186:189], v[26:29]
	v_mfma_f32_16x16x32_bf16 v[22:25], v[162:165], v[186:189], v[22:25]
	v_mfma_f32_16x16x32_bf16 v[6:9], v[154:157], v[212:215], v[6:9]
	v_mfma_f32_16x16x32_bf16 v[2:5], v[162:165], v[212:215], v[2:5]
	s_barrier
	s_setprio 0
	s_add_i32 s59, 0, 0x18000
	s_add_i32 s60, 0, 0x1c000
	v_add_u32_e32 v146, s59, v228
	v_add_u32_e32 v162, s60, v228
	ds_read_b128 v[130:133], v146
	ds_read_b128 v[138:141], v146 offset:1024
	ds_read_b128 v[142:145], v146 offset:2048
	ds_read_b128 v[146:149], v146 offset:3072
	ds_read_b128 v[150:153], v162
	ds_read_b128 v[154:157], v162 offset:1024
	ds_read_b128 v[158:161], v162 offset:2048
	ds_read_b128 v[162:165], v162 offset:3072
	s_add_u32 s50, s50, 0x40000
	s_addc_u32 s51, s51, 0
	s_mov_b32 m0, s36
	v_lshl_add_u64 v[224:225], s[50:51], 0, v[196:197]
	ds_read_b128 v[166:169], v244 offset:32768
	ds_read_b128 v[170:173], v244 offset:33792
	ds_read_b128 v[174:177], v244 offset:34816
	ds_read_b128 v[178:181], v244 offset:35840
	ds_read_b128 v[182:185], v244 offset:36864
	ds_read_b128 v[186:189], v244 offset:37888
	ds_read_b128 v[190:193], v244 offset:38912
	ds_read_b128 v[212:215], v244 offset:39936
	global_load_lds_dwordx4 v[224:225], off
	v_lshl_add_u64 v[224:225], s[50:51], 0, v[194:195]
	s_mov_b32 m0, s38
	s_nop 0
	global_load_lds_dwordx4 v[224:225], off
	s_waitcnt vmcnt(8)
	s_waitcnt lgkmcnt(0)
	s_setprio 1
	s_barrier
	v_mfma_f32_16x16x32_bf16 v[134:137], v[130:133], v[166:169], v[134:137]
	v_mfma_f32_16x16x32_bf16 v[126:129], v[142:145], v[166:169], v[126:129]
	v_mfma_f32_16x16x32_bf16 v[114:117], v[130:133], v[174:177], v[114:117]
	v_mfma_f32_16x16x32_bf16 v[110:113], v[142:145], v[174:177], v[110:113]
	v_mfma_f32_16x16x32_bf16 v[98:101], v[130:133], v[182:185], v[98:101]
	v_mfma_f32_16x16x32_bf16 v[94:97], v[142:145], v[182:185], v[94:97]
	v_mfma_f32_16x16x32_bf16 v[82:85], v[130:133], v[190:193], v[82:85]
	v_mfma_f32_16x16x32_bf16 v[78:81], v[142:145], v[190:193], v[78:81]
	v_mfma_f32_16x16x32_bf16 v[134:137], v[138:141], v[170:173], v[134:137]
	v_mfma_f32_16x16x32_bf16 v[126:129], v[146:149], v[170:173], v[126:129]
	v_mfma_f32_16x16x32_bf16 v[114:117], v[138:141], v[178:181], v[114:117]
	v_mfma_f32_16x16x32_bf16 v[110:113], v[146:149], v[178:181], v[110:113]
	v_mfma_f32_16x16x32_bf16 v[98:101], v[138:141], v[186:189], v[98:101]
	v_mfma_f32_16x16x32_bf16 v[94:97], v[146:149], v[186:189], v[94:97]
	v_mfma_f32_16x16x32_bf16 v[82:85], v[138:141], v[212:215], v[82:85]
	v_mfma_f32_16x16x32_bf16 v[78:81], v[146:149], v[212:215], v[78:81]
	s_setprio 0
	s_setprio 1
	v_mfma_f32_16x16x32_bf16 v[122:125], v[150:153], v[166:169], v[122:125]
	v_mfma_f32_16x16x32_bf16 v[118:121], v[158:161], v[166:169], v[118:121]
	v_mfma_f32_16x16x32_bf16 v[106:109], v[150:153], v[174:177], v[106:109]
	v_mfma_f32_16x16x32_bf16 v[102:105], v[158:161], v[174:177], v[102:105]
	v_mfma_f32_16x16x32_bf16 v[90:93], v[150:153], v[182:185], v[90:93]
	v_mfma_f32_16x16x32_bf16 v[86:89], v[158:161], v[182:185], v[86:89]
	v_mfma_f32_16x16x32_bf16 v[74:77], v[150:153], v[190:193], v[74:77]
	v_mfma_f32_16x16x32_bf16 v[70:73], v[158:161], v[190:193], v[70:73]
	v_mfma_f32_16x16x32_bf16 v[122:125], v[154:157], v[170:173], v[122:125]
	v_mfma_f32_16x16x32_bf16 v[118:121], v[162:165], v[170:173], v[118:121]
	v_mfma_f32_16x16x32_bf16 v[106:109], v[154:157], v[178:181], v[106:109]
	v_mfma_f32_16x16x32_bf16 v[102:105], v[162:165], v[178:181], v[102:105]
	v_mfma_f32_16x16x32_bf16 v[90:93], v[154:157], v[186:189], v[90:93]
	v_mfma_f32_16x16x32_bf16 v[86:89], v[162:165], v[186:189], v[86:89]
	v_mfma_f32_16x16x32_bf16 v[74:77], v[154:157], v[212:215], v[74:77]
	v_mfma_f32_16x16x32_bf16 v[70:73], v[162:165], v[212:215], v[70:73]
	s_barrier
; #define PG8_STAGE(bufoff, gbase, voff) do { _Pragma("unroll") for (int _i = 0; _i < 2; ++_i) \
;         __builtin_amdgcn_global_load_lds((const unsigned*)((const char*)(gbase) + (voff)[_i]), (LAS unsigned*)(lds + (bufoff) + ldsw + _i * 8192), 16, 0, 0); } while (0)
; #define PG8_LDA(dst, b, h) do { _Pragma("unroll") for (int m = 0; m < 4; ++m) _Pragma("unroll") for (int k = 0; k < 2; ++k) dst[m][k] = *(const LAS bf16x8*)(lds + PG8_SA(b, h) + aoff + m * 2048 + k * 1024); } while (0)
; #define PG8_MMA(ai, bj, At, Bt) do { __builtin_amdgcn_s_setprio(1); _Pragma("unroll") for (int m = 0; m < 4; ++m) _Pragma("unroll") for (int n = 0; n < 2; ++n) _Pragma("unroll") for (int k = 0; k < 2; ++k) \
;         acc[ai][bj][m][n] = __builtin_amdgcn_mfma_f32_16x16x32_bf16(Bt[n][k], At[m][k], acc[ai][bj][m][n], 0, 0, 0); __builtin_amdgcn_s_setprio(0); } while (0)
; #define PG8_WAIT_V(n) asm volatile("s_waitcnt vmcnt(" #n ")" ::: "memory")
; #define PG8_WAIT_L(n) asm volatile("s_waitcnt lgkmcnt(" #n ")" ::: "memory")
; #define PG8_BAR __builtin_amdgcn_s_barrier()
; #define PG8_SCHED __builtin_amdgcn_sched_barrier(0)
;     __device__ __forceinline__ void operator()(f32x4 (&acc)[2][2][4][2], const Unit& u, int wr, int wc, int fr, int fq) const {
;     ...
;         bf16_t* rp0 = x + (size_t)(u.pm * BM + wr * 64 + fr) * DM + col0;
;         u32x4 bx[2][4][2];
; #pragma unroll
;         for (int ai = 0; ai < 2; ++ai)
; #pragma unroll
;             for (int m = 0; m < 4; ++m)
; #pragma unroll
;                 for (int bj = 0; bj < 2; ++bj) bx[ai][m][bj] = *(const u32x4*)(rp0 + (size_t)(ai * HALF + m * 16) * DM + bj * HALF);
; template <class Epi, bool SEG>
; __device__ __forceinline__ void gemm_phase(LAS unsigned char* lds, const Gemm g, const int G, const int cidx, const Epi& E) {
;     ...
;             PG8_LDA(At, 1, 1); PG8_STAGE(PG8_SB(1, 0), b3, voffB); PG8_STAGE(PG8_SB(1, 1), b3 + hstepB, voffB); PG8_STAGE(PG8_SA(1, 0), a3, voffA);
;             PG8_WAIT_V(8); PG8_WAIT_L(0); PG8_BAR; PG8_MMA(1, 0, At, B0); PG8_MMA(1, 1, At, B1); PG8_BAR; PG8_SCHED;
;         }
;         if (wr == 0) PG8_BAR;
	s_setprio 0
	s_add_i32 s50, s59, s9
	v_lshl_add_u64 v[216:217], v[216:217], 0, s[28:29]
	s_mov_b32 m0, s50
	ds_read_b128 v[166:169], v244 offset:49152
	ds_read_b128 v[170:173], v244 offset:50176
	ds_read_b128 v[174:177], v244 offset:51200
	ds_read_b128 v[178:181], v244 offset:52224
	ds_read_b128 v[182:185], v244 offset:53248
	ds_read_b128 v[186:189], v244 offset:54272
	ds_read_b128 v[190:193], v244 offset:55296
	ds_read_b128 v[212:215], v244 offset:56320
	global_load_lds_dwordx4 v[216:217], off
	s_add_i32 m0, s50, 0x2000
	s_add_u32 s48, s48, 0x40080
	v_lshl_add_u64 v[216:217], v[218:219], 0, s[28:29]
	s_addc_u32 s49, s49, 0
	s_add_i32 s50, s60, s9
	global_load_lds_dwordx4 v[216:217], off
	v_lshl_add_u64 v[216:217], s[48:49], 0, v[0:1]
	s_mov_b32 m0, s50
	s_nop 0
	global_load_lds_dwordx4 v[216:217], off
	v_lshl_add_u64 v[216:217], s[48:49], 0, v[14:15]
	s_add_i32 m0, s50, 0x2000
	s_nop 0
	global_load_lds_dwordx4 v[216:217], off
	v_lshl_add_u64 v[216:217], v[220:221], 0, s[28:29]
	s_mov_b32 m0, s39
	s_nop 0
	global_load_lds_dwordx4 v[216:217], off
	v_lshl_add_u64 v[216:217], v[222:223], 0, s[28:29]
	s_mov_b32 m0, s52
	s_nop 0
	global_load_lds_dwordx4 v[216:217], off
	s_waitcnt vmcnt(8)
	s_waitcnt lgkmcnt(0)
	s_setprio 1
	s_barrier
	v_mfma_f32_16x16x32_bf16 v[66:69], v[130:133], v[166:169], v[66:69]
	v_mfma_f32_16x16x32_bf16 v[62:65], v[142:145], v[166:169], v[62:65]
	v_mfma_f32_16x16x32_bf16 v[50:53], v[130:133], v[174:177], v[50:53]
	v_mfma_f32_16x16x32_bf16 v[46:49], v[142:145], v[174:177], v[46:49]
	v_mfma_f32_16x16x32_bf16 v[34:37], v[130:133], v[182:185], v[34:37]
	v_mfma_f32_16x16x32_bf16 v[30:33], v[142:145], v[182:185], v[30:33]
	v_mfma_f32_16x16x32_bf16 v[18:21], v[130:133], v[190:193], v[18:21]
	v_mfma_f32_16x16x32_bf16 v[10:13], v[142:145], v[190:193], v[10:13]
	v_mfma_f32_16x16x32_bf16 v[66:69], v[138:141], v[170:173], v[66:69]
	v_mfma_f32_16x16x32_bf16 v[62:65], v[146:149], v[170:173], v[62:65]
	v_mfma_f32_16x16x32_bf16 v[50:53], v[138:141], v[178:181], v[50:53]
	v_mfma_f32_16x16x32_bf16 v[46:49], v[146:149], v[178:181], v[46:49]
	v_mfma_f32_16x16x32_bf16 v[34:37], v[138:141], v[186:189], v[34:37]
	v_mfma_f32_16x16x32_bf16 v[30:33], v[146:149], v[186:189], v[30:33]
	v_mfma_f32_16x16x32_bf16 v[18:21], v[138:141], v[212:215], v[18:21]
	v_mfma_f32_16x16x32_bf16 v[10:13], v[146:149], v[212:215], v[10:13]
	s_setprio 0
	s_setprio 1
	v_mfma_f32_16x16x32_bf16 v[58:61], v[150:153], v[166:169], v[58:61]
	v_mfma_f32_16x16x32_bf16 v[54:57], v[158:161], v[166:169], v[54:57]
	v_mfma_f32_16x16x32_bf16 v[42:45], v[150:153], v[174:177], v[42:45]
	v_mfma_f32_16x16x32_bf16 v[38:41], v[158:161], v[174:177], v[38:41]
	v_mfma_f32_16x16x32_bf16 v[26:29], v[150:153], v[182:185], v[26:29]
	v_mfma_f32_16x16x32_bf16 v[22:25], v[158:161], v[182:185], v[22:25]
	v_mfma_f32_16x16x32_bf16 v[6:9], v[150:153], v[190:193], v[6:9]
	v_mfma_f32_16x16x32_bf16 v[2:5], v[158:161], v[190:193], v[2:5]
	v_mfma_f32_16x16x32_bf16 v[58:61], v[154:157], v[170:173], v[58:61]
	v_mfma_f32_16x16x32_bf16 v[54:57], v[162:165], v[170:173], v[54:57]
	v_mfma_f32_16x16x32_bf16 v[42:45], v[154:157], v[178:181], v[42:45]
	v_mfma_f32_16x16x32_bf16 v[38:41], v[162:165], v[178:181], v[38:41]
	v_mfma_f32_16x16x32_bf16 v[26:29], v[154:157], v[186:189], v[26:29]
	v_mfma_f32_16x16x32_bf16 v[22:25], v[162:165], v[186:189], v[22:25]
	v_mfma_f32_16x16x32_bf16 v[6:9], v[154:157], v[212:215], v[6:9]
	v_mfma_f32_16x16x32_bf16 v[2:5], v[162:165], v[212:215], v[2:5]
	s_barrier
	s_setprio 0
	s_add_i32 s58, s58, 2
	s_add_u32 s40, s40, 0x100
	s_addc_u32 s41, s41, 0
	s_add_u32 s56, s56, 0x100
	s_addc_u32 s57, s57, 0
	s_cmp_gt_u32 s58, 13
	s_cbranch_scc0 .LBB0_706
	s_lshl_b32 s15, s15, 8
	v_add_u32_e32 v132, s15, v17
	v_ashrrev_i32_e32 v133, 31, v132
	v_lshl_or_b32 v130, s14, 8, v229
	v_lshlrev_b64 v[132:133], 11, v[132:133]
	v_lshl_add_u64 v[132:133], s[82:83], 0, v[132:133]
	v_ashrrev_i32_e32 v131, 31, v130
	v_lshl_add_u64 v[226:227], v[130:131], 1, v[132:133]
	global_load_dwordx4 v[248:251], v[226:227], off
	global_load_dwordx4 v[190:193], v[226:227], off offset:256
	v_add_co_u32_e32 v224, vcc, 0x8000, v226
	s_mov_b32 s17, 0x18000
	s_nop 0
	v_addc_co_u32_e32 v225, vcc, 0, v227, vcc
	global_load_dwordx4 v[186:189], v[224:225], off
	global_load_dwordx4 v[182:185], v[224:225], off offset:256
	s_nop 4
	s_and_b64 vcc, exec, s[12:13]
	s_cbranch_vccz .LBB0_709
	s_barrier
; __device__ __forceinline__ unsigned cvtpk(float lo, float hi) { f32x2_t v = {lo, hi}; bf16x2_t b = __builtin_convertvector(v, bf16x2_t); return __builtin_bit_cast(unsigned, b); }
; __device__ __forceinline__ float bflo(unsigned w) { return __uint_as_float(w << 16); }
; __device__ __forceinline__ float bfhi(unsigned w) { return __uint_as_float(w & 0xffff0000u); }
;     __device__ __forceinline__ void operator()(f32x4 (&acc)[2][2][4][2], const Unit& u, int wr, int wc, int fr, int fq) const {
;     ...
;                 for (int bj = 0; bj < 2; ++bj) bx[ai][m][bj] = *(const u32x4*)(rp0 + (size_t)(ai * HALF + m * 16) * DM + bj * HALF);
;         float sqv[8];
; #pragma unroll
;         for (int ai = 0; ai < 2; ++ai)
; #pragma unroll
;             for (int m = 0; m < 4; ++m) { bf16_t* rp = rp0 + (size_t)(ai * HALF + m * 16) * DM; float sq = 0.f;
; #pragma unroll
;                 for (int bj = 0; bj < 2; ++bj) { const u32x4 b = bx[ai][m][bj];
;                     const f32x4 v0 = acc[ai][bj][m][0] + (f32x4){bflo(b.x), bfhi(b.x), bflo(b.y), bfhi(b.y)}, v1 = acc[ai][bj][m][1] + (f32x4){bflo(b.z), bfhi(b.z), bflo(b.w), bfhi(b.w)};
;                     sq += ((v0[0] * v0[0] + v0[1] * v0[1]) + (v0[2] * v0[2] + v0[3] * v0[3])) + ((v1[0] * v1[0] + v1[1] * v1[1]) + (v1[2] * v1[2] + v1[3] * v1[3]));
;                     u32x4 w; w.x = cvtpk(v0[0], v0[1]); w.y = cvtpk(v0[2], v0[3]); w.z = cvtpk(v1[0], v1[1]); w.w = cvtpk(v1[2], v1[3]);
;                     *(u32x4*)(rp + bj * HALF) = w; }
.LBB0_709:
	v_add_co_u32_e32 v222, vcc, s79, v226
	s_waitcnt vmcnt(0)
	v_lshlrev_b32_e32 v208, 16, v248
	v_addc_co_u32_e32 v223, vcc, 0, v227, vcc
	global_load_dwordx4 v[178:181], v[222:223], off
	global_load_dwordx4 v[174:177], v[222:223], off offset:256
	v_add_co_u32_e32 v220, vcc, s17, v226
	s_mov_b32 s17, 0x48000
	s_nop 0
	v_addc_co_u32_e32 v221, vcc, 0, v227, vcc
	global_load_dwordx4 v[170:173], v[220:221], off
	global_load_dwordx4 v[166:169], v[220:221], off offset:256
	v_add_co_u32_e32 v218, vcc, s68, v226
	v_and_b32_e32 v209, 0xffff0000, v248
	s_nop 0
	v_addc_co_u32_e32 v219, vcc, 0, v227, vcc
	global_load_dwordx4 v[162:165], v[218:219], off
	global_load_dwordx4 v[158:161], v[218:219], off offset:256
	v_add_co_u32_e32 v216, vcc, s17, v226
	v_lshlrev_b32_e32 v248, 16, v249
	s_nop 0
	v_addc_co_u32_e32 v217, vcc, 0, v227, vcc
	global_load_dwordx4 v[154:157], v[216:217], off
	global_load_dwordx4 v[150:153], v[216:217], off offset:256
	v_and_b32_e32 v249, 0xffff0000, v249
	v_pk_add_f32 v[136:137], v[136:137], v[248:249]
	v_pk_add_f32 v[134:135], v[134:135], v[208:209]
	v_lshlrev_b32_e32 v208, 16, v250
	v_and_b32_e32 v209, 0xffff0000, v250
	v_lshlrev_b32_e32 v248, 16, v251
	v_and_b32_e32 v249, 0xffff0000, v251
	v_pk_add_f32 v[248:249], v[128:129], v[248:249]
	v_pk_add_f32 v[128:129], v[126:127], v[208:209]
	v_mul_f32_e32 v126, v135, v135
	v_mul_f32_e32 v127, v137, v137
	s_mov_b32 s17, 0x50000
	v_fmac_f32_e32 v126, v134, v134
	v_fmac_f32_e32 v127, v136, v136
	v_add_co_u32_e32 v214, vcc, s17, v226
	v_add_f32_e32 v126, v126, v127
	v_mul_f32_e32 v127, v129, v129
	v_mul_f32_e32 v208, v249, v249
	v_addc_co_u32_e32 v215, vcc, 0, v227, vcc
	s_mov_b32 s17, 0x58000
	v_fmac_f32_e32 v127, v128, v128
	v_fmac_f32_e32 v208, v248, v248
	v_add_co_u32_e32 v212, vcc, s17, v226
	v_add_f32_e32 v127, v127, v208
	s_nop 0
	v_addc_co_u32_e32 v213, vcc, 0, v227, vcc
	v_add_f32_e32 v208, v126, v127
	v_cvt_pk_bf16_f32 v126, v134, v135
	v_cvt_pk_bf16_f32 v127, v136, v137
	v_cvt_pk_bf16_f32 v128, v128, v129
	v_cvt_pk_bf16_f32 v129, v248, v249
	global_load_dwordx4 v[146:149], v[214:215], off
	global_load_dwordx4 v[142:145], v[214:215], off offset:256
	global_load_dwordx4 v[138:141], v[212:213], off
	global_load_dwordx4 v[130:133], v[212:213], off offset:256
	v_cmp_lt_i32_e32 vcc, v237, v232
	global_store_dwordx4 v[226:227], v[126:129], off
	s_nop 1
	v_lshlrev_b32_e32 v126, 16, v190
	v_and_b32_e32 v127, 0xffff0000, v190
	v_lshlrev_b32_e32 v128, 16, v191
	v_and_b32_e32 v129, 0xffff0000, v191
	v_pk_add_f32 v[124:125], v[124:125], v[128:129]
	v_pk_add_f32 v[122:123], v[122:123], v[126:127]
	v_lshlrev_b32_e32 v126, 16, v192
	v_and_b32_e32 v127, 0xffff0000, v192
	v_lshlrev_b32_e32 v128, 16, v193
	v_and_b32_e32 v129, 0xffff0000, v193
	v_pk_add_f32 v[126:127], v[118:119], v[126:127]
	v_mul_f32_e32 v118, v123, v123
	v_mul_f32_e32 v119, v125, v125
	v_pk_add_f32 v[128:129], v[120:121], v[128:129]
	v_fmac_f32_e32 v118, v122, v122
	v_fmac_f32_e32 v119, v124, v124
	v_add_f32_e32 v118, v118, v119
	v_mul_f32_e32 v119, v127, v127
	v_mul_f32_e32 v120, v129, v129
	v_fmac_f32_e32 v119, v126, v126
	v_fmac_f32_e32 v120, v128, v128
	v_add_f32_e32 v119, v119, v120
	v_cvt_pk_bf16_f32 v120, v122, v123
	v_cvt_pk_bf16_f32 v121, v124, v125
	v_cvt_pk_bf16_f32 v122, v126, v127
	v_cvt_pk_bf16_f32 v123, v128, v129
	global_store_dwordx4 v[226:227], v[120:123], off offset:256
	v_add_f32_e32 v118, v118, v119
	v_add_f32_e32 v118, v208, v118
	v_lshlrev_b32_e32 v120, 16, v186
	v_and_b32_e32 v121, 0xffff0000, v186
	v_lshlrev_b32_e32 v122, 16, v187
	v_and_b32_e32 v123, 0xffff0000, v187
	v_pk_add_f32 v[116:117], v[116:117], v[122:123]
	v_pk_add_f32 v[114:115], v[114:115], v[120:121]
	v_lshlrev_b32_e32 v120, 16, v188
	v_and_b32_e32 v121, 0xffff0000, v188
	v_lshlrev_b32_e32 v122, 16, v189
	v_and_b32_e32 v123, 0xffff0000, v189
	v_pk_add_f32 v[122:123], v[112:113], v[122:123]
	v_pk_add_f32 v[112:113], v[110:111], v[120:121]
	v_mul_f32_e32 v110, v115, v115
	v_mul_f32_e32 v111, v117, v117
	v_fmac_f32_e32 v110, v114, v114
	v_fmac_f32_e32 v111, v116, v116
	v_add_f32_e32 v110, v110, v111
	v_mul_f32_e32 v111, v113, v113
	v_mul_f32_e32 v119, v123, v123
	v_fmac_f32_e32 v111, v112, v112
	v_fmac_f32_e32 v119, v122, v122
	v_add_f32_e32 v111, v111, v119
	v_add_f32_e32 v119, v110, v111
	v_cvt_pk_bf16_f32 v110, v114, v115
	v_cvt_pk_bf16_f32 v111, v116, v117
	v_cvt_pk_bf16_f32 v112, v112, v113
	v_cvt_pk_bf16_f32 v113, v122, v123
	global_store_dwordx4 v[224:225], v[110:113], off
	s_nop 1
	v_lshlrev_b32_e32 v110, 16, v182
	v_and_b32_e32 v111, 0xffff0000, v182
	v_lshlrev_b32_e32 v112, 16, v183
	v_and_b32_e32 v113, 0xffff0000, v183
	v_pk_add_f32 v[108:109], v[108:109], v[112:113]
	v_pk_add_f32 v[106:107], v[106:107], v[110:111]
	v_lshlrev_b32_e32 v110, 16, v184
	v_and_b32_e32 v111, 0xffff0000, v184
	v_lshlrev_b32_e32 v112, 16, v185
	v_and_b32_e32 v113, 0xffff0000, v185
	v_pk_add_f32 v[110:111], v[102:103], v[110:111]
	v_mul_f32_e32 v102, v107, v107
	v_mul_f32_e32 v103, v109, v109
	v_pk_add_f32 v[112:113], v[104:105], v[112:113]
	v_fmac_f32_e32 v102, v106, v106
	v_fmac_f32_e32 v103, v108, v108
	v_add_f32_e32 v102, v102, v103
	v_mul_f32_e32 v103, v111, v111
	v_mul_f32_e32 v104, v113, v113
	v_fmac_f32_e32 v103, v110, v110
	v_fmac_f32_e32 v104, v112, v112
	v_add_f32_e32 v103, v103, v104
	v_cvt_pk_bf16_f32 v104, v106, v107
	v_cvt_pk_bf16_f32 v105, v108, v109
	v_cvt_pk_bf16_f32 v106, v110, v111
	v_cvt_pk_bf16_f32 v107, v112, v113
	global_store_dwordx4 v[224:225], v[104:107], off offset:256
	v_add_f32_e32 v102, v102, v103
	v_add_f32_e32 v102, v119, v102
	s_waitcnt vmcnt(15)
; __device__ __forceinline__ unsigned cvtpk(float lo, float hi) { f32x2_t v = {lo, hi}; bf16x2_t b = __builtin_convertvector(v, bf16x2_t); return __builtin_bit_cast(unsigned, b); }
; __device__ __forceinline__ float bflo(unsigned w) { return __uint_as_float(w << 16); }
; __device__ __forceinline__ float bfhi(unsigned w) { return __uint_as_float(w & 0xffff0000u); }
;     __device__ __forceinline__ void operator()(f32x4 (&acc)[2][2][4][2], const Unit& u, int wr, int wc, int fr, int fq) const {
;     ...
;             for (int m = 0; m < 4; ++m) { bf16_t* rp = rp0 + (size_t)(ai * HALF + m * 16) * DM; float sq = 0.f;
; #pragma unroll
;                 for (int bj = 0; bj < 2; ++bj) { const u32x4 b = bx[ai][m][bj];
;                     const f32x4 v0 = acc[ai][bj][m][0] + (f32x4){bflo(b.x), bfhi(b.x), bflo(b.y), bfhi(b.y)}, v1 = acc[ai][bj][m][1] + (f32x4){bflo(b.z), bfhi(b.z), bflo(b.w), bfhi(b.w)};
;                     sq += ((v0[0] * v0[0] + v0[1] * v0[1]) + (v0[2] * v0[2] + v0[3] * v0[3])) + ((v1[0] * v1[0] + v1[1] * v1[1]) + (v1[2] * v1[2] + v1[3] * v1[3]));
;                     u32x4 w; w.x = cvtpk(v0[0], v0[1]); w.y = cvtpk(v0[2], v0[3]); w.z = cvtpk(v1[0], v1[1]); w.w = cvtpk(v1[2], v1[3]);
;                     *(u32x4*)(rp + bj * HALF) = w; }
;                 sqv[ai * 4 + m] = sq; }
	v_lshlrev_b32_e32 v104, 16, v178
	v_and_b32_e32 v105, 0xffff0000, v178
	v_lshlrev_b32_e32 v106, 16, v179
	v_and_b32_e32 v107, 0xffff0000, v179
	v_pk_add_f32 v[100:101], v[100:101], v[106:107]
	v_pk_add_f32 v[98:99], v[98:99], v[104:105]
	v_lshlrev_b32_e32 v104, 16, v180
	v_and_b32_e32 v105, 0xffff0000, v180
	v_lshlrev_b32_e32 v106, 16, v181
	v_and_b32_e32 v107, 0xffff0000, v181
	v_pk_add_f32 v[106:107], v[96:97], v[106:107]
	v_pk_add_f32 v[96:97], v[94:95], v[104:105]
	v_mul_f32_e32 v94, v99, v99
	v_mul_f32_e32 v95, v101, v101
	v_fmac_f32_e32 v94, v98, v98
	v_fmac_f32_e32 v95, v100, v100
	v_add_f32_e32 v94, v94, v95
	v_mul_f32_e32 v95, v97, v97
	v_mul_f32_e32 v103, v107, v107
	v_fmac_f32_e32 v95, v96, v96
	v_fmac_f32_e32 v103, v106, v106
	v_add_f32_e32 v95, v95, v103
	v_add_f32_e32 v103, v94, v95
	v_cvt_pk_bf16_f32 v94, v98, v99
	v_cvt_pk_bf16_f32 v95, v100, v101
	v_cvt_pk_bf16_f32 v96, v96, v97
	v_cvt_pk_bf16_f32 v97, v106, v107
	global_store_dwordx4 v[222:223], v[94:97], off
	s_waitcnt vmcnt(15)
	s_nop 0
	v_lshlrev_b32_e32 v94, 16, v174
	v_and_b32_e32 v95, 0xffff0000, v174
	v_lshlrev_b32_e32 v96, 16, v175
	v_and_b32_e32 v97, 0xffff0000, v175
	v_pk_add_f32 v[92:93], v[92:93], v[96:97]
	v_pk_add_f32 v[90:91], v[90:91], v[94:95]
	v_lshlrev_b32_e32 v94, 16, v176
	v_and_b32_e32 v95, 0xffff0000, v176
	v_lshlrev_b32_e32 v96, 16, v177
	v_and_b32_e32 v97, 0xffff0000, v177
	v_pk_add_f32 v[94:95], v[86:87], v[94:95]
	v_mul_f32_e32 v86, v91, v91
	v_mul_f32_e32 v87, v93, v93
	v_pk_add_f32 v[96:97], v[88:89], v[96:97]
	v_fmac_f32_e32 v86, v90, v90
	v_fmac_f32_e32 v87, v92, v92
	v_add_f32_e32 v86, v86, v87
	v_mul_f32_e32 v87, v95, v95
	v_mul_f32_e32 v88, v97, v97
	v_fmac_f32_e32 v87, v94, v94
	v_fmac_f32_e32 v88, v96, v96
	v_add_f32_e32 v87, v87, v88
	v_cvt_pk_bf16_f32 v88, v90, v91
	v_cvt_pk_bf16_f32 v89, v92, v93
	v_cvt_pk_bf16_f32 v90, v94, v95
	v_cvt_pk_bf16_f32 v91, v96, v97
	global_store_dwordx4 v[222:223], v[88:91], off offset:256
	v_add_f32_e32 v86, v86, v87
	v_add_f32_e32 v86, v103, v86
	s_waitcnt vmcnt(15)
	v_lshlrev_b32_e32 v88, 16, v170
	v_and_b32_e32 v89, 0xffff0000, v170
	v_lshlrev_b32_e32 v90, 16, v171
	v_and_b32_e32 v91, 0xffff0000, v171
	v_pk_add_f32 v[84:85], v[84:85], v[90:91]
	v_pk_add_f32 v[82:83], v[82:83], v[88:89]
	v_lshlrev_b32_e32 v88, 16, v172
	v_and_b32_e32 v89, 0xffff0000, v172
	v_lshlrev_b32_e32 v90, 16, v173
	v_and_b32_e32 v91, 0xffff0000, v173
	v_pk_add_f32 v[90:91], v[80:81], v[90:91]
	v_pk_add_f32 v[80:81], v[78:79], v[88:89]
	v_mul_f32_e32 v78, v83, v83
	v_mul_f32_e32 v79, v85, v85
	v_fmac_f32_e32 v78, v82, v82
	v_fmac_f32_e32 v79, v84, v84
	v_add_f32_e32 v78, v78, v79
	v_mul_f32_e32 v79, v81, v81
	v_mul_f32_e32 v87, v91, v91
	v_fmac_f32_e32 v79, v80, v80
	v_fmac_f32_e32 v87, v90, v90
	v_add_f32_e32 v79, v79, v87
	v_add_f32_e32 v87, v78, v79
	v_cvt_pk_bf16_f32 v78, v82, v83
	v_cvt_pk_bf16_f32 v79, v84, v85
	v_cvt_pk_bf16_f32 v80, v80, v81
	v_cvt_pk_bf16_f32 v81, v90, v91
	global_store_dwordx4 v[220:221], v[78:81], off
	s_waitcnt vmcnt(15)
	s_nop 0
	v_lshlrev_b32_e32 v78, 16, v166
	v_and_b32_e32 v79, 0xffff0000, v166
	v_lshlrev_b32_e32 v80, 16, v167
	v_and_b32_e32 v81, 0xffff0000, v167
	v_pk_add_f32 v[76:77], v[76:77], v[80:81]
	v_pk_add_f32 v[74:75], v[74:75], v[78:79]
	v_lshlrev_b32_e32 v78, 16, v168
	v_and_b32_e32 v79, 0xffff0000, v168
	v_lshlrev_b32_e32 v80, 16, v169
	v_and_b32_e32 v81, 0xffff0000, v169
	v_pk_add_f32 v[80:81], v[72:73], v[80:81]
	v_pk_add_f32 v[72:73], v[70:71], v[78:79]
	v_mul_f32_e32 v70, v75, v75
	v_mul_f32_e32 v71, v77, v77
	v_fmac_f32_e32 v70, v74, v74
	v_fmac_f32_e32 v71, v76, v76
	v_add_f32_e32 v70, v70, v71
	v_mul_f32_e32 v71, v73, v73
	v_mul_f32_e32 v78, v81, v81
	v_fmac_f32_e32 v71, v72, v72
	v_fmac_f32_e32 v78, v80, v80
	v_add_f32_e32 v71, v71, v78
	v_add_f32_e32 v70, v70, v71
	v_add_f32_e32 v78, v87, v70
	v_cvt_pk_bf16_f32 v70, v74, v75
	v_cvt_pk_bf16_f32 v71, v76, v77
	v_cvt_pk_bf16_f32 v72, v72, v73
	v_cvt_pk_bf16_f32 v73, v80, v81
	global_store_dwordx4 v[220:221], v[70:73], off offset:256
	s_waitcnt vmcnt(15)
	s_nop 0
	v_lshlrev_b32_e32 v70, 16, v162
	v_and_b32_e32 v71, 0xffff0000, v162
	v_lshlrev_b32_e32 v72, 16, v163
	v_and_b32_e32 v73, 0xffff0000, v163
	v_pk_add_f32 v[68:69], v[68:69], v[72:73]
	v_pk_add_f32 v[66:67], v[66:67], v[70:71]
	v_lshlrev_b32_e32 v70, 16, v164
	v_and_b32_e32 v71, 0xffff0000, v164
	v_lshlrev_b32_e32 v72, 16, v165
	v_and_b32_e32 v73, 0xffff0000, v165
	v_pk_add_f32 v[72:73], v[64:65], v[72:73]
	v_pk_add_f32 v[64:65], v[62:63], v[70:71]
	v_mul_f32_e32 v62, v67, v67
	v_mul_f32_e32 v63, v69, v69
	v_fmac_f32_e32 v62, v66, v66
	v_fmac_f32_e32 v63, v68, v68
	v_add_f32_e32 v62, v62, v63
	v_mul_f32_e32 v63, v65, v65
	v_mul_f32_e32 v70, v73, v73
	v_fmac_f32_e32 v63, v64, v64
	v_fmac_f32_e32 v70, v72, v72
	v_add_f32_e32 v63, v63, v70
	v_add_f32_e32 v70, v62, v63
	v_cvt_pk_bf16_f32 v62, v66, v67
	v_cvt_pk_bf16_f32 v63, v68, v69
	v_cvt_pk_bf16_f32 v64, v64, v65
	v_cvt_pk_bf16_f32 v65, v72, v73
	global_store_dwordx4 v[218:219], v[62:65], off
	s_waitcnt vmcnt(15)
	s_nop 0
	v_lshlrev_b32_e32 v62, 16, v158
	v_and_b32_e32 v63, 0xffff0000, v158
	v_lshlrev_b32_e32 v64, 16, v159
	v_and_b32_e32 v65, 0xffff0000, v159
	v_pk_add_f32 v[60:61], v[60:61], v[64:65]
	v_pk_add_f32 v[58:59], v[58:59], v[62:63]
	v_lshlrev_b32_e32 v62, 16, v160
	v_and_b32_e32 v63, 0xffff0000, v160
	v_lshlrev_b32_e32 v64, 16, v161
	v_and_b32_e32 v65, 0xffff0000, v161
	v_pk_add_f32 v[64:65], v[56:57], v[64:65]
	v_pk_add_f32 v[56:57], v[54:55], v[62:63]
	v_mul_f32_e32 v54, v59, v59
	v_mul_f32_e32 v55, v61, v61
	v_fmac_f32_e32 v54, v58, v58
	v_fmac_f32_e32 v55, v60, v60
	v_add_f32_e32 v54, v54, v55
	v_mul_f32_e32 v55, v57, v57
	v_mul_f32_e32 v62, v65, v65
	v_fmac_f32_e32 v55, v56, v56
	v_fmac_f32_e32 v62, v64, v64
	v_add_f32_e32 v55, v55, v62
	v_add_f32_e32 v54, v54, v55
	v_add_f32_e32 v62, v70, v54
	v_cvt_pk_bf16_f32 v54, v58, v59
	v_cvt_pk_bf16_f32 v55, v60, v61
	v_cvt_pk_bf16_f32 v56, v56, v57
	v_cvt_pk_bf16_f32 v57, v64, v65
	global_store_dwordx4 v[218:219], v[54:57], off offset:256
	s_waitcnt vmcnt(15)
; __device__ __forceinline__ unsigned cvtpk(float lo, float hi) { f32x2_t v = {lo, hi}; bf16x2_t b = __builtin_convertvector(v, bf16x2_t); return __builtin_bit_cast(unsigned, b); }
; __device__ __forceinline__ float bflo(unsigned w) { return __uint_as_float(w << 16); }
; __device__ __forceinline__ float bfhi(unsigned w) { return __uint_as_float(w & 0xffff0000u); }
;     __device__ __forceinline__ void operator()(f32x4 (&acc)[2][2][4][2], const Unit& u, int wr, int wc, int fr, int fq) const {
;     ...
;             for (int m = 0; m < 4; ++m) { bf16_t* rp = rp0 + (size_t)(ai * HALF + m * 16) * DM; float sq = 0.f;
; #pragma unroll
;                 for (int bj = 0; bj < 2; ++bj) { const u32x4 b = bx[ai][m][bj];
;                     const f32x4 v0 = acc[ai][bj][m][0] + (f32x4){bflo(b.x), bfhi(b.x), bflo(b.y), bfhi(b.y)}, v1 = acc[ai][bj][m][1] + (f32x4){bflo(b.z), bfhi(b.z), bflo(b.w), bfhi(b.w)};
;                     sq += ((v0[0] * v0[0] + v0[1] * v0[1]) + (v0[2] * v0[2] + v0[3] * v0[3])) + ((v1[0] * v1[0] + v1[1] * v1[1]) + (v1[2] * v1[2] + v1[3] * v1[3]));
;                     u32x4 w; w.x = cvtpk(v0[0], v0[1]); w.y = cvtpk(v0[2], v0[3]); w.z = cvtpk(v1[0], v1[1]); w.w = cvtpk(v1[2], v1[3]);
;                     *(u32x4*)(rp + bj * HALF) = w; }
;                 sqv[ai * 4 + m] = sq; }
	s_nop 0
	v_lshlrev_b32_e32 v54, 16, v154
	v_and_b32_e32 v55, 0xffff0000, v154
	v_lshlrev_b32_e32 v56, 16, v155
	v_and_b32_e32 v57, 0xffff0000, v155
	v_pk_add_f32 v[52:53], v[52:53], v[56:57]
	v_pk_add_f32 v[50:51], v[50:51], v[54:55]
	v_lshlrev_b32_e32 v54, 16, v156
	v_and_b32_e32 v55, 0xffff0000, v156
	v_lshlrev_b32_e32 v56, 16, v157
	v_and_b32_e32 v57, 0xffff0000, v157
	v_pk_add_f32 v[56:57], v[48:49], v[56:57]
	v_pk_add_f32 v[48:49], v[46:47], v[54:55]
	v_mul_f32_e32 v46, v51, v51
	v_mul_f32_e32 v47, v53, v53
	v_fmac_f32_e32 v46, v50, v50
	v_fmac_f32_e32 v47, v52, v52
	v_add_f32_e32 v46, v46, v47
	v_mul_f32_e32 v47, v49, v49
	v_mul_f32_e32 v54, v57, v57
	v_fmac_f32_e32 v47, v48, v48
	v_fmac_f32_e32 v54, v56, v56
	v_add_f32_e32 v47, v47, v54
	v_add_f32_e32 v54, v46, v47
	v_cvt_pk_bf16_f32 v46, v50, v51
	v_cvt_pk_bf16_f32 v47, v52, v53
	v_cvt_pk_bf16_f32 v48, v48, v49
	v_cvt_pk_bf16_f32 v49, v56, v57
	global_store_dwordx4 v[216:217], v[46:49], off
	s_waitcnt vmcnt(15)
	s_nop 0
	v_lshlrev_b32_e32 v46, 16, v150
	v_and_b32_e32 v47, 0xffff0000, v150
	v_lshlrev_b32_e32 v48, 16, v151
	v_and_b32_e32 v49, 0xffff0000, v151
	v_pk_add_f32 v[44:45], v[44:45], v[48:49]
	v_pk_add_f32 v[42:43], v[42:43], v[46:47]
	v_lshlrev_b32_e32 v46, 16, v152
	v_and_b32_e32 v47, 0xffff0000, v152
	v_lshlrev_b32_e32 v48, 16, v153
	v_and_b32_e32 v49, 0xffff0000, v153
	v_pk_add_f32 v[48:49], v[40:41], v[48:49]
	v_pk_add_f32 v[40:41], v[38:39], v[46:47]
	v_mul_f32_e32 v38, v43, v43
	v_mul_f32_e32 v39, v45, v45
	v_fmac_f32_e32 v38, v42, v42
	v_fmac_f32_e32 v39, v44, v44
	v_add_f32_e32 v38, v38, v39
	v_mul_f32_e32 v39, v41, v41
	v_mul_f32_e32 v46, v49, v49
	v_fmac_f32_e32 v39, v40, v40
	v_fmac_f32_e32 v46, v48, v48
	v_add_f32_e32 v39, v39, v46
	v_add_f32_e32 v38, v38, v39
	v_add_f32_e32 v46, v54, v38
	v_cvt_pk_bf16_f32 v38, v42, v43
	v_cvt_pk_bf16_f32 v39, v44, v45
	v_cvt_pk_bf16_f32 v40, v40, v41
	v_cvt_pk_bf16_f32 v41, v48, v49
	global_store_dwordx4 v[216:217], v[38:41], off offset:256
	s_waitcnt vmcnt(15)
	s_nop 0
	v_lshlrev_b32_e32 v38, 16, v146
	v_and_b32_e32 v39, 0xffff0000, v146
	v_lshlrev_b32_e32 v40, 16, v147
	v_and_b32_e32 v41, 0xffff0000, v147
	v_pk_add_f32 v[36:37], v[36:37], v[40:41]
	v_pk_add_f32 v[34:35], v[34:35], v[38:39]
	v_lshlrev_b32_e32 v38, 16, v148
	v_and_b32_e32 v39, 0xffff0000, v148
	v_lshlrev_b32_e32 v40, 16, v149
	v_and_b32_e32 v41, 0xffff0000, v149
	v_pk_add_f32 v[40:41], v[32:33], v[40:41]
	v_pk_add_f32 v[32:33], v[30:31], v[38:39]
	v_mul_f32_e32 v30, v35, v35
	v_mul_f32_e32 v31, v37, v37
	v_fmac_f32_e32 v30, v34, v34
	v_fmac_f32_e32 v31, v36, v36
	v_add_f32_e32 v30, v30, v31
	v_mul_f32_e32 v31, v33, v33
	v_mul_f32_e32 v38, v41, v41
	v_fmac_f32_e32 v31, v32, v32
	v_fmac_f32_e32 v38, v40, v40
	v_add_f32_e32 v31, v31, v38
	v_add_f32_e32 v38, v30, v31
	v_cvt_pk_bf16_f32 v30, v34, v35
	v_cvt_pk_bf16_f32 v31, v36, v37
	v_cvt_pk_bf16_f32 v32, v32, v33
	v_cvt_pk_bf16_f32 v33, v40, v41
	global_store_dwordx4 v[214:215], v[30:33], off
	s_waitcnt vmcnt(15)
	s_nop 0
	v_lshlrev_b32_e32 v30, 16, v142
	v_and_b32_e32 v31, 0xffff0000, v142
	v_lshlrev_b32_e32 v32, 16, v143
	v_and_b32_e32 v33, 0xffff0000, v143
	v_pk_add_f32 v[28:29], v[28:29], v[32:33]
	v_pk_add_f32 v[26:27], v[26:27], v[30:31]
	v_lshlrev_b32_e32 v30, 16, v144
	v_and_b32_e32 v31, 0xffff0000, v144
	v_lshlrev_b32_e32 v32, 16, v145
	v_and_b32_e32 v33, 0xffff0000, v145
	v_pk_add_f32 v[32:33], v[24:25], v[32:33]
	v_pk_add_f32 v[24:25], v[22:23], v[30:31]
	v_mul_f32_e32 v22, v27, v27
	v_mul_f32_e32 v23, v29, v29
	v_fmac_f32_e32 v22, v26, v26
	v_fmac_f32_e32 v23, v28, v28
	v_add_f32_e32 v22, v22, v23
	v_mul_f32_e32 v23, v25, v25
	v_mul_f32_e32 v30, v33, v33
	v_fmac_f32_e32 v23, v24, v24
	v_fmac_f32_e32 v30, v32, v32
	v_add_f32_e32 v23, v23, v30
	v_add_f32_e32 v22, v22, v23
	v_add_f32_e32 v30, v38, v22
	v_cvt_pk_bf16_f32 v22, v26, v27
	v_cvt_pk_bf16_f32 v23, v28, v29
	v_cvt_pk_bf16_f32 v24, v24, v25
	v_cvt_pk_bf16_f32 v25, v32, v33
	global_store_dwordx4 v[214:215], v[22:25], off offset:256
	s_waitcnt vmcnt(15)
; __device__ __forceinline__ unsigned cvtpk(float lo, float hi) { f32x2_t v = {lo, hi}; bf16x2_t b = __builtin_convertvector(v, bf16x2_t); return __builtin_bit_cast(unsigned, b); }
; __device__ __forceinline__ float bflo(unsigned w) { return __uint_as_float(w << 16); }
; __device__ __forceinline__ float bfhi(unsigned w) { return __uint_as_float(w & 0xffff0000u); }
;     __device__ __forceinline__ void operator()(f32x4 (&acc)[2][2][4][2], const Unit& u, int wr, int wc, int fr, int fq) const {
;     ...
;             for (int m = 0; m < 4; ++m) { bf16_t* rp = rp0 + (size_t)(ai * HALF + m * 16) * DM; float sq = 0.f;
; #pragma unroll
;                 for (int bj = 0; bj < 2; ++bj) { const u32x4 b = bx[ai][m][bj];
;                     const f32x4 v0 = acc[ai][bj][m][0] + (f32x4){bflo(b.x), bfhi(b.x), bflo(b.y), bfhi(b.y)}, v1 = acc[ai][bj][m][1] + (f32x4){bflo(b.z), bfhi(b.z), bflo(b.w), bfhi(b.w)};
;                     sq += ((v0[0] * v0[0] + v0[1] * v0[1]) + (v0[2] * v0[2] + v0[3] * v0[3])) + ((v1[0] * v1[0] + v1[1] * v1[1]) + (v1[2] * v1[2] + v1[3] * v1[3]));
;                     u32x4 w; w.x = cvtpk(v0[0], v0[1]); w.y = cvtpk(v0[2], v0[3]); w.z = cvtpk(v1[0], v1[1]); w.w = cvtpk(v1[2], v1[3]);
;                     *(u32x4*)(rp + bj * HALF) = w; }
;                 sqv[ai * 4 + m] = sq; }
; #pragma unroll
;         for (int i = 0; i < 8; ++i) { float s = sqv[i]; s += __shfl_xor(s, 16); s += __shfl_xor(s, 32); sqv[i] = s; }
;         if (fq == 0) {
; #pragma unroll
;             for (int i = 0; i < 8; ++i) red[((i >> 2) * HALF + wr * 64 + (i & 3) * 16 + fr) * 4 + wc] = sqv[i]; }
	s_nop 0
	v_lshlrev_b32_e32 v22, 16, v138
	v_and_b32_e32 v23, 0xffff0000, v138
	v_lshlrev_b32_e32 v24, 16, v139
	v_and_b32_e32 v25, 0xffff0000, v139
	v_pk_add_f32 v[20:21], v[20:21], v[24:25]
	v_pk_add_f32 v[18:19], v[18:19], v[22:23]
	v_lshlrev_b32_e32 v22, 16, v140
	v_and_b32_e32 v23, 0xffff0000, v140
	v_lshlrev_b32_e32 v24, 16, v141
	v_and_b32_e32 v25, 0xffff0000, v141
	v_pk_add_f32 v[24:25], v[12:13], v[24:25]
	v_pk_add_f32 v[12:13], v[10:11], v[22:23]
	v_mul_f32_e32 v10, v19, v19
	v_mul_f32_e32 v11, v21, v21
	v_fmac_f32_e32 v10, v18, v18
	v_fmac_f32_e32 v11, v20, v20
	v_add_f32_e32 v10, v10, v11
	v_mul_f32_e32 v11, v13, v13
	v_mul_f32_e32 v22, v25, v25
	v_fmac_f32_e32 v11, v12, v12
	v_fmac_f32_e32 v22, v24, v24
	v_add_f32_e32 v11, v11, v22
	v_add_f32_e32 v22, v10, v11
	v_cvt_pk_bf16_f32 v10, v18, v19
	v_cvt_pk_bf16_f32 v11, v20, v21
	v_cvt_pk_bf16_f32 v12, v12, v13
	v_cvt_pk_bf16_f32 v13, v24, v25
	global_store_dwordx4 v[212:213], v[10:13], off
	s_waitcnt vmcnt(15)
	s_nop 0
	v_lshlrev_b32_e32 v10, 16, v130
	v_and_b32_e32 v11, 0xffff0000, v130
	v_lshlrev_b32_e32 v12, 16, v131
	v_and_b32_e32 v13, 0xffff0000, v131
	v_pk_add_f32 v[8:9], v[8:9], v[12:13]
	v_pk_add_f32 v[6:7], v[6:7], v[10:11]
	v_lshlrev_b32_e32 v10, 16, v132
	v_and_b32_e32 v11, 0xffff0000, v132
	v_lshlrev_b32_e32 v12, 16, v133
	v_and_b32_e32 v13, 0xffff0000, v133
	v_pk_add_f32 v[12:13], v[4:5], v[12:13]
	v_pk_add_f32 v[4:5], v[2:3], v[10:11]
	v_mul_f32_e32 v2, v7, v7
	v_mul_f32_e32 v3, v9, v9
	v_fmac_f32_e32 v2, v6, v6
	v_fmac_f32_e32 v3, v8, v8
	v_add_f32_e32 v2, v2, v3
	v_mul_f32_e32 v3, v5, v5
	v_mul_f32_e32 v10, v13, v13
	v_fmac_f32_e32 v3, v4, v4
	v_fmac_f32_e32 v10, v12, v12
	v_add_f32_e32 v3, v3, v10
	v_add_f32_e32 v2, v2, v3
	v_add_f32_e32 v20, v22, v2
	v_cvt_pk_bf16_f32 v2, v6, v7
	v_cvt_pk_bf16_f32 v3, v8, v9
	v_cvt_pk_bf16_f32 v4, v4, v5
	v_cvt_pk_bf16_f32 v5, v12, v13
	global_store_dwordx4 v[212:213], v[2:5], off offset:256
	s_nop 1
	v_cndmask_b32_e32 v2, v231, v237, vcc
	v_cmp_lt_i32_e32 vcc, v238, v232
	v_lshlrev_b32_e32 v21, 2, v2
	ds_bpermute_b32 v4, v21, v102
	v_cndmask_b32_e32 v2, v231, v238, vcc
	v_lshlrev_b32_e32 v22, 2, v2
	ds_bpermute_b32 v2, v21, v118
	ds_bpermute_b32 v6, v21, v86
	ds_bpermute_b32 v8, v21, v78
	ds_bpermute_b32 v10, v21, v62
	ds_bpermute_b32 v12, v21, v46
	ds_bpermute_b32 v18, v21, v30
	ds_bpermute_b32 v21, v21, v20
	s_waitcnt lgkmcnt(6)
	v_add_f32_e32 v2, v118, v2
	v_add_f32_e32 v4, v102, v4
	s_waitcnt lgkmcnt(5)
	v_add_f32_e32 v6, v86, v6
	s_waitcnt lgkmcnt(4)
	v_add_f32_e32 v8, v78, v8
	s_waitcnt lgkmcnt(3)
	v_add_f32_e32 v10, v62, v10
	s_waitcnt lgkmcnt(2)
	v_add_f32_e32 v12, v46, v12
	s_waitcnt lgkmcnt(1)
	v_add_f32_e32 v18, v30, v18
	s_waitcnt lgkmcnt(0)
	v_add_f32_e32 v20, v20, v21
	ds_bpermute_b32 v3, v22, v2
	ds_bpermute_b32 v5, v22, v4
	ds_bpermute_b32 v7, v22, v6
	ds_bpermute_b32 v9, v22, v8
	ds_bpermute_b32 v11, v22, v10
	ds_bpermute_b32 v13, v22, v12
	ds_bpermute_b32 v19, v22, v18
	ds_bpermute_b32 v21, v22, v20
	s_and_saveexec_b64 s[40:41], s[42:43]
	s_cbranch_execz .LBB0_711
	s_waitcnt lgkmcnt(6)
	v_add_f32_e32 v4, v4, v5
	v_add_f32_e32 v2, v2, v3
	s_waitcnt lgkmcnt(0)
	v_add_f32_e32 v20, v20, v21
	v_add_f32_e32 v18, v18, v19
	v_add_f32_e32 v12, v12, v13
	v_add_f32_e32 v10, v10, v11
	v_add_f32_e32 v8, v8, v9
	v_add_f32_e32 v6, v6, v7
	ds_write2st64_b32 v245, v2, v4 offset1:1
	ds_write2st64_b32 v245, v6, v8 offset0:2 offset1:3
	ds_write2st64_b32 v246, v10, v12 offset1:1
	ds_write2st64_b32 v246, v18, v20 offset0:2 offset1:3

; #define PG8_STAGE(bufoff, gbase, voff) do { _Pragma("unroll") for (int _i = 0; _i < 2; ++_i) \
;         __builtin_amdgcn_global_load_lds((const unsigned*)((const char*)(gbase) + (voff)[_i]), (LAS unsigned*)(lds + (bufoff) + ldsw + _i * 8192), 16, 0, 0); } while (0)
; #define PG8_LDA(dst, b, h) do { _Pragma("unroll") for (int m = 0; m < 4; ++m) _Pragma("unroll") for (int k = 0; k < 2; ++k) dst[m][k] = *(const LAS bf16x8*)(lds + PG8_SA(b, h) + aoff + m * 2048 + k * 1024); } while (0)
; #define PG8_LDB(dst, b, h) do { _Pragma("unroll") for (int n = 0; n < 2; ++n) _Pragma("unroll") for (int k = 0; k < 2; ++k) dst[n][k] = *(const LAS bf16x8*)(lds + PG8_SB(b, h) + boff + n * 2048 + k * 1024); } while (0)
; #define PG8_MMA(ai, bj, At, Bt) do { __builtin_amdgcn_s_setprio(1); _Pragma("unroll") for (int m = 0; m < 4; ++m) _Pragma("unroll") for (int n = 0; n < 2; ++n) _Pragma("unroll") for (int k = 0; k < 2; ++k) \
;         acc[ai][bj][m][n] = __builtin_amdgcn_mfma_f32_16x16x32_bf16(Bt[n][k], At[m][k], acc[ai][bj][m][n], 0, 0, 0); __builtin_amdgcn_s_setprio(0); } while (0)
; #define PG8_WAIT_V(n) asm volatile("s_waitcnt vmcnt(" #n ")" ::: "memory")
; #define PG8_WAIT_L(n) asm volatile("s_waitcnt lgkmcnt(" #n ")" ::: "memory")
; #define PG8_BAR __builtin_amdgcn_s_barrier()
; #define PG8_SCHED __builtin_amdgcn_sched_barrier(0)
; template <class Epi, bool SEG>
; __device__ __forceinline__ void gemm_phase(LAS unsigned char* lds, const Gemm g, const int G, const int cidx, const Epi& E) {
;     ...
;         for (int t = 0; t < nt; t += 2) {
;             const bool last = (t == nt - 2);
;             const char* a1 = cA + (size_t)(t + 1) * kstep;
;             const char* a2 = last ? nA : cA + (size_t)(t + 2) * kstep; const char* b2 = last ? nB : cB + (size_t)(t + 2) * kstep;
;             const char* a3 = a2 + kstep; const char* b3 = b2 + kstep;
;             PG8_LDB(B0, 0, 0); PG8_LDB(B1, 0, 1); PG8_SCHED; PG8_LDA(At, 0, 0); PG8_STAGE(PG8_SA(1, 1), a1 + hstepA, voffA);
;             PG8_WAIT_V(8); PG8_WAIT_L(0); PG8_BAR; PG8_MMA(0, 0, At, B0); PG8_MMA(0, 1, At, B1); PG8_BAR; PG8_SCHED;
;             PG8_LDA(At, 0, 1); PG8_STAGE(PG8_SB(0, 0), b2, voffB); PG8_STAGE(PG8_SB(0, 1), b2 + hstepB, voffB); PG8_STAGE(PG8_SA(0, 0), a2, voffA);
;             PG8_WAIT_V(8); PG8_WAIT_L(0); PG8_BAR; PG8_MMA(1, 0, At, B0); PG8_MMA(1, 1, At, B1); PG8_BAR; PG8_SCHED;
.LBB0_786:
	s_add_u32 s22, s6, 0xfffc2080
	s_addc_u32 s23, s7, -1
	s_add_i32 s55, 0, 0x10000
	s_cmp_eq_u32 s54, 12
	s_cselect_b32 s41, s17, s23
	s_cselect_b32 s40, s16, s22
	s_cselect_b32 s23, s15, s53
	s_cselect_b32 s22, s21, s52
	s_add_i32 s58, 0, 0x14000
	v_add_u32_e32 v114, s55, v243
	v_add_u32_e32 v130, s58, v243
	ds_read_b128 v[102:105], v114
	ds_read_b128 v[106:109], v114 offset:1024
	ds_read_b128 v[110:113], v114 offset:2048
	ds_read_b128 v[114:117], v114 offset:3072
	ds_read_b128 v[118:121], v130
	ds_read_b128 v[122:125], v130 offset:1024
	ds_read_b128 v[126:129], v130 offset:2048
	ds_read_b128 v[130:133], v130 offset:3072
	v_lshl_add_u64 v[208:209], s[6:7], 0, v[198:199]
	s_add_i32 m0, s11, 0xc000
	ds_read_b128 v[166:169], v247
	ds_read_b128 v[170:173], v247 offset:1024
	ds_read_b128 v[174:177], v247 offset:2048
	ds_read_b128 v[178:181], v247 offset:3072
	ds_read_b128 v[182:185], v247 offset:4096
	ds_read_b128 v[186:189], v247 offset:5120
	ds_read_b128 v[212:215], v247 offset:6144
	ds_read_b128 v[216:219], v247 offset:7168
	global_load_lds_dwordx4 v[208:209], off
	v_lshl_add_u64 v[208:209], s[6:7], 0, v[200:201]
	s_add_i32 m0, s11, 0xe000
	s_nop 0
	global_load_lds_dwordx4 v[208:209], off
	s_waitcnt vmcnt(8)
	s_waitcnt lgkmcnt(0)
	s_setprio 1
	s_barrier
	v_mfma_f32_16x16x32_bf16 v[162:165], v[102:105], v[166:169], v[162:165]
	v_mfma_f32_16x16x32_bf16 v[66:69], v[110:113], v[166:169], v[66:69]
	v_mfma_f32_16x16x32_bf16 v[158:161], v[102:105], v[174:177], v[158:161]
	v_mfma_f32_16x16x32_bf16 v[62:65], v[110:113], v[174:177], v[62:65]
	v_mfma_f32_16x16x32_bf16 v[146:149], v[102:105], v[182:185], v[146:149]
	v_mfma_f32_16x16x32_bf16 v[50:53], v[110:113], v[182:185], v[50:53]
	v_mfma_f32_16x16x32_bf16 v[138:141], v[102:105], v[212:215], v[138:141]
	v_mfma_f32_16x16x32_bf16 v[42:45], v[110:113], v[212:215], v[42:45]
	v_mfma_f32_16x16x32_bf16 v[162:165], v[106:109], v[170:173], v[162:165]
	v_mfma_f32_16x16x32_bf16 v[66:69], v[114:117], v[170:173], v[66:69]
	v_mfma_f32_16x16x32_bf16 v[158:161], v[106:109], v[178:181], v[158:161]
	v_mfma_f32_16x16x32_bf16 v[62:65], v[114:117], v[178:181], v[62:65]
	v_mfma_f32_16x16x32_bf16 v[146:149], v[106:109], v[186:189], v[146:149]
	v_mfma_f32_16x16x32_bf16 v[50:53], v[114:117], v[186:189], v[50:53]
	v_mfma_f32_16x16x32_bf16 v[138:141], v[106:109], v[216:219], v[138:141]
	v_mfma_f32_16x16x32_bf16 v[42:45], v[114:117], v[216:219], v[42:45]
	s_setprio 0
	s_setprio 1
	v_mfma_f32_16x16x32_bf16 v[154:157], v[118:121], v[166:169], v[154:157]
	v_mfma_f32_16x16x32_bf16 v[58:61], v[126:129], v[166:169], v[58:61]
	v_mfma_f32_16x16x32_bf16 v[150:153], v[118:121], v[174:177], v[150:153]
	v_mfma_f32_16x16x32_bf16 v[54:57], v[126:129], v[174:177], v[54:57]
	v_mfma_f32_16x16x32_bf16 v[142:145], v[118:121], v[182:185], v[142:145]
	v_mfma_f32_16x16x32_bf16 v[46:49], v[126:129], v[182:185], v[46:49]
	v_mfma_f32_16x16x32_bf16 v[134:137], v[118:121], v[212:215], v[134:137]
	v_mfma_f32_16x16x32_bf16 v[38:41], v[126:129], v[212:215], v[38:41]
	v_mfma_f32_16x16x32_bf16 v[154:157], v[122:125], v[170:173], v[154:157]
	v_mfma_f32_16x16x32_bf16 v[58:61], v[130:133], v[170:173], v[58:61]
	v_mfma_f32_16x16x32_bf16 v[150:153], v[122:125], v[178:181], v[150:153]
	v_mfma_f32_16x16x32_bf16 v[54:57], v[130:133], v[178:181], v[54:57]
	v_mfma_f32_16x16x32_bf16 v[142:145], v[122:125], v[186:189], v[142:145]
	v_mfma_f32_16x16x32_bf16 v[46:49], v[130:133], v[186:189], v[46:49]
	v_mfma_f32_16x16x32_bf16 v[134:137], v[122:125], v[216:219], v[134:137]
	v_mfma_f32_16x16x32_bf16 v[38:41], v[130:133], v[216:219], v[38:41]
	s_barrier
	s_setprio 0
	s_add_i32 s55, s55, s10
	v_lshl_add_u64 v[208:209], s[22:23], 0, v[0:1]
	s_mov_b32 m0, s55
	ds_read_b128 v[166:169], v247 offset:16384
	ds_read_b128 v[170:173], v247 offset:17408
	ds_read_b128 v[174:177], v247 offset:18432
	ds_read_b128 v[178:181], v247 offset:19456
	ds_read_b128 v[182:185], v247 offset:20480
	ds_read_b128 v[186:189], v247 offset:21504
	ds_read_b128 v[212:215], v247 offset:22528
	ds_read_b128 v[216:219], v247 offset:23552
	global_load_lds_dwordx4 v[208:209], off
	s_add_i32 m0, s55, 0x2000
	s_add_u32 s56, s22, 0x40000
	v_lshl_add_u64 v[220:221], s[22:23], 0, v[192:193]
	s_addc_u32 s57, s23, 0
	s_add_i32 s55, s58, s10
	global_load_lds_dwordx4 v[220:221], off
	v_lshl_add_u64 v[222:223], s[56:57], 0, v[0:1]
	s_mov_b32 m0, s55
	v_lshl_add_u64 v[224:225], s[40:41], 0, v[190:191]
	global_load_lds_dwordx4 v[222:223], off
	v_lshl_add_u64 v[222:223], s[56:57], 0, v[192:193]
	s_add_i32 m0, s55, 0x2000
	s_nop 0
	global_load_lds_dwordx4 v[222:223], off
	v_lshl_add_u64 v[222:223], s[40:41], 0, v[14:15]
	s_mov_b32 m0, s11
	s_nop 0
	global_load_lds_dwordx4 v[222:223], off
	s_mov_b32 m0, s9
	s_nop 0
	global_load_lds_dwordx4 v[224:225], off
	s_waitcnt vmcnt(8)
	s_waitcnt lgkmcnt(0)
	s_setprio 1
	s_barrier
; #define PG8_STAGE(bufoff, gbase, voff) do { _Pragma("unroll") for (int _i = 0; _i < 2; ++_i) \
;         __builtin_amdgcn_global_load_lds((const unsigned*)((const char*)(gbase) + (voff)[_i]), (LAS unsigned*)(lds + (bufoff) + ldsw + _i * 8192), 16, 0, 0); } while (0)
; #define PG8_LDA(dst, b, h) do { _Pragma("unroll") for (int m = 0; m < 4; ++m) _Pragma("unroll") for (int k = 0; k < 2; ++k) dst[m][k] = *(const LAS bf16x8*)(lds + PG8_SA(b, h) + aoff + m * 2048 + k * 1024); } while (0)
; #define PG8_LDB(dst, b, h) do { _Pragma("unroll") for (int n = 0; n < 2; ++n) _Pragma("unroll") for (int k = 0; k < 2; ++k) dst[n][k] = *(const LAS bf16x8*)(lds + PG8_SB(b, h) + boff + n * 2048 + k * 1024); } while (0)
; #define PG8_MMA(ai, bj, At, Bt) do { __builtin_amdgcn_s_setprio(1); _Pragma("unroll") for (int m = 0; m < 4; ++m) _Pragma("unroll") for (int n = 0; n < 2; ++n) _Pragma("unroll") for (int k = 0; k < 2; ++k) \
;         acc[ai][bj][m][n] = __builtin_amdgcn_mfma_f32_16x16x32_bf16(Bt[n][k], At[m][k], acc[ai][bj][m][n], 0, 0, 0); __builtin_amdgcn_s_setprio(0); } while (0)
; #define PG8_WAIT_V(n) asm volatile("s_waitcnt vmcnt(" #n ")" ::: "memory")
; #define PG8_WAIT_L(n) asm volatile("s_waitcnt lgkmcnt(" #n ")" ::: "memory")
; #define PG8_BAR __builtin_amdgcn_s_barrier()
; #define PG8_SCHED __builtin_amdgcn_sched_barrier(0)
; template <class Epi, bool SEG>
; __device__ __forceinline__ void gemm_phase(LAS unsigned char* lds, const Gemm g, const int G, const int cidx, const Epi& E) {
;     ...
;             PG8_WAIT_V(8); PG8_WAIT_L(0); PG8_BAR; PG8_MMA(1, 0, At, B0); PG8_MMA(1, 1, At, B1); PG8_BAR; PG8_SCHED;
;             PG8_LDB(B0, 1, 0); PG8_LDB(B1, 1, 1); PG8_SCHED; PG8_LDA(At, 1, 0); PG8_STAGE(PG8_SA(0, 1), a2 + hstepA, voffA);
;             PG8_WAIT_V(8); PG8_WAIT_L(0); PG8_BAR; PG8_MMA(0, 0, At, B0); PG8_MMA(0, 1, At, B1); PG8_BAR; PG8_SCHED;
;             PG8_LDA(At, 1, 1); PG8_STAGE(PG8_SB(1, 0), b3, voffB); PG8_STAGE(PG8_SB(1, 1), b3 + hstepB, voffB); PG8_STAGE(PG8_SA(1, 0), a3, voffA);
	v_mfma_f32_16x16x32_bf16 v[98:101], v[102:105], v[166:169], v[98:101]
	v_mfma_f32_16x16x32_bf16 v[34:37], v[110:113], v[166:169], v[34:37]
	v_mfma_f32_16x16x32_bf16 v[94:97], v[102:105], v[174:177], v[94:97]
	v_mfma_f32_16x16x32_bf16 v[30:33], v[110:113], v[174:177], v[30:33]
	v_mfma_f32_16x16x32_bf16 v[82:85], v[102:105], v[182:185], v[82:85]
	v_mfma_f32_16x16x32_bf16 v[18:21], v[110:113], v[182:185], v[18:21]
	v_mfma_f32_16x16x32_bf16 v[74:77], v[102:105], v[212:215], v[74:77]
	v_mfma_f32_16x16x32_bf16 v[6:9], v[110:113], v[212:215], v[6:9]
	v_mfma_f32_16x16x32_bf16 v[98:101], v[106:109], v[170:173], v[98:101]
	v_mfma_f32_16x16x32_bf16 v[34:37], v[114:117], v[170:173], v[34:37]
	v_mfma_f32_16x16x32_bf16 v[94:97], v[106:109], v[178:181], v[94:97]
	v_mfma_f32_16x16x32_bf16 v[30:33], v[114:117], v[178:181], v[30:33]
	v_mfma_f32_16x16x32_bf16 v[82:85], v[106:109], v[186:189], v[82:85]
	v_mfma_f32_16x16x32_bf16 v[18:21], v[114:117], v[186:189], v[18:21]
	v_mfma_f32_16x16x32_bf16 v[74:77], v[106:109], v[216:219], v[74:77]
	v_mfma_f32_16x16x32_bf16 v[6:9], v[114:117], v[216:219], v[6:9]
	s_setprio 0
	s_setprio 1
	v_mfma_f32_16x16x32_bf16 v[90:93], v[118:121], v[166:169], v[90:93]
	v_mfma_f32_16x16x32_bf16 v[26:29], v[126:129], v[166:169], v[26:29]
	v_mfma_f32_16x16x32_bf16 v[86:89], v[118:121], v[174:177], v[86:89]
	v_mfma_f32_16x16x32_bf16 v[22:25], v[126:129], v[174:177], v[22:25]
	v_mfma_f32_16x16x32_bf16 v[78:81], v[118:121], v[182:185], v[78:81]
	v_mfma_f32_16x16x32_bf16 v[10:13], v[126:129], v[182:185], v[10:13]
	v_mfma_f32_16x16x32_bf16 v[70:73], v[118:121], v[212:215], v[70:73]
	v_mfma_f32_16x16x32_bf16 v[2:5], v[126:129], v[212:215], v[2:5]
	v_mfma_f32_16x16x32_bf16 v[90:93], v[122:125], v[170:173], v[90:93]
	v_mfma_f32_16x16x32_bf16 v[26:29], v[130:133], v[170:173], v[26:29]
	v_mfma_f32_16x16x32_bf16 v[86:89], v[122:125], v[178:181], v[86:89]
	v_mfma_f32_16x16x32_bf16 v[22:25], v[130:133], v[178:181], v[22:25]
	v_mfma_f32_16x16x32_bf16 v[78:81], v[122:125], v[186:189], v[78:81]
	v_mfma_f32_16x16x32_bf16 v[10:13], v[130:133], v[186:189], v[10:13]
	v_mfma_f32_16x16x32_bf16 v[70:73], v[122:125], v[216:219], v[70:73]
	v_mfma_f32_16x16x32_bf16 v[2:5], v[130:133], v[216:219], v[2:5]
	s_barrier
	s_setprio 0
	s_add_i32 s55, 0, 0x18000
	s_add_i32 s56, 0, 0x1c000
	v_add_u32_e32 v114, s55, v243
	v_add_u32_e32 v130, s56, v243
	ds_read_b128 v[102:105], v114
	ds_read_b128 v[106:109], v114 offset:1024
	ds_read_b128 v[110:113], v114 offset:2048
	ds_read_b128 v[114:117], v114 offset:3072
	ds_read_b128 v[118:121], v130
	ds_read_b128 v[122:125], v130 offset:1024
	ds_read_b128 v[126:129], v130 offset:2048
	ds_read_b128 v[130:133], v130 offset:3072
	s_add_u32 s40, s40, 0x3e000
	s_addc_u32 s41, s41, 0
	s_mov_b32 m0, s36
	v_lshl_add_u64 v[226:227], s[40:41], 0, v[14:15]
	ds_read_b128 v[166:169], v247 offset:32768
	ds_read_b128 v[170:173], v247 offset:33792
	ds_read_b128 v[174:177], v247 offset:34816
	ds_read_b128 v[178:181], v247 offset:35840
	ds_read_b128 v[182:185], v247 offset:36864
	ds_read_b128 v[186:189], v247 offset:37888
	ds_read_b128 v[212:215], v247 offset:38912
	ds_read_b128 v[216:219], v247 offset:39936
	global_load_lds_dwordx4 v[226:227], off
	v_lshl_add_u64 v[226:227], s[40:41], 0, v[190:191]
	s_mov_b32 m0, s12
	s_nop 0
	global_load_lds_dwordx4 v[226:227], off
	s_waitcnt vmcnt(8)
	s_waitcnt lgkmcnt(0)
	s_setprio 1
	s_barrier
	v_mfma_f32_16x16x32_bf16 v[162:165], v[102:105], v[166:169], v[162:165]
	v_mfma_f32_16x16x32_bf16 v[66:69], v[110:113], v[166:169], v[66:69]
	v_mfma_f32_16x16x32_bf16 v[158:161], v[102:105], v[174:177], v[158:161]
	v_mfma_f32_16x16x32_bf16 v[62:65], v[110:113], v[174:177], v[62:65]
	v_mfma_f32_16x16x32_bf16 v[146:149], v[102:105], v[182:185], v[146:149]
	v_mfma_f32_16x16x32_bf16 v[50:53], v[110:113], v[182:185], v[50:53]
	v_mfma_f32_16x16x32_bf16 v[138:141], v[102:105], v[212:215], v[138:141]
	v_mfma_f32_16x16x32_bf16 v[42:45], v[110:113], v[212:215], v[42:45]
	v_mfma_f32_16x16x32_bf16 v[162:165], v[106:109], v[170:173], v[162:165]
	v_mfma_f32_16x16x32_bf16 v[66:69], v[114:117], v[170:173], v[66:69]
	v_mfma_f32_16x16x32_bf16 v[158:161], v[106:109], v[178:181], v[158:161]
	v_mfma_f32_16x16x32_bf16 v[62:65], v[114:117], v[178:181], v[62:65]
	v_mfma_f32_16x16x32_bf16 v[146:149], v[106:109], v[186:189], v[146:149]
	v_mfma_f32_16x16x32_bf16 v[50:53], v[114:117], v[186:189], v[50:53]
	v_mfma_f32_16x16x32_bf16 v[138:141], v[106:109], v[216:219], v[138:141]
	v_mfma_f32_16x16x32_bf16 v[42:45], v[114:117], v[216:219], v[42:45]
	s_setprio 0
	s_setprio 1
	v_mfma_f32_16x16x32_bf16 v[154:157], v[118:121], v[166:169], v[154:157]
	v_mfma_f32_16x16x32_bf16 v[58:61], v[126:129], v[166:169], v[58:61]
	v_mfma_f32_16x16x32_bf16 v[150:153], v[118:121], v[174:177], v[150:153]
	v_mfma_f32_16x16x32_bf16 v[54:57], v[126:129], v[174:177], v[54:57]
	v_mfma_f32_16x16x32_bf16 v[142:145], v[118:121], v[182:185], v[142:145]
	v_mfma_f32_16x16x32_bf16 v[46:49], v[126:129], v[182:185], v[46:49]
	v_mfma_f32_16x16x32_bf16 v[134:137], v[118:121], v[212:215], v[134:137]
	v_mfma_f32_16x16x32_bf16 v[38:41], v[126:129], v[212:215], v[38:41]
	v_mfma_f32_16x16x32_bf16 v[154:157], v[122:125], v[170:173], v[154:157]
	v_mfma_f32_16x16x32_bf16 v[58:61], v[130:133], v[170:173], v[58:61]
	v_mfma_f32_16x16x32_bf16 v[150:153], v[122:125], v[178:181], v[150:153]
	v_mfma_f32_16x16x32_bf16 v[54:57], v[130:133], v[178:181], v[54:57]
	v_mfma_f32_16x16x32_bf16 v[142:145], v[122:125], v[186:189], v[142:145]
	v_mfma_f32_16x16x32_bf16 v[46:49], v[130:133], v[186:189], v[46:49]
	v_mfma_f32_16x16x32_bf16 v[134:137], v[122:125], v[216:219], v[134:137]
	v_mfma_f32_16x16x32_bf16 v[38:41], v[130:133], v[216:219], v[38:41]
	s_barrier
; #define PG8_LDA(dst, b, h) do { _Pragma("unroll") for (int m = 0; m < 4; ++m) _Pragma("unroll") for (int k = 0; k < 2; ++k) dst[m][k] = *(const LAS bf16x8*)(lds + PG8_SA(b, h) + aoff + m * 2048 + k * 1024); } while (0)
;     __device__ __forceinline__ void operator()(f32x4 (&acc)[2][2][4][2], const Unit& u, int wr, int wc, int fr, int fq) const {
;     ...
;         const float* cwt = cw + (size_t)u.pn * (2 * 4 * 128) + colb;
;         bf16_t* obase = Aout + u.pn * 128 + colb;
;         f32x4 qs[8];
; #pragma unroll
;         for (int i = 0; i < 8; ++i) { const int tok = u.pm * 248 + 62 * (2 * (i >> 2) + wr) - 1 + 16 * (i & 3) + fr; int tc = tok < 0 ? 0 : tok; tc = tc > ntok - 1 ? ntok - 1 : tc;
;             qs[i] = *(const f32x4*)(ss + (size_t)tc * 4); }
;         asm volatile("" : "+v"(qs[0]), "+v"(qs[1]), "+v"(qs[2]), "+v"(qs[3]), "+v"(qs[4]), "+v"(qs[5]), "+v"(qs[6]), "+v"(qs[7]));
; #pragma unroll
;         for (int ai = 0; ai < 2; ++ai) {
; #pragma unroll
;             for (int m = 0; m < 4; ++m) {
;                 const f32x4 q = qs[ai * 4 + m];
;                 const float rs = rsqrtf(((q[0] + q[1]) + (q[2] + q[3])) * (1.f / DM) + EPS);
; #pragma unroll
;                 for (int bj = 0; bj < 2; ++bj)
; #pragma unroll
;                     for (int n = 0; n < 2; ++n) acc[ai][bj][m][n] *= rs;
;             }
;         }
;         __builtin_amdgcn_sched_barrier(0); asm volatile("s_nop 1");
;         const bool f15 = fr == 15, f0 = fr == 0;
;         f32x2 wq[2][2][4];
;     ...
;         CONV_WLOAD(0, 0, 0);
; template <class Epi, bool SEG>
; __device__ __forceinline__ void gemm_phase(LAS unsigned char* lds, const Gemm g, const int G, const int cidx, const Epi& E) {
;     ...
;             PG8_WAIT_V(8); PG8_WAIT_L(0); PG8_BAR; PG8_MMA(1, 0, At, B0); PG8_MMA(1, 1, At, B1); PG8_BAR; PG8_SCHED;
;             PG8_LDB(B0, 1, 0); PG8_LDB(B1, 1, 1); PG8_SCHED; PG8_LDA(At, 1, 0); PG8_STAGE(PG8_SA(0, 1), a2 + hstepA, voffA);
;             PG8_WAIT_V(8); PG8_WAIT_L(0); PG8_BAR; PG8_MMA(0, 0, At, B0); PG8_MMA(0, 1, At, B1); PG8_BAR; PG8_SCHED;
;             PG8_LDA(At, 1, 1); PG8_STAGE(PG8_SB(1, 0), b3, voffB); PG8_STAGE(PG8_SB(1, 1), b3 + hstepB, voffB); PG8_STAGE(PG8_SA(1, 0), a3, voffA);
;             PG8_WAIT_V(8); PG8_WAIT_L(0); PG8_BAR; PG8_MMA(1, 0, At, B0); PG8_MMA(1, 1, At, B1); PG8_BAR; PG8_SCHED;
;         }
;         if (wr == 0) PG8_BAR;
	s_setprio 0
	s_add_i32 s40, s55, s10
	v_lshl_add_u64 v[208:209], v[208:209], 0, s[28:29]
	s_mov_b32 m0, s40
	ds_read_b128 v[166:169], v247 offset:49152
	ds_read_b128 v[170:173], v247 offset:50176
	ds_read_b128 v[174:177], v247 offset:51200
	ds_read_b128 v[178:181], v247 offset:52224
	ds_read_b128 v[182:185], v247 offset:53248
	ds_read_b128 v[186:189], v247 offset:54272
	ds_read_b128 v[212:215], v247 offset:55296
	ds_read_b128 v[216:219], v247 offset:56320
	global_load_lds_dwordx4 v[208:209], off
	s_add_i32 m0, s40, 0x2000
	s_add_u32 s22, s22, 0x40080
	v_lshl_add_u64 v[208:209], v[220:221], 0, s[28:29]
	s_addc_u32 s23, s23, 0
	s_add_i32 s40, s56, s10
	global_load_lds_dwordx4 v[208:209], off
	v_lshl_add_u64 v[208:209], s[22:23], 0, v[0:1]
	s_mov_b32 m0, s40
	s_nop 0
	global_load_lds_dwordx4 v[208:209], off
	v_lshl_add_u64 v[208:209], s[22:23], 0, v[192:193]
	s_add_i32 m0, s40, 0x2000
	s_nop 0
	global_load_lds_dwordx4 v[208:209], off
	v_lshl_add_u64 v[208:209], v[222:223], 0, s[28:29]
	s_mov_b32 m0, s13
	s_nop 0
	global_load_lds_dwordx4 v[208:209], off
	v_lshl_add_u64 v[208:209], v[224:225], 0, s[28:29]
	s_mov_b32 m0, s8
	s_nop 0
	global_load_lds_dwordx4 v[208:209], off
	s_waitcnt vmcnt(8)
	s_waitcnt lgkmcnt(0)
	s_setprio 1
	s_barrier
	v_mfma_f32_16x16x32_bf16 v[98:101], v[102:105], v[166:169], v[98:101]
	v_mfma_f32_16x16x32_bf16 v[34:37], v[110:113], v[166:169], v[34:37]
	v_mfma_f32_16x16x32_bf16 v[94:97], v[102:105], v[174:177], v[94:97]
	v_mfma_f32_16x16x32_bf16 v[30:33], v[110:113], v[174:177], v[30:33]
	v_mfma_f32_16x16x32_bf16 v[82:85], v[102:105], v[182:185], v[82:85]
	v_mfma_f32_16x16x32_bf16 v[18:21], v[110:113], v[182:185], v[18:21]
	v_mfma_f32_16x16x32_bf16 v[74:77], v[102:105], v[212:215], v[74:77]
	v_mfma_f32_16x16x32_bf16 v[6:9], v[110:113], v[212:215], v[6:9]
	v_mfma_f32_16x16x32_bf16 v[98:101], v[106:109], v[170:173], v[98:101]
	v_mfma_f32_16x16x32_bf16 v[34:37], v[114:117], v[170:173], v[34:37]
	v_mfma_f32_16x16x32_bf16 v[94:97], v[106:109], v[178:181], v[94:97]
	v_mfma_f32_16x16x32_bf16 v[30:33], v[114:117], v[178:181], v[30:33]
	v_mfma_f32_16x16x32_bf16 v[82:85], v[106:109], v[186:189], v[82:85]
	v_mfma_f32_16x16x32_bf16 v[18:21], v[114:117], v[186:189], v[18:21]
	v_mfma_f32_16x16x32_bf16 v[74:77], v[106:109], v[216:219], v[74:77]
	v_mfma_f32_16x16x32_bf16 v[6:9], v[114:117], v[216:219], v[6:9]
	s_setprio 0
	s_setprio 1
	v_mfma_f32_16x16x32_bf16 v[90:93], v[118:121], v[166:169], v[90:93]
	v_mfma_f32_16x16x32_bf16 v[26:29], v[126:129], v[166:169], v[26:29]
	v_mfma_f32_16x16x32_bf16 v[86:89], v[118:121], v[174:177], v[86:89]
	v_mfma_f32_16x16x32_bf16 v[22:25], v[126:129], v[174:177], v[22:25]
	v_mfma_f32_16x16x32_bf16 v[78:81], v[118:121], v[182:185], v[78:81]
	v_mfma_f32_16x16x32_bf16 v[10:13], v[126:129], v[182:185], v[10:13]
	v_mfma_f32_16x16x32_bf16 v[70:73], v[118:121], v[212:215], v[70:73]
	v_mfma_f32_16x16x32_bf16 v[2:5], v[126:129], v[212:215], v[2:5]
	v_mfma_f32_16x16x32_bf16 v[90:93], v[122:125], v[170:173], v[90:93]
	v_mfma_f32_16x16x32_bf16 v[26:29], v[130:133], v[170:173], v[26:29]
	v_mfma_f32_16x16x32_bf16 v[86:89], v[122:125], v[178:181], v[86:89]
	v_mfma_f32_16x16x32_bf16 v[22:25], v[130:133], v[178:181], v[22:25]
	v_mfma_f32_16x16x32_bf16 v[78:81], v[122:125], v[186:189], v[78:81]
	v_mfma_f32_16x16x32_bf16 v[10:13], v[130:133], v[186:189], v[10:13]
	v_mfma_f32_16x16x32_bf16 v[70:73], v[122:125], v[216:219], v[70:73]
	v_mfma_f32_16x16x32_bf16 v[2:5], v[130:133], v[216:219], v[2:5]
	s_barrier
	s_setprio 0
	s_add_i32 s54, s54, 2
	s_add_u32 s6, s6, 0x100
	s_addc_u32 s7, s7, 0
	s_add_u32 s52, s52, 0x100
	s_addc_u32 s53, s53, 0
	s_cmp_gt_u32 s54, 13
	s_cbranch_scc0 .LBB0_786
	s_mul_i32 s15, s31, 0xf8
	s_add_i32 s15, s15, -1
	v_add_u32_e32 v102, s15, v17
	v_add_u32_e32 v104, 16, v102
	v_add_u32_e32 v105, s1, v104
	v_med3_i32 v105, v105, 0, v242
	v_add_u32_e32 v104, s38, v104
	v_lshlrev_b32_e32 v106, 4, v105
	v_add_u32_e32 v105, 32, v102
	v_med3_i32 v104, v104, 0, v242
	v_lshlrev_b32_e32 v110, 4, v104
	v_add_u32_e32 v104, s38, v105
	s_ashr_i32 s21, s20, 31
	v_add_u32_e32 v108, 48, v102
	v_med3_i32 v104, v104, 0, v242
	s_lshl_b64 s[6:7], s[20:21], 12
	v_add_u32_e32 v103, s1, v102
	v_add_u32_e32 v107, s1, v105
	v_add_u32_e32 v109, s1, v108
	v_add_u32_e32 v102, s38, v102
	v_lshlrev_b32_e32 v111, 4, v104
	v_add_u32_e32 v104, s38, v108
	v_med3_i32 v103, v103, 0, v242
	v_med3_i32 v107, v107, 0, v242
	v_med3_i32 v109, v109, 0, v242
	v_med3_i32 v102, v102, 0, v242
	v_med3_i32 v104, v104, 0, v242
	v_lshl_add_u64 v[214:215], v[194:195], 0, s[6:7]
	v_readlane_b32 s6, v253, 24
	v_lshlrev_b32_e32 v103, 4, v103
	v_lshlrev_b32_e32 v107, 4, v107
	v_lshlrev_b32_e32 v109, 4, v109
	v_lshlrev_b32_e32 v102, 4, v102
	v_lshlrev_b32_e32 v108, 4, v104
	v_readlane_b32 s7, v253, 25
	s_nop 4
	global_load_dwordx4 v[174:177], v102, s[6:7]
	s_nop 0
	global_load_dwordx4 v[216:219], v103, s[6:7]
	s_nop 0
	global_load_dwordx4 v[166:169], v108, s[6:7]
	global_load_dwordx4 v[170:173], v111, s[6:7]
	global_load_dwordx4 v[178:181], v110, s[6:7]
	global_load_dwordx4 v[182:185], v109, s[6:7]
	global_load_dwordx4 v[186:189], v107, s[6:7]
	s_nop 0
	global_load_dwordx4 v[220:223], v106, s[6:7]
	global_load_dwordx4 v[114:117], v[214:215], off offset:1024
	global_load_dwordx4 v[110:113], v[214:215], off offset:3072
	global_load_dwordx4 v[130:133], v[214:215], off offset:512
	global_load_dwordx4 v[102:105], v[214:215], off offset:1536
	global_load_dwordx4 v[126:129], v[214:215], off offset:2560
	global_load_dwordx4 v[106:109], v[214:215], off offset:3584
	global_load_dwordx4 v[122:125], v[214:215], off
	global_load_dwordx4 v[118:121], v[214:215], off offset:2048
	v_readlane_b32 s6, v255, 19
	v_readlane_b32 s7, v255, 20
	s_mov_b64 s[46:47], s[82:83]
	s_and_b64 vcc, exec, s[6:7]
	s_cbranch_vccz .LBB0_789
	s_barrier
;     __device__ __forceinline__ void operator()(f32x4 (&acc)[2][2][4][2], const Unit& u, int wr, int wc, int fr, int fq) const {
;     ...
;         for (int ai = 0; ai < 2; ++ai) {
; #pragma unroll
;             for (int m = 0; m < 4; ++m) {
;                 const f32x4 q = qs[ai * 4 + m];
;                 const float rs = rsqrtf(((q[0] + q[1]) + (q[2] + q[3])) * (1.f / DM) + EPS);
; #pragma unroll
;                 for (int bj = 0; bj < 2; ++bj)
; #pragma unroll
;                     for (int n = 0; n < 2; ++n) acc[ai][bj][m][n] *= rs;
;     ...
;                 for (int ai = 0; ai < 2; ++ai) {
;                     const int tokbase = u.pm * 248 + 62 * (2 * ai + wr) - 1;
; #pragma unroll
;                     for (int m = 0; m < 4; ++m) {
;                         const int rr = 16 * m + fr, tok = tokbase + rr, pos = tok & Tmask;
;                         const bool lbad = pos == 0, rbad = pos == Tmask;
;                         float uu[2][2];
; #pragma unroll
;                         for (int bj = 0; bj < 2; ++bj) {
;                             const f32x4 c = acc[ai][bj][m][n], cm = acc[ai][bj][m > 0 ? m - 1 : m][n], cp = acc[ai][bj][m < 3 ? m + 1 : m][n];
; #pragma unroll
;                             for (int jj = 0; jj < 2; ++jj) {
;                                 const int j = 2 * jh + jj;
;                                 float t = bb[bj][jj] + w1[bj][jj] * c[j];
;                                 fmac_shr1(t, c[j], w0[bj][jj]);
;                                 fmac_shl1(t, c[j], w2[bj][jj]);
;                                 if (m > 0) fmac_ror1(t, cm[j], w0f[bj][jj]);
;                                 if (m < 3) fmac_ror15(t, cp[j], w2l[bj][jj]);
;                                 uu[bj][jj] = t;
;                             }
;                         }
;                         if (__any(lbad | rbad)) {
; #pragma unroll
;                             for (int bj = 0; bj < 2; ++bj) {
;                                 const f32x4 c = acc[ai][bj][m][n], cm = acc[ai][bj][m > 0 ? m - 1 : m][n], cp = acc[ai][bj][m < 3 ? m + 1 : m][n];
; #pragma unroll
;                                 for (int jj = 0; jj < 2; ++jj) {
;                                     const int j = 2 * jh + jj;
;                                     const float up = dpp_ror1(f15 ? cm[j] : c[j]), dn = dpp_ror15(f0 ? cp[j] : c[j]);
.LBB0_789:
	s_waitcnt vmcnt(8)
	s_nop 0
	v_mov_b32_e32 v208, v217
	v_mov_b32_e32 v209, v218
	v_mov_b32_e32 v217, v219
	v_mov_b32_e32 v218, v221
	v_mov_b32_e32 v219, v222
	v_mov_b32_e32 v221, v223
	v_pk_add_f32 v[216:217], v[208:209], v[216:217]
	v_pk_add_f32 v[218:219], v[218:219], v[220:221]
	v_mov_b32_e32 v221, v216
	v_mov_b32_e32 v220, v218
	v_mov_b32_e32 v216, v219
	v_pk_add_f32 v[216:217], v[220:221], v[216:217]
	s_nop 0
	v_pk_fma_f32 v[216:217], v[216:217], s[60:61], v[202:203] op_sel_hi:[1,0,0]
	s_nop 0
	v_mul_f32_e32 v218, 0x4b800000, v217
	v_cmp_gt_f32_e64 s[6:7], s59, v217
	v_cmp_gt_f32_e32 vcc, s59, v216
	s_nop 0
	v_cndmask_b32_e64 v217, v217, v218, s[6:7]
	v_rsq_f32_e32 v217, v217
	s_nop 0
	v_mul_f32_e32 v218, 0x45800000, v217
	v_cndmask_b32_e64 v212, v217, v218, s[6:7]
	v_mul_f32_e32 v217, 0x4b800000, v216
	v_cndmask_b32_e32 v216, v216, v217, vcc
	v_rsq_f32_e32 v216, v216
	v_pk_mul_f32 v[224:225], v[154:155], v[212:213] op_sel_hi:[1,0]
	v_pk_mul_f32 v[228:229], v[162:163], v[212:213] op_sel_hi:[1,0]
	v_mul_f32_e32 v217, 0x45800000, v216
	v_cndmask_b32_e32 v154, v216, v217, vcc
	v_pk_mul_f32 v[162:163], v[158:159], v[154:155] op_sel_hi:[1,0]
	v_pk_mul_f32 v[158:159], v[150:151], v[154:155] op_sel_hi:[1,0]
	s_nop 1
	s_add_i32 s21, s15, s1
	v_add_u32_e32 v249, s21, v17
	v_and_b32_e32 v150, s35, v249
	v_cmp_eq_u32_e64 s[80:81], s35, v150
	v_cmp_eq_u32_e64 s[82:83], 0, v150
	s_or_b64 s[6:7], s[82:83], s[80:81]
	s_mov_b64 vcc, s[6:7]
	s_waitcnt vmcnt(7)
	v_cndmask_b32_e64 v251, 0, v115, s[42:43]
	v_cndmask_b32_e64 v234, 0, v114, s[42:43]
	s_waitcnt vmcnt(6)
	v_cndmask_b32_e64 v151, 0, v111, s[42:43]
	s_waitcnt vmcnt(4)
	v_fma_f32 v220, v130, v228, v102
	v_fma_f32 v221, v131, v229, v103
	s_waitcnt vmcnt(2)
	v_fma_f32 v222, v126, v224, v106
	v_fma_f32 v223, v127, v225, v107
	s_waitcnt vmcnt(1)
	v_fmac_f32_dpp v220, v228, v122 row_shr:1 row_mask:0xf bank_mask:0xf bound_ctrl:0
	v_fmac_f32_dpp v221, v229, v123 row_shr:1 row_mask:0xf bank_mask:0xf bound_ctrl:0
	s_waitcnt vmcnt(0)
	v_fmac_f32_dpp v222, v224, v118 row_shr:1 row_mask:0xf bank_mask:0xf bound_ctrl:0
	v_fmac_f32_dpp v223, v225, v119 row_shr:1 row_mask:0xf bank_mask:0xf bound_ctrl:0
	v_cndmask_b32_e64 v213, 0, v110, s[42:43]
	v_fmac_f32_dpp v220, v228, v114 row_shl:1 row_mask:0xf bank_mask:0xf bound_ctrl:0
	v_fmac_f32_dpp v221, v229, v115 row_shl:1 row_mask:0xf bank_mask:0xf bound_ctrl:0
	v_fmac_f32_dpp v222, v224, v110 row_shl:1 row_mask:0xf bank_mask:0xf bound_ctrl:0
	v_fmac_f32_dpp v223, v225, v111 row_shl:1 row_mask:0xf bank_mask:0xf bound_ctrl:0
	s_nop 0
	v_fmac_f32_dpp v220, v162, v234 row_ror:15 row_mask:0xf bank_mask:0xf bound_ctrl:0
	v_fmac_f32_dpp v221, v163, v251 row_ror:15 row_mask:0xf bank_mask:0xf bound_ctrl:0
	v_fmac_f32_dpp v222, v158, v213 row_ror:15 row_mask:0xf bank_mask:0xf bound_ctrl:0
	v_fmac_f32_dpp v223, v159, v151 row_ror:15 row_mask:0xf bank_mask:0xf bound_ctrl:0
	s_cbranch_vccz .LBB0_791
	v_cndmask_b32_e64 v150, v228, v162, s[44:45]
	v_mov_b32_e32 v216, v1
	v_mov_b32_e32 v208, v1
	v_mov_b32_e32 v209, v1
	v_mov_b32_dpp v216, v150 row_ror:15 row_mask:0xf bank_mask:0xf
	v_cndmask_b32_e64 v150, v229, v163, s[44:45]
	v_mov_b32_e32 v217, v1
	v_mov_b32_dpp v208, v228 row_ror:1 row_mask:0xf bank_mask:0xf
	v_mov_b32_dpp v209, v229 row_ror:1 row_mask:0xf bank_mask:0xf
	v_mov_b32_dpp v217, v150 row_ror:15 row_mask:0xf bank_mask:0xf
	v_pk_mul_f32 v[208:209], v[122:123], v[208:209]
	v_pk_mul_f32 v[216:217], v[114:115], v[216:217]
	v_cndmask_b32_e64 v209, 0, v209, s[82:83]
	v_cndmask_b32_e64 v208, 0, v208, s[82:83]
	v_cndmask_b32_e64 v217, 0, v217, s[80:81]
	v_cndmask_b32_e64 v216, 0, v216, s[80:81]
	v_pk_add_f32 v[208:209], v[208:209], v[216:217]
	v_cndmask_b32_e64 v150, v224, v158, s[44:45]
	v_mov_b32_e32 v216, v1
	v_pk_add_f32 v[220:221], v[220:221], v[208:209] neg_lo:[0,1] neg_hi:[0,1]
	v_mov_b32_e32 v208, v1
	v_mov_b32_dpp v216, v150 row_ror:15 row_mask:0xf bank_mask:0xf
	v_mov_b32_e32 v209, v1
	v_cndmask_b32_e64 v150, v225, v159, s[44:45]
	v_mov_b32_e32 v217, v1
	v_mov_b32_dpp v208, v224 row_ror:1 row_mask:0xf bank_mask:0xf
	v_mov_b32_dpp v209, v225 row_ror:1 row_mask:0xf bank_mask:0xf
	v_mov_b32_dpp v217, v150 row_ror:15 row_mask:0xf bank_mask:0xf
	v_pk_mul_f32 v[208:209], v[118:119], v[208:209]
	v_pk_mul_f32 v[216:217], v[110:111], v[216:217]
	v_cndmask_b32_e64 v209, 0, v209, s[82:83]
	v_cndmask_b32_e64 v208, 0, v208, s[82:83]
	v_cndmask_b32_e64 v217, 0, v217, s[80:81]
	v_cndmask_b32_e64 v216, 0, v216, s[80:81]
	v_pk_add_f32 v[208:209], v[208:209], v[216:217]
	s_nop 0
	v_pk_add_f32 v[222:223], v[222:223], v[208:209] neg_lo:[0,1] neg_hi:[0,1]

; #define PG8_STAGE(bufoff, gbase, voff) do { _Pragma("unroll") for (int _i = 0; _i < 2; ++_i) \
;         __builtin_amdgcn_global_load_lds((const unsigned*)((const char*)(gbase) + (voff)[_i]), (LAS unsigned*)(lds + (bufoff) + ldsw + _i * 8192), 16, 0, 0); } while (0)
; #define PG8_LDA(dst, b, h) do { _Pragma("unroll") for (int m = 0; m < 4; ++m) _Pragma("unroll") for (int k = 0; k < 2; ++k) dst[m][k] = *(const LAS bf16x8*)(lds + PG8_SA(b, h) + aoff + m * 2048 + k * 1024); } while (0)
; #define PG8_LDB(dst, b, h) do { _Pragma("unroll") for (int n = 0; n < 2; ++n) _Pragma("unroll") for (int k = 0; k < 2; ++k) dst[n][k] = *(const LAS bf16x8*)(lds + PG8_SB(b, h) + boff + n * 2048 + k * 1024); } while (0)
; #define PG8_MMA(ai, bj, At, Bt) do { __builtin_amdgcn_s_setprio(1); _Pragma("unroll") for (int m = 0; m < 4; ++m) _Pragma("unroll") for (int n = 0; n < 2; ++n) _Pragma("unroll") for (int k = 0; k < 2; ++k) \
;         acc[ai][bj][m][n] = __builtin_amdgcn_mfma_f32_16x16x32_bf16(Bt[n][k], At[m][k], acc[ai][bj][m][n], 0, 0, 0); __builtin_amdgcn_s_setprio(0); } while (0)
; #define PG8_WAIT_V(n) asm volatile("s_waitcnt vmcnt(" #n ")" ::: "memory")
; #define PG8_WAIT_L(n) asm volatile("s_waitcnt lgkmcnt(" #n ")" ::: "memory")
; #define PG8_BAR __builtin_amdgcn_s_barrier()
; #define PG8_SCHED __builtin_amdgcn_sched_barrier(0)
; template <class Epi, bool SEG>
; __device__ __forceinline__ void gemm_phase(LAS unsigned char* lds, const Gemm g, const int G, const int cidx, const Epi& E) {
;     ...
;         for (int t = 0; t < nt; t += 2) {
;             const bool last = (t == nt - 2);
;             const char* a1 = cA + (size_t)(t + 1) * kstep;
;             const char* a2 = last ? nA : cA + (size_t)(t + 2) * kstep; const char* b2 = last ? nB : cB + (size_t)(t + 2) * kstep;
;             const char* a3 = a2 + kstep; const char* b3 = b2 + kstep;
;             PG8_LDB(B0, 0, 0); PG8_LDB(B1, 0, 1); PG8_SCHED; PG8_LDA(At, 0, 0); PG8_STAGE(PG8_SA(1, 1), a1 + hstepA, voffA);
;             PG8_WAIT_V(8); PG8_WAIT_L(0); PG8_BAR; PG8_MMA(0, 0, At, B0); PG8_MMA(0, 1, At, B1); PG8_BAR; PG8_SCHED;
;             PG8_LDA(At, 0, 1); PG8_STAGE(PG8_SB(0, 0), b2, voffB); PG8_STAGE(PG8_SB(0, 1), b2 + hstepB, voffB); PG8_STAGE(PG8_SA(0, 0), a2, voffA);
;             PG8_WAIT_V(8); PG8_WAIT_L(0); PG8_BAR; PG8_MMA(1, 0, At, B0); PG8_MMA(1, 1, At, B1); PG8_BAR; PG8_SCHED;
.LBB0_958:
	s_add_u32 s20, s18, 0x100
	s_addc_u32 s21, s19, 0
	s_add_i32 s55, 0, 0x10000
	s_cmp_eq_u32 s54, 40
	s_cselect_b32 s47, s7, s21
	s_cselect_b32 s46, s6, s20
	s_cselect_b32 s23, s17, s53
	s_cselect_b32 s22, s16, s52
	s_add_i32 s56, 0, 0x14000
	v_add_u32_e32 v146, s55, v228
	v_add_u32_e32 v162, s56, v228
	ds_read_b128 v[130:133], v146
	ds_read_b128 v[138:141], v146 offset:1024
	ds_read_b128 v[142:145], v146 offset:2048
	ds_read_b128 v[146:149], v146 offset:3072
	ds_read_b128 v[150:153], v162
	ds_read_b128 v[154:157], v162 offset:1024
	ds_read_b128 v[158:161], v162 offset:2048
	ds_read_b128 v[162:165], v162 offset:3072
	v_lshl_add_u64 v[208:209], s[18:19], 0, v[198:199]
	s_add_i32 m0, s30, 0xc000
	ds_read_b128 v[166:169], v244
	ds_read_b128 v[170:173], v244 offset:1024
	ds_read_b128 v[174:177], v244 offset:2048
	ds_read_b128 v[178:181], v244 offset:3072
	ds_read_b128 v[182:185], v244 offset:4096
	ds_read_b128 v[186:189], v244 offset:5120
	ds_read_b128 v[190:193], v244 offset:6144
	ds_read_b128 v[212:215], v244 offset:7168
	global_load_lds_dwordx4 v[208:209], off
	v_lshl_add_u64 v[208:209], s[18:19], 0, v[200:201]
	s_add_i32 m0, s30, 0xe000
	s_nop 0
	global_load_lds_dwordx4 v[208:209], off
	s_waitcnt vmcnt(8)
	s_waitcnt lgkmcnt(0)
	s_setprio 1
	s_barrier
	v_mfma_f32_16x16x32_bf16 v[134:137], v[130:133], v[166:169], v[134:137]
	v_mfma_f32_16x16x32_bf16 v[126:129], v[142:145], v[166:169], v[126:129]
	v_mfma_f32_16x16x32_bf16 v[114:117], v[130:133], v[174:177], v[114:117]
	v_mfma_f32_16x16x32_bf16 v[110:113], v[142:145], v[174:177], v[110:113]
	v_mfma_f32_16x16x32_bf16 v[98:101], v[130:133], v[182:185], v[98:101]
	v_mfma_f32_16x16x32_bf16 v[94:97], v[142:145], v[182:185], v[94:97]
	v_mfma_f32_16x16x32_bf16 v[82:85], v[130:133], v[190:193], v[82:85]
	v_mfma_f32_16x16x32_bf16 v[78:81], v[142:145], v[190:193], v[78:81]
	v_mfma_f32_16x16x32_bf16 v[134:137], v[138:141], v[170:173], v[134:137]
	v_mfma_f32_16x16x32_bf16 v[126:129], v[146:149], v[170:173], v[126:129]
	v_mfma_f32_16x16x32_bf16 v[114:117], v[138:141], v[178:181], v[114:117]
	v_mfma_f32_16x16x32_bf16 v[110:113], v[146:149], v[178:181], v[110:113]
	v_mfma_f32_16x16x32_bf16 v[98:101], v[138:141], v[186:189], v[98:101]
	v_mfma_f32_16x16x32_bf16 v[94:97], v[146:149], v[186:189], v[94:97]
	v_mfma_f32_16x16x32_bf16 v[82:85], v[138:141], v[212:215], v[82:85]
	v_mfma_f32_16x16x32_bf16 v[78:81], v[146:149], v[212:215], v[78:81]
	s_setprio 0
	s_setprio 1
	v_mfma_f32_16x16x32_bf16 v[122:125], v[150:153], v[166:169], v[122:125]
	v_mfma_f32_16x16x32_bf16 v[118:121], v[158:161], v[166:169], v[118:121]
	v_mfma_f32_16x16x32_bf16 v[106:109], v[150:153], v[174:177], v[106:109]
	v_mfma_f32_16x16x32_bf16 v[102:105], v[158:161], v[174:177], v[102:105]
	v_mfma_f32_16x16x32_bf16 v[90:93], v[150:153], v[182:185], v[90:93]
	v_mfma_f32_16x16x32_bf16 v[86:89], v[158:161], v[182:185], v[86:89]
	v_mfma_f32_16x16x32_bf16 v[74:77], v[150:153], v[190:193], v[74:77]
	v_mfma_f32_16x16x32_bf16 v[70:73], v[158:161], v[190:193], v[70:73]
	v_mfma_f32_16x16x32_bf16 v[122:125], v[154:157], v[170:173], v[122:125]
	v_mfma_f32_16x16x32_bf16 v[118:121], v[162:165], v[170:173], v[118:121]
	v_mfma_f32_16x16x32_bf16 v[106:109], v[154:157], v[178:181], v[106:109]
	v_mfma_f32_16x16x32_bf16 v[102:105], v[162:165], v[178:181], v[102:105]
	v_mfma_f32_16x16x32_bf16 v[90:93], v[154:157], v[186:189], v[90:93]
	v_mfma_f32_16x16x32_bf16 v[86:89], v[162:165], v[186:189], v[86:89]
	v_mfma_f32_16x16x32_bf16 v[74:77], v[154:157], v[212:215], v[74:77]
	v_mfma_f32_16x16x32_bf16 v[70:73], v[162:165], v[212:215], v[70:73]
	s_barrier
	s_setprio 0
	s_add_i32 s18, s55, s9
	v_lshl_add_u64 v[208:209], s[22:23], 0, v[0:1]
	s_mov_b32 m0, s18
	ds_read_b128 v[166:169], v244 offset:16384
	ds_read_b128 v[170:173], v244 offset:17408
	ds_read_b128 v[174:177], v244 offset:18432
	ds_read_b128 v[178:181], v244 offset:19456
	ds_read_b128 v[182:185], v244 offset:20480
	ds_read_b128 v[186:189], v244 offset:21504
	ds_read_b128 v[190:193], v244 offset:22528
	ds_read_b128 v[212:215], v244 offset:23552
	global_load_lds_dwordx4 v[208:209], off
	s_add_i32 m0, s18, 0x2000
	s_add_u32 s18, s22, 0xb0000
	v_lshl_add_u64 v[216:217], s[22:23], 0, v[14:15]
	s_addc_u32 s19, s23, 0
	s_add_i32 s55, s56, s9
	global_load_lds_dwordx4 v[216:217], off
	v_lshl_add_u64 v[218:219], s[18:19], 0, v[0:1]
	s_mov_b32 m0, s55
	v_lshl_add_u64 v[220:221], s[46:47], 0, v[194:195]
	global_load_lds_dwordx4 v[218:219], off
	v_lshl_add_u64 v[218:219], s[18:19], 0, v[14:15]
	s_add_i32 m0, s55, 0x2000
	s_nop 0
	global_load_lds_dwordx4 v[218:219], off
	v_lshl_add_u64 v[218:219], s[46:47], 0, v[196:197]
	s_mov_b32 m0, s30
	s_nop 0
	global_load_lds_dwordx4 v[218:219], off
	s_mov_b32 m0, s31
	s_nop 0
	global_load_lds_dwordx4 v[220:221], off
	s_waitcnt vmcnt(8)
	s_waitcnt lgkmcnt(0)
	s_setprio 1
	s_barrier
; #define PG8_STAGE(bufoff, gbase, voff) do { _Pragma("unroll") for (int _i = 0; _i < 2; ++_i) \
;         __builtin_amdgcn_global_load_lds((const unsigned*)((const char*)(gbase) + (voff)[_i]), (LAS unsigned*)(lds + (bufoff) + ldsw + _i * 8192), 16, 0, 0); } while (0)
; #define PG8_LDA(dst, b, h) do { _Pragma("unroll") for (int m = 0; m < 4; ++m) _Pragma("unroll") for (int k = 0; k < 2; ++k) dst[m][k] = *(const LAS bf16x8*)(lds + PG8_SA(b, h) + aoff + m * 2048 + k * 1024); } while (0)
; #define PG8_LDB(dst, b, h) do { _Pragma("unroll") for (int n = 0; n < 2; ++n) _Pragma("unroll") for (int k = 0; k < 2; ++k) dst[n][k] = *(const LAS bf16x8*)(lds + PG8_SB(b, h) + boff + n * 2048 + k * 1024); } while (0)
; #define PG8_MMA(ai, bj, At, Bt) do { __builtin_amdgcn_s_setprio(1); _Pragma("unroll") for (int m = 0; m < 4; ++m) _Pragma("unroll") for (int n = 0; n < 2; ++n) _Pragma("unroll") for (int k = 0; k < 2; ++k) \
;         acc[ai][bj][m][n] = __builtin_amdgcn_mfma_f32_16x16x32_bf16(Bt[n][k], At[m][k], acc[ai][bj][m][n], 0, 0, 0); __builtin_amdgcn_s_setprio(0); } while (0)
; #define PG8_WAIT_V(n) asm volatile("s_waitcnt vmcnt(" #n ")" ::: "memory")
; #define PG8_WAIT_L(n) asm volatile("s_waitcnt lgkmcnt(" #n ")" ::: "memory")
; #define PG8_BAR __builtin_amdgcn_s_barrier()
; #define PG8_SCHED __builtin_amdgcn_sched_barrier(0)
; template <class Epi, bool SEG>
; __device__ __forceinline__ void gemm_phase(LAS unsigned char* lds, const Gemm g, const int G, const int cidx, const Epi& E) {
;     ...
;             PG8_WAIT_V(8); PG8_WAIT_L(0); PG8_BAR; PG8_MMA(1, 0, At, B0); PG8_MMA(1, 1, At, B1); PG8_BAR; PG8_SCHED;
;             PG8_LDB(B0, 1, 0); PG8_LDB(B1, 1, 1); PG8_SCHED; PG8_LDA(At, 1, 0); PG8_STAGE(PG8_SA(0, 1), a2 + hstepA, voffA);
;             PG8_WAIT_V(8); PG8_WAIT_L(0); PG8_BAR; PG8_MMA(0, 0, At, B0); PG8_MMA(0, 1, At, B1); PG8_BAR; PG8_SCHED;
;             PG8_LDA(At, 1, 1); PG8_STAGE(PG8_SB(1, 0), b3, voffB); PG8_STAGE(PG8_SB(1, 1), b3 + hstepB, voffB); PG8_STAGE(PG8_SA(1, 0), a3, voffA);
	v_mfma_f32_16x16x32_bf16 v[66:69], v[130:133], v[166:169], v[66:69]
	v_mfma_f32_16x16x32_bf16 v[62:65], v[142:145], v[166:169], v[62:65]
	v_mfma_f32_16x16x32_bf16 v[50:53], v[130:133], v[174:177], v[50:53]
	v_mfma_f32_16x16x32_bf16 v[46:49], v[142:145], v[174:177], v[46:49]
	v_mfma_f32_16x16x32_bf16 v[34:37], v[130:133], v[182:185], v[34:37]
	v_mfma_f32_16x16x32_bf16 v[30:33], v[142:145], v[182:185], v[30:33]
	v_mfma_f32_16x16x32_bf16 v[18:21], v[130:133], v[190:193], v[18:21]
	v_mfma_f32_16x16x32_bf16 v[10:13], v[142:145], v[190:193], v[10:13]
	v_mfma_f32_16x16x32_bf16 v[66:69], v[138:141], v[170:173], v[66:69]
	v_mfma_f32_16x16x32_bf16 v[62:65], v[146:149], v[170:173], v[62:65]
	v_mfma_f32_16x16x32_bf16 v[50:53], v[138:141], v[178:181], v[50:53]
	v_mfma_f32_16x16x32_bf16 v[46:49], v[146:149], v[178:181], v[46:49]
	v_mfma_f32_16x16x32_bf16 v[34:37], v[138:141], v[186:189], v[34:37]
	v_mfma_f32_16x16x32_bf16 v[30:33], v[146:149], v[186:189], v[30:33]
	v_mfma_f32_16x16x32_bf16 v[18:21], v[138:141], v[212:215], v[18:21]
	v_mfma_f32_16x16x32_bf16 v[10:13], v[146:149], v[212:215], v[10:13]
	s_setprio 0
	s_setprio 1
	v_mfma_f32_16x16x32_bf16 v[58:61], v[150:153], v[166:169], v[58:61]
	v_mfma_f32_16x16x32_bf16 v[54:57], v[158:161], v[166:169], v[54:57]
	v_mfma_f32_16x16x32_bf16 v[42:45], v[150:153], v[174:177], v[42:45]
	v_mfma_f32_16x16x32_bf16 v[38:41], v[158:161], v[174:177], v[38:41]
	v_mfma_f32_16x16x32_bf16 v[26:29], v[150:153], v[182:185], v[26:29]
	v_mfma_f32_16x16x32_bf16 v[22:25], v[158:161], v[182:185], v[22:25]
	v_mfma_f32_16x16x32_bf16 v[6:9], v[150:153], v[190:193], v[6:9]
	v_mfma_f32_16x16x32_bf16 v[2:5], v[158:161], v[190:193], v[2:5]
	v_mfma_f32_16x16x32_bf16 v[58:61], v[154:157], v[170:173], v[58:61]
	v_mfma_f32_16x16x32_bf16 v[54:57], v[162:165], v[170:173], v[54:57]
	v_mfma_f32_16x16x32_bf16 v[42:45], v[154:157], v[178:181], v[42:45]
	v_mfma_f32_16x16x32_bf16 v[38:41], v[162:165], v[178:181], v[38:41]
	v_mfma_f32_16x16x32_bf16 v[26:29], v[154:157], v[186:189], v[26:29]
	v_mfma_f32_16x16x32_bf16 v[22:25], v[162:165], v[186:189], v[22:25]
	v_mfma_f32_16x16x32_bf16 v[6:9], v[154:157], v[212:215], v[6:9]
	v_mfma_f32_16x16x32_bf16 v[2:5], v[162:165], v[212:215], v[2:5]
	s_barrier
	s_setprio 0
	s_add_i32 s55, 0, 0x18000
	s_add_i32 s56, 0, 0x1c000
	v_add_u32_e32 v146, s55, v228
	v_add_u32_e32 v162, s56, v228
	ds_read_b128 v[130:133], v146
	ds_read_b128 v[138:141], v146 offset:1024
	ds_read_b128 v[142:145], v146 offset:2048
	ds_read_b128 v[146:149], v146 offset:3072
	ds_read_b128 v[150:153], v162
	ds_read_b128 v[154:157], v162 offset:1024
	ds_read_b128 v[158:161], v162 offset:2048
	ds_read_b128 v[162:165], v162 offset:3072
	s_add_u32 s18, s46, 0xb0000
	s_addc_u32 s19, s47, 0
	s_mov_b32 m0, s36
	v_lshl_add_u64 v[222:223], s[18:19], 0, v[196:197]
	ds_read_b128 v[166:169], v244 offset:32768
	ds_read_b128 v[170:173], v244 offset:33792
	ds_read_b128 v[174:177], v244 offset:34816
	ds_read_b128 v[178:181], v244 offset:35840
	ds_read_b128 v[182:185], v244 offset:36864
	ds_read_b128 v[186:189], v244 offset:37888
	ds_read_b128 v[190:193], v244 offset:38912
	ds_read_b128 v[212:215], v244 offset:39936
	global_load_lds_dwordx4 v[222:223], off
	v_lshl_add_u64 v[222:223], s[18:19], 0, v[194:195]
	s_mov_b32 m0, s38
	s_nop 0
	global_load_lds_dwordx4 v[222:223], off
	s_waitcnt vmcnt(8)
	s_waitcnt lgkmcnt(0)
	s_setprio 1
	s_barrier
	v_mfma_f32_16x16x32_bf16 v[134:137], v[130:133], v[166:169], v[134:137]
	v_mfma_f32_16x16x32_bf16 v[126:129], v[142:145], v[166:169], v[126:129]
	v_mfma_f32_16x16x32_bf16 v[114:117], v[130:133], v[174:177], v[114:117]
	v_mfma_f32_16x16x32_bf16 v[110:113], v[142:145], v[174:177], v[110:113]
	v_mfma_f32_16x16x32_bf16 v[98:101], v[130:133], v[182:185], v[98:101]
	v_mfma_f32_16x16x32_bf16 v[94:97], v[142:145], v[182:185], v[94:97]
	v_mfma_f32_16x16x32_bf16 v[82:85], v[130:133], v[190:193], v[82:85]
	v_mfma_f32_16x16x32_bf16 v[78:81], v[142:145], v[190:193], v[78:81]
	v_mfma_f32_16x16x32_bf16 v[134:137], v[138:141], v[170:173], v[134:137]
	v_mfma_f32_16x16x32_bf16 v[126:129], v[146:149], v[170:173], v[126:129]
	v_mfma_f32_16x16x32_bf16 v[114:117], v[138:141], v[178:181], v[114:117]
	v_mfma_f32_16x16x32_bf16 v[110:113], v[146:149], v[178:181], v[110:113]
	v_mfma_f32_16x16x32_bf16 v[98:101], v[138:141], v[186:189], v[98:101]
	v_mfma_f32_16x16x32_bf16 v[94:97], v[146:149], v[186:189], v[94:97]
	v_mfma_f32_16x16x32_bf16 v[82:85], v[138:141], v[212:215], v[82:85]
	v_mfma_f32_16x16x32_bf16 v[78:81], v[146:149], v[212:215], v[78:81]
	s_setprio 0
	s_setprio 1
	v_mfma_f32_16x16x32_bf16 v[122:125], v[150:153], v[166:169], v[122:125]
	v_mfma_f32_16x16x32_bf16 v[118:121], v[158:161], v[166:169], v[118:121]
	v_mfma_f32_16x16x32_bf16 v[106:109], v[150:153], v[174:177], v[106:109]
	v_mfma_f32_16x16x32_bf16 v[102:105], v[158:161], v[174:177], v[102:105]
	v_mfma_f32_16x16x32_bf16 v[90:93], v[150:153], v[182:185], v[90:93]
	v_mfma_f32_16x16x32_bf16 v[86:89], v[158:161], v[182:185], v[86:89]
	v_mfma_f32_16x16x32_bf16 v[74:77], v[150:153], v[190:193], v[74:77]
	v_mfma_f32_16x16x32_bf16 v[70:73], v[158:161], v[190:193], v[70:73]
	v_mfma_f32_16x16x32_bf16 v[122:125], v[154:157], v[170:173], v[122:125]
	v_mfma_f32_16x16x32_bf16 v[118:121], v[162:165], v[170:173], v[118:121]
	v_mfma_f32_16x16x32_bf16 v[106:109], v[154:157], v[178:181], v[106:109]
	v_mfma_f32_16x16x32_bf16 v[102:105], v[162:165], v[178:181], v[102:105]
	v_mfma_f32_16x16x32_bf16 v[90:93], v[154:157], v[186:189], v[90:93]
	v_mfma_f32_16x16x32_bf16 v[86:89], v[162:165], v[186:189], v[86:89]
	v_mfma_f32_16x16x32_bf16 v[74:77], v[154:157], v[212:215], v[74:77]
	v_mfma_f32_16x16x32_bf16 v[70:73], v[162:165], v[212:215], v[70:73]
	s_barrier
; #define PG8_STAGE(bufoff, gbase, voff) do { _Pragma("unroll") for (int _i = 0; _i < 2; ++_i) \
;         __builtin_amdgcn_global_load_lds((const unsigned*)((const char*)(gbase) + (voff)[_i]), (LAS unsigned*)(lds + (bufoff) + ldsw + _i * 8192), 16, 0, 0); } while (0)
; #define PG8_LDA(dst, b, h) do { _Pragma("unroll") for (int m = 0; m < 4; ++m) _Pragma("unroll") for (int k = 0; k < 2; ++k) dst[m][k] = *(const LAS bf16x8*)(lds + PG8_SA(b, h) + aoff + m * 2048 + k * 1024); } while (0)
; #define PG8_LDB(dst, b, h) do { _Pragma("unroll") for (int n = 0; n < 2; ++n) _Pragma("unroll") for (int k = 0; k < 2; ++k) dst[n][k] = *(const LAS bf16x8*)(lds + PG8_SB(b, h) + boff + n * 2048 + k * 1024); } while (0)
; #define PG8_WAIT_V(n) asm volatile("s_waitcnt vmcnt(" #n ")" ::: "memory")
; #define PG8_WAIT_L(n) asm volatile("s_waitcnt lgkmcnt(" #n ")" ::: "memory")
; #define PG8_BAR __builtin_amdgcn_s_barrier()
; #define PG8_SCHED __builtin_amdgcn_sched_barrier(0)
;     __device__ __forceinline__ void operator()(f32x4 (&acc)[2][2][4][2], const Unit& u, int wr, int wc, int fr, int fq) const {
;         const int col0 = u.pn * BM + wc * 32 + 8 * fq;
;         bf16_t* rp0 = x + (size_t)(u.pm * BM + wr * 64 + fr) * DM + col0;
;         u32x4 bx[2][4][2];
; #pragma unroll
;         for (int ai = 0; ai < 2; ++ai)
; #pragma unroll
;             for (int m = 0; m < 4; ++m)
; #pragma unroll
;                 for (int bj = 0; bj < 2; ++bj) bx[ai][m][bj] = *(const u32x4*)(rp0 + (size_t)(ai * HALF + m * 16) * DM + bj * HALF);
; template <class Epi, bool SEG>
; __device__ __forceinline__ void gemm_phase(LAS unsigned char* lds, const Gemm g, const int G, const int cidx, const Epi& E) {
;     ...
;             PG8_WAIT_V(8); PG8_WAIT_L(0); PG8_BAR; PG8_MMA(1, 0, At, B0); PG8_MMA(1, 1, At, B1); PG8_BAR; PG8_SCHED;
;             PG8_LDB(B0, 1, 0); PG8_LDB(B1, 1, 1); PG8_SCHED; PG8_LDA(At, 1, 0); PG8_STAGE(PG8_SA(0, 1), a2 + hstepA, voffA);
;             PG8_WAIT_V(8); PG8_WAIT_L(0); PG8_BAR; PG8_MMA(0, 0, At, B0); PG8_MMA(0, 1, At, B1); PG8_BAR; PG8_SCHED;
;             PG8_LDA(At, 1, 1); PG8_STAGE(PG8_SB(1, 0), b3, voffB); PG8_STAGE(PG8_SB(1, 1), b3 + hstepB, voffB); PG8_STAGE(PG8_SA(1, 0), a3, voffA);
;             PG8_WAIT_V(8); PG8_WAIT_L(0); PG8_BAR; PG8_MMA(1, 0, At, B0); PG8_MMA(1, 1, At, B1); PG8_BAR; PG8_SCHED;
;         }
;         if (wr == 0) PG8_BAR;
	s_setprio 0
	s_add_i32 s18, s55, s9
	v_lshl_add_u64 v[208:209], v[208:209], 0, s[28:29]
	s_mov_b32 m0, s18
	ds_read_b128 v[166:169], v244 offset:49152
	ds_read_b128 v[170:173], v244 offset:50176
	ds_read_b128 v[174:177], v244 offset:51200
	ds_read_b128 v[178:181], v244 offset:52224
	ds_read_b128 v[182:185], v244 offset:53248
	ds_read_b128 v[186:189], v244 offset:54272
	ds_read_b128 v[190:193], v244 offset:55296
	ds_read_b128 v[212:215], v244 offset:56320
	global_load_lds_dwordx4 v[208:209], off
	s_add_i32 m0, s18, 0x2000
	s_add_u32 s18, s22, 0xb0080
	v_lshl_add_u64 v[208:209], v[216:217], 0, s[28:29]
	s_addc_u32 s19, s23, 0
	s_add_i32 s22, s56, s9
	global_load_lds_dwordx4 v[208:209], off
	v_lshl_add_u64 v[208:209], s[18:19], 0, v[0:1]
	s_mov_b32 m0, s22
	s_nop 0
	global_load_lds_dwordx4 v[208:209], off
	v_lshl_add_u64 v[208:209], s[18:19], 0, v[14:15]
	s_add_i32 m0, s22, 0x2000
	s_nop 0
	global_load_lds_dwordx4 v[208:209], off
	v_lshl_add_u64 v[208:209], v[218:219], 0, s[28:29]
	s_mov_b32 m0, s39
	s_nop 0
	global_load_lds_dwordx4 v[208:209], off
	v_lshl_add_u64 v[208:209], v[220:221], 0, s[28:29]
	s_mov_b32 m0, s48
	s_nop 0
	global_load_lds_dwordx4 v[208:209], off
	s_waitcnt vmcnt(8)
	s_waitcnt lgkmcnt(0)
	s_setprio 1
	s_barrier
	v_mfma_f32_16x16x32_bf16 v[66:69], v[130:133], v[166:169], v[66:69]
	v_mfma_f32_16x16x32_bf16 v[62:65], v[142:145], v[166:169], v[62:65]
	v_mfma_f32_16x16x32_bf16 v[50:53], v[130:133], v[174:177], v[50:53]
	v_mfma_f32_16x16x32_bf16 v[46:49], v[142:145], v[174:177], v[46:49]
	v_mfma_f32_16x16x32_bf16 v[34:37], v[130:133], v[182:185], v[34:37]
	v_mfma_f32_16x16x32_bf16 v[30:33], v[142:145], v[182:185], v[30:33]
	v_mfma_f32_16x16x32_bf16 v[18:21], v[130:133], v[190:193], v[18:21]
	v_mfma_f32_16x16x32_bf16 v[10:13], v[142:145], v[190:193], v[10:13]
	v_mfma_f32_16x16x32_bf16 v[66:69], v[138:141], v[170:173], v[66:69]
	v_mfma_f32_16x16x32_bf16 v[62:65], v[146:149], v[170:173], v[62:65]
	v_mfma_f32_16x16x32_bf16 v[50:53], v[138:141], v[178:181], v[50:53]
	v_mfma_f32_16x16x32_bf16 v[46:49], v[146:149], v[178:181], v[46:49]
	v_mfma_f32_16x16x32_bf16 v[34:37], v[138:141], v[186:189], v[34:37]
	v_mfma_f32_16x16x32_bf16 v[30:33], v[146:149], v[186:189], v[30:33]
	v_mfma_f32_16x16x32_bf16 v[18:21], v[138:141], v[212:215], v[18:21]
	v_mfma_f32_16x16x32_bf16 v[10:13], v[146:149], v[212:215], v[10:13]
	s_setprio 0
	s_setprio 1
	v_mfma_f32_16x16x32_bf16 v[58:61], v[150:153], v[166:169], v[58:61]
	v_mfma_f32_16x16x32_bf16 v[54:57], v[158:161], v[166:169], v[54:57]
	v_mfma_f32_16x16x32_bf16 v[42:45], v[150:153], v[174:177], v[42:45]
	v_mfma_f32_16x16x32_bf16 v[38:41], v[158:161], v[174:177], v[38:41]
	v_mfma_f32_16x16x32_bf16 v[26:29], v[150:153], v[182:185], v[26:29]
	v_mfma_f32_16x16x32_bf16 v[22:25], v[158:161], v[182:185], v[22:25]
	v_mfma_f32_16x16x32_bf16 v[6:9], v[150:153], v[190:193], v[6:9]
	v_mfma_f32_16x16x32_bf16 v[2:5], v[158:161], v[190:193], v[2:5]
	v_mfma_f32_16x16x32_bf16 v[58:61], v[154:157], v[170:173], v[58:61]
	v_mfma_f32_16x16x32_bf16 v[54:57], v[162:165], v[170:173], v[54:57]
	v_mfma_f32_16x16x32_bf16 v[42:45], v[154:157], v[178:181], v[42:45]
	v_mfma_f32_16x16x32_bf16 v[38:41], v[162:165], v[178:181], v[38:41]
	v_mfma_f32_16x16x32_bf16 v[26:29], v[154:157], v[186:189], v[26:29]
	v_mfma_f32_16x16x32_bf16 v[22:25], v[162:165], v[186:189], v[22:25]
	v_mfma_f32_16x16x32_bf16 v[6:9], v[154:157], v[212:215], v[6:9]
	v_mfma_f32_16x16x32_bf16 v[2:5], v[162:165], v[212:215], v[2:5]
	s_barrier
	s_setprio 0
	s_add_i32 s54, s54, 2
	s_add_u32 s52, s52, 0x100
	s_addc_u32 s53, s53, 0
	s_cmp_gt_u32 s54, 41
	s_mov_b64 s[18:19], s[20:21]
	s_cbranch_scc0 .LBB0_958
	s_lshl_b32 s15, s15, 8
	v_add_u32_e32 v132, s15, v17
	v_ashrrev_i32_e32 v133, 31, v132
	v_lshl_or_b32 v130, s14, 8, v229
	v_lshlrev_b64 v[132:133], 11, v[132:133]
	v_lshl_add_u64 v[132:133], s[82:83], 0, v[132:133]
	v_ashrrev_i32_e32 v131, 31, v130
	v_lshl_add_u64 v[226:227], v[130:131], 1, v[132:133]
	global_load_dwordx4 v[248:251], v[226:227], off
	global_load_dwordx4 v[190:193], v[226:227], off offset:256
	v_add_co_u32_e32 v224, vcc, 0x8000, v226
	s_mov_b32 s18, 0x18000
	s_nop 0
	v_addc_co_u32_e32 v225, vcc, 0, v227, vcc
	global_load_dwordx4 v[186:189], v[224:225], off
	global_load_dwordx4 v[182:185], v[224:225], off offset:256
	s_nop 4
	s_and_b64 vcc, exec, s[12:13]
	s_cbranch_vccz .LBB0_961
	s_barrier
; __device__ __forceinline__ unsigned cvtpk(float lo, float hi) { f32x2_t v = {lo, hi}; bf16x2_t b = __builtin_convertvector(v, bf16x2_t); return __builtin_bit_cast(unsigned, b); }
; __device__ __forceinline__ float bflo(unsigned w) { return __uint_as_float(w << 16); }
; __device__ __forceinline__ float bfhi(unsigned w) { return __uint_as_float(w & 0xffff0000u); }
;     __device__ __forceinline__ void operator()(f32x4 (&acc)[2][2][4][2], const Unit& u, int wr, int wc, int fr, int fq) const {
;         const int col0 = u.pn * BM + wc * 32 + 8 * fq;
;         bf16_t* rp0 = x + (size_t)(u.pm * BM + wr * 64 + fr) * DM + col0;
;         u32x4 bx[2][4][2];
; #pragma unroll
;         for (int ai = 0; ai < 2; ++ai)
; #pragma unroll
;             for (int m = 0; m < 4; ++m)
; #pragma unroll
;                 for (int bj = 0; bj < 2; ++bj) bx[ai][m][bj] = *(const u32x4*)(rp0 + (size_t)(ai * HALF + m * 16) * DM + bj * HALF);
;         float sqv[8];
; #pragma unroll
;         for (int ai = 0; ai < 2; ++ai)
; #pragma unroll
;             for (int m = 0; m < 4; ++m) { bf16_t* rp = rp0 + (size_t)(ai * HALF + m * 16) * DM; float sq = 0.f;
; #pragma unroll
;                 for (int bj = 0; bj < 2; ++bj) { const u32x4 b = bx[ai][m][bj];
;                     const f32x4 v0 = acc[ai][bj][m][0] + (f32x4){bflo(b.x), bfhi(b.x), bflo(b.y), bfhi(b.y)}, v1 = acc[ai][bj][m][1] + (f32x4){bflo(b.z), bfhi(b.z), bflo(b.w), bfhi(b.w)};
;                     sq += ((v0[0] * v0[0] + v0[1] * v0[1]) + (v0[2] * v0[2] + v0[3] * v0[3])) + ((v1[0] * v1[0] + v1[1] * v1[1]) + (v1[2] * v1[2] + v1[3] * v1[3]));
;                     u32x4 w; w.x = cvtpk(v0[0], v0[1]); w.y = cvtpk(v0[2], v0[3]); w.z = cvtpk(v1[0], v1[1]); w.w = cvtpk(v1[2], v1[3]);
;                     *(u32x4*)(rp + bj * HALF) = w; }
;                 sqv[ai * 4 + m] = sq; }
.LBB0_961:
	v_add_co_u32_e32 v222, vcc, s79, v226
	s_waitcnt vmcnt(0)
	v_lshlrev_b32_e32 v208, 16, v248
	v_addc_co_u32_e32 v223, vcc, 0, v227, vcc
	global_load_dwordx4 v[178:181], v[222:223], off
	global_load_dwordx4 v[174:177], v[222:223], off offset:256
	v_add_co_u32_e32 v220, vcc, s18, v226
	s_mov_b32 s18, 0x48000
	s_nop 0
	v_addc_co_u32_e32 v221, vcc, 0, v227, vcc
	global_load_dwordx4 v[170:173], v[220:221], off
	global_load_dwordx4 v[166:169], v[220:221], off offset:256
	v_add_co_u32_e32 v218, vcc, s68, v226
	v_and_b32_e32 v209, 0xffff0000, v248
	s_nop 0
	v_addc_co_u32_e32 v219, vcc, 0, v227, vcc
	global_load_dwordx4 v[162:165], v[218:219], off
	global_load_dwordx4 v[158:161], v[218:219], off offset:256
	v_add_co_u32_e32 v216, vcc, s18, v226
	v_lshlrev_b32_e32 v248, 16, v249
	s_nop 0
	v_addc_co_u32_e32 v217, vcc, 0, v227, vcc
	global_load_dwordx4 v[154:157], v[216:217], off
	global_load_dwordx4 v[150:153], v[216:217], off offset:256
	v_and_b32_e32 v249, 0xffff0000, v249
	v_pk_add_f32 v[136:137], v[136:137], v[248:249]
	v_pk_add_f32 v[134:135], v[134:135], v[208:209]
	v_lshlrev_b32_e32 v208, 16, v250
	v_and_b32_e32 v209, 0xffff0000, v250
	v_lshlrev_b32_e32 v248, 16, v251
	v_and_b32_e32 v249, 0xffff0000, v251
	v_pk_add_f32 v[248:249], v[128:129], v[248:249]
	v_pk_add_f32 v[128:129], v[126:127], v[208:209]
	v_mul_f32_e32 v126, v135, v135
	v_mul_f32_e32 v127, v137, v137
	s_mov_b32 s18, 0x50000
	v_fmac_f32_e32 v126, v134, v134
	v_fmac_f32_e32 v127, v136, v136
	v_add_co_u32_e32 v214, vcc, s18, v226
	v_add_f32_e32 v126, v126, v127
	v_mul_f32_e32 v127, v129, v129
	v_mul_f32_e32 v208, v249, v249
	v_addc_co_u32_e32 v215, vcc, 0, v227, vcc
	s_mov_b32 s18, 0x58000
	v_fmac_f32_e32 v127, v128, v128
	v_fmac_f32_e32 v208, v248, v248
	v_add_co_u32_e32 v212, vcc, s18, v226
	v_add_f32_e32 v127, v127, v208
	s_nop 0
	v_addc_co_u32_e32 v213, vcc, 0, v227, vcc
	v_add_f32_e32 v208, v126, v127
	v_cvt_pk_bf16_f32 v126, v134, v135
	v_cvt_pk_bf16_f32 v127, v136, v137
	v_cvt_pk_bf16_f32 v128, v128, v129
	v_cvt_pk_bf16_f32 v129, v248, v249
	global_load_dwordx4 v[146:149], v[214:215], off
	global_load_dwordx4 v[142:145], v[214:215], off offset:256
	global_load_dwordx4 v[138:141], v[212:213], off
	global_load_dwordx4 v[130:133], v[212:213], off offset:256
	v_cmp_lt_i32_e32 vcc, v237, v232
	global_store_dwordx4 v[226:227], v[126:129], off
	s_nop 1
	v_lshlrev_b32_e32 v126, 16, v190
	v_and_b32_e32 v127, 0xffff0000, v190
	v_lshlrev_b32_e32 v128, 16, v191
	v_and_b32_e32 v129, 0xffff0000, v191
	v_pk_add_f32 v[124:125], v[124:125], v[128:129]
	v_pk_add_f32 v[122:123], v[122:123], v[126:127]
	v_lshlrev_b32_e32 v126, 16, v192
	v_and_b32_e32 v127, 0xffff0000, v192
	v_lshlrev_b32_e32 v128, 16, v193
	v_and_b32_e32 v129, 0xffff0000, v193
	v_pk_add_f32 v[126:127], v[118:119], v[126:127]
	v_mul_f32_e32 v118, v123, v123
	v_mul_f32_e32 v119, v125, v125
	v_pk_add_f32 v[128:129], v[120:121], v[128:129]
	v_fmac_f32_e32 v118, v122, v122
	v_fmac_f32_e32 v119, v124, v124
	v_add_f32_e32 v118, v118, v119
	v_mul_f32_e32 v119, v127, v127
	v_mul_f32_e32 v120, v129, v129
	v_fmac_f32_e32 v119, v126, v126
	v_fmac_f32_e32 v120, v128, v128
	v_add_f32_e32 v119, v119, v120
	v_cvt_pk_bf16_f32 v120, v122, v123
	v_cvt_pk_bf16_f32 v121, v124, v125
	v_cvt_pk_bf16_f32 v122, v126, v127
	v_cvt_pk_bf16_f32 v123, v128, v129
	global_store_dwordx4 v[226:227], v[120:123], off offset:256
	v_add_f32_e32 v118, v118, v119
	v_add_f32_e32 v118, v208, v118
	v_lshlrev_b32_e32 v120, 16, v186
	v_and_b32_e32 v121, 0xffff0000, v186
	v_lshlrev_b32_e32 v122, 16, v187
	v_and_b32_e32 v123, 0xffff0000, v187
	v_pk_add_f32 v[116:117], v[116:117], v[122:123]
	v_pk_add_f32 v[114:115], v[114:115], v[120:121]
	v_lshlrev_b32_e32 v120, 16, v188
	v_and_b32_e32 v121, 0xffff0000, v188
	v_lshlrev_b32_e32 v122, 16, v189
	v_and_b32_e32 v123, 0xffff0000, v189
	v_pk_add_f32 v[122:123], v[112:113], v[122:123]
	v_pk_add_f32 v[112:113], v[110:111], v[120:121]
	v_mul_f32_e32 v110, v115, v115
	v_mul_f32_e32 v111, v117, v117
	v_fmac_f32_e32 v110, v114, v114
	v_fmac_f32_e32 v111, v116, v116
	v_add_f32_e32 v110, v110, v111
	v_mul_f32_e32 v111, v113, v113
	v_mul_f32_e32 v119, v123, v123
	v_fmac_f32_e32 v111, v112, v112
	v_fmac_f32_e32 v119, v122, v122
	v_add_f32_e32 v111, v111, v119
	v_add_f32_e32 v119, v110, v111
	v_cvt_pk_bf16_f32 v110, v114, v115
	v_cvt_pk_bf16_f32 v111, v116, v117
	v_cvt_pk_bf16_f32 v112, v112, v113
	v_cvt_pk_bf16_f32 v113, v122, v123
	global_store_dwordx4 v[224:225], v[110:113], off
	s_nop 1
	v_lshlrev_b32_e32 v110, 16, v182
	v_and_b32_e32 v111, 0xffff0000, v182
	v_lshlrev_b32_e32 v112, 16, v183
	v_and_b32_e32 v113, 0xffff0000, v183
	v_pk_add_f32 v[108:109], v[108:109], v[112:113]
	v_pk_add_f32 v[106:107], v[106:107], v[110:111]
	v_lshlrev_b32_e32 v110, 16, v184
	v_and_b32_e32 v111, 0xffff0000, v184
	v_lshlrev_b32_e32 v112, 16, v185
	v_and_b32_e32 v113, 0xffff0000, v185
	v_pk_add_f32 v[110:111], v[102:103], v[110:111]
	v_mul_f32_e32 v102, v107, v107
	v_mul_f32_e32 v103, v109, v109
	v_pk_add_f32 v[112:113], v[104:105], v[112:113]
	v_fmac_f32_e32 v102, v106, v106
	v_fmac_f32_e32 v103, v108, v108
	v_add_f32_e32 v102, v102, v103
	v_mul_f32_e32 v103, v111, v111
	v_mul_f32_e32 v104, v113, v113
	v_fmac_f32_e32 v103, v110, v110
	v_fmac_f32_e32 v104, v112, v112
	v_add_f32_e32 v103, v103, v104
	v_cvt_pk_bf16_f32 v104, v106, v107
	v_cvt_pk_bf16_f32 v105, v108, v109
	v_cvt_pk_bf16_f32 v106, v110, v111
	v_cvt_pk_bf16_f32 v107, v112, v113
	global_store_dwordx4 v[224:225], v[104:107], off offset:256
	v_add_f32_e32 v102, v102, v103
	v_add_f32_e32 v102, v119, v102
	s_waitcnt vmcnt(15)
; __device__ __forceinline__ unsigned cvtpk(float lo, float hi) { f32x2_t v = {lo, hi}; bf16x2_t b = __builtin_convertvector(v, bf16x2_t); return __builtin_bit_cast(unsigned, b); }
; __device__ __forceinline__ float bflo(unsigned w) { return __uint_as_float(w << 16); }
; __device__ __forceinline__ float bfhi(unsigned w) { return __uint_as_float(w & 0xffff0000u); }
;     __device__ __forceinline__ void operator()(f32x4 (&acc)[2][2][4][2], const Unit& u, int wr, int wc, int fr, int fq) const {
;     ...
;             for (int m = 0; m < 4; ++m) { bf16_t* rp = rp0 + (size_t)(ai * HALF + m * 16) * DM; float sq = 0.f;
; #pragma unroll
;                 for (int bj = 0; bj < 2; ++bj) { const u32x4 b = bx[ai][m][bj];
;                     const f32x4 v0 = acc[ai][bj][m][0] + (f32x4){bflo(b.x), bfhi(b.x), bflo(b.y), bfhi(b.y)}, v1 = acc[ai][bj][m][1] + (f32x4){bflo(b.z), bfhi(b.z), bflo(b.w), bfhi(b.w)};
;                     sq += ((v0[0] * v0[0] + v0[1] * v0[1]) + (v0[2] * v0[2] + v0[3] * v0[3])) + ((v1[0] * v1[0] + v1[1] * v1[1]) + (v1[2] * v1[2] + v1[3] * v1[3]));
;                     u32x4 w; w.x = cvtpk(v0[0], v0[1]); w.y = cvtpk(v0[2], v0[3]); w.z = cvtpk(v1[0], v1[1]); w.w = cvtpk(v1[2], v1[3]);
;                     *(u32x4*)(rp + bj * HALF) = w; }
;                 sqv[ai * 4 + m] = sq; }
	v_lshlrev_b32_e32 v104, 16, v178
	v_and_b32_e32 v105, 0xffff0000, v178
	v_lshlrev_b32_e32 v106, 16, v179
	v_and_b32_e32 v107, 0xffff0000, v179
	v_pk_add_f32 v[100:101], v[100:101], v[106:107]
	v_pk_add_f32 v[98:99], v[98:99], v[104:105]
	v_lshlrev_b32_e32 v104, 16, v180
	v_and_b32_e32 v105, 0xffff0000, v180
	v_lshlrev_b32_e32 v106, 16, v181
	v_and_b32_e32 v107, 0xffff0000, v181
	v_pk_add_f32 v[106:107], v[96:97], v[106:107]
	v_pk_add_f32 v[96:97], v[94:95], v[104:105]
	v_mul_f32_e32 v94, v99, v99
	v_mul_f32_e32 v95, v101, v101
	v_fmac_f32_e32 v94, v98, v98
	v_fmac_f32_e32 v95, v100, v100
	v_add_f32_e32 v94, v94, v95
	v_mul_f32_e32 v95, v97, v97
	v_mul_f32_e32 v103, v107, v107
	v_fmac_f32_e32 v95, v96, v96
	v_fmac_f32_e32 v103, v106, v106
	v_add_f32_e32 v95, v95, v103
	v_add_f32_e32 v103, v94, v95
	v_cvt_pk_bf16_f32 v94, v98, v99
	v_cvt_pk_bf16_f32 v95, v100, v101
	v_cvt_pk_bf16_f32 v96, v96, v97
	v_cvt_pk_bf16_f32 v97, v106, v107
	global_store_dwordx4 v[222:223], v[94:97], off
	s_waitcnt vmcnt(15)
	s_nop 0
	v_lshlrev_b32_e32 v94, 16, v174
	v_and_b32_e32 v95, 0xffff0000, v174
	v_lshlrev_b32_e32 v96, 16, v175
	v_and_b32_e32 v97, 0xffff0000, v175
	v_pk_add_f32 v[92:93], v[92:93], v[96:97]
	v_pk_add_f32 v[90:91], v[90:91], v[94:95]
	v_lshlrev_b32_e32 v94, 16, v176
	v_and_b32_e32 v95, 0xffff0000, v176
	v_lshlrev_b32_e32 v96, 16, v177
	v_and_b32_e32 v97, 0xffff0000, v177
	v_pk_add_f32 v[94:95], v[86:87], v[94:95]
	v_mul_f32_e32 v86, v91, v91
	v_mul_f32_e32 v87, v93, v93
	v_pk_add_f32 v[96:97], v[88:89], v[96:97]
	v_fmac_f32_e32 v86, v90, v90
	v_fmac_f32_e32 v87, v92, v92
	v_add_f32_e32 v86, v86, v87
	v_mul_f32_e32 v87, v95, v95
	v_mul_f32_e32 v88, v97, v97
	v_fmac_f32_e32 v87, v94, v94
	v_fmac_f32_e32 v88, v96, v96
	v_add_f32_e32 v87, v87, v88
	v_cvt_pk_bf16_f32 v88, v90, v91
	v_cvt_pk_bf16_f32 v89, v92, v93
	v_cvt_pk_bf16_f32 v90, v94, v95
	v_cvt_pk_bf16_f32 v91, v96, v97
	global_store_dwordx4 v[222:223], v[88:91], off offset:256
	v_add_f32_e32 v86, v86, v87
	v_add_f32_e32 v86, v103, v86
	s_waitcnt vmcnt(15)
	v_lshlrev_b32_e32 v88, 16, v170
	v_and_b32_e32 v89, 0xffff0000, v170
	v_lshlrev_b32_e32 v90, 16, v171
	v_and_b32_e32 v91, 0xffff0000, v171
	v_pk_add_f32 v[84:85], v[84:85], v[90:91]
	v_pk_add_f32 v[82:83], v[82:83], v[88:89]
	v_lshlrev_b32_e32 v88, 16, v172
	v_and_b32_e32 v89, 0xffff0000, v172
	v_lshlrev_b32_e32 v90, 16, v173
	v_and_b32_e32 v91, 0xffff0000, v173
	v_pk_add_f32 v[90:91], v[80:81], v[90:91]
	v_pk_add_f32 v[80:81], v[78:79], v[88:89]
	v_mul_f32_e32 v78, v83, v83
	v_mul_f32_e32 v79, v85, v85
	v_fmac_f32_e32 v78, v82, v82
	v_fmac_f32_e32 v79, v84, v84
	v_add_f32_e32 v78, v78, v79
	v_mul_f32_e32 v79, v81, v81
	v_mul_f32_e32 v87, v91, v91
	v_fmac_f32_e32 v79, v80, v80
	v_fmac_f32_e32 v87, v90, v90
	v_add_f32_e32 v79, v79, v87
	v_add_f32_e32 v87, v78, v79
	v_cvt_pk_bf16_f32 v78, v82, v83
	v_cvt_pk_bf16_f32 v79, v84, v85
	v_cvt_pk_bf16_f32 v80, v80, v81
	v_cvt_pk_bf16_f32 v81, v90, v91
	global_store_dwordx4 v[220:221], v[78:81], off
	s_waitcnt vmcnt(15)
	s_nop 0
	v_lshlrev_b32_e32 v78, 16, v166
	v_and_b32_e32 v79, 0xffff0000, v166
	v_lshlrev_b32_e32 v80, 16, v167
	v_and_b32_e32 v81, 0xffff0000, v167
	v_pk_add_f32 v[76:77], v[76:77], v[80:81]
	v_pk_add_f32 v[74:75], v[74:75], v[78:79]
	v_lshlrev_b32_e32 v78, 16, v168
	v_and_b32_e32 v79, 0xffff0000, v168
	v_lshlrev_b32_e32 v80, 16, v169
	v_and_b32_e32 v81, 0xffff0000, v169
	v_pk_add_f32 v[80:81], v[72:73], v[80:81]
	v_pk_add_f32 v[72:73], v[70:71], v[78:79]
	v_mul_f32_e32 v70, v75, v75
	v_mul_f32_e32 v71, v77, v77
	v_fmac_f32_e32 v70, v74, v74
	v_fmac_f32_e32 v71, v76, v76
	v_add_f32_e32 v70, v70, v71
	v_mul_f32_e32 v71, v73, v73
	v_mul_f32_e32 v78, v81, v81
	v_fmac_f32_e32 v71, v72, v72
	v_fmac_f32_e32 v78, v80, v80
	v_add_f32_e32 v71, v71, v78
	v_add_f32_e32 v70, v70, v71
	v_add_f32_e32 v78, v87, v70
	v_cvt_pk_bf16_f32 v70, v74, v75
	v_cvt_pk_bf16_f32 v71, v76, v77
	v_cvt_pk_bf16_f32 v72, v72, v73
	v_cvt_pk_bf16_f32 v73, v80, v81
	global_store_dwordx4 v[220:221], v[70:73], off offset:256
	s_waitcnt vmcnt(15)
	s_nop 0
	v_lshlrev_b32_e32 v70, 16, v162
	v_and_b32_e32 v71, 0xffff0000, v162
	v_lshlrev_b32_e32 v72, 16, v163
	v_and_b32_e32 v73, 0xffff0000, v163
	v_pk_add_f32 v[68:69], v[68:69], v[72:73]
	v_pk_add_f32 v[66:67], v[66:67], v[70:71]
	v_lshlrev_b32_e32 v70, 16, v164
	v_and_b32_e32 v71, 0xffff0000, v164
	v_lshlrev_b32_e32 v72, 16, v165
	v_and_b32_e32 v73, 0xffff0000, v165
	v_pk_add_f32 v[72:73], v[64:65], v[72:73]
	v_pk_add_f32 v[64:65], v[62:63], v[70:71]
	v_mul_f32_e32 v62, v67, v67
	v_mul_f32_e32 v63, v69, v69
	v_fmac_f32_e32 v62, v66, v66
	v_fmac_f32_e32 v63, v68, v68
	v_add_f32_e32 v62, v62, v63
	v_mul_f32_e32 v63, v65, v65
	v_mul_f32_e32 v70, v73, v73
	v_fmac_f32_e32 v63, v64, v64
	v_fmac_f32_e32 v70, v72, v72
	v_add_f32_e32 v63, v63, v70
	v_add_f32_e32 v70, v62, v63
	v_cvt_pk_bf16_f32 v62, v66, v67
	v_cvt_pk_bf16_f32 v63, v68, v69
	v_cvt_pk_bf16_f32 v64, v64, v65
	v_cvt_pk_bf16_f32 v65, v72, v73
	global_store_dwordx4 v[218:219], v[62:65], off
	s_waitcnt vmcnt(15)
	s_nop 0
	v_lshlrev_b32_e32 v62, 16, v158
	v_and_b32_e32 v63, 0xffff0000, v158
	v_lshlrev_b32_e32 v64, 16, v159
	v_and_b32_e32 v65, 0xffff0000, v159
	v_pk_add_f32 v[60:61], v[60:61], v[64:65]
	v_pk_add_f32 v[58:59], v[58:59], v[62:63]
	v_lshlrev_b32_e32 v62, 16, v160
	v_and_b32_e32 v63, 0xffff0000, v160
	v_lshlrev_b32_e32 v64, 16, v161
	v_and_b32_e32 v65, 0xffff0000, v161
	v_pk_add_f32 v[64:65], v[56:57], v[64:65]
	v_pk_add_f32 v[56:57], v[54:55], v[62:63]
	v_mul_f32_e32 v54, v59, v59
	v_mul_f32_e32 v55, v61, v61
	v_fmac_f32_e32 v54, v58, v58
	v_fmac_f32_e32 v55, v60, v60
	v_add_f32_e32 v54, v54, v55
	v_mul_f32_e32 v55, v57, v57
	v_mul_f32_e32 v62, v65, v65
	v_fmac_f32_e32 v55, v56, v56
	v_fmac_f32_e32 v62, v64, v64
	v_add_f32_e32 v55, v55, v62
	v_add_f32_e32 v54, v54, v55
	v_add_f32_e32 v62, v70, v54
	v_cvt_pk_bf16_f32 v54, v58, v59
	v_cvt_pk_bf16_f32 v55, v60, v61
	v_cvt_pk_bf16_f32 v56, v56, v57
	v_cvt_pk_bf16_f32 v57, v64, v65
	global_store_dwordx4 v[218:219], v[54:57], off offset:256
	s_waitcnt vmcnt(15)
; __device__ __forceinline__ unsigned cvtpk(float lo, float hi) { f32x2_t v = {lo, hi}; bf16x2_t b = __builtin_convertvector(v, bf16x2_t); return __builtin_bit_cast(unsigned, b); }
; __device__ __forceinline__ float bflo(unsigned w) { return __uint_as_float(w << 16); }
; __device__ __forceinline__ float bfhi(unsigned w) { return __uint_as_float(w & 0xffff0000u); }
;     __device__ __forceinline__ void operator()(f32x4 (&acc)[2][2][4][2], const Unit& u, int wr, int wc, int fr, int fq) const {
;     ...
;             for (int m = 0; m < 4; ++m) { bf16_t* rp = rp0 + (size_t)(ai * HALF + m * 16) * DM; float sq = 0.f;
; #pragma unroll
;                 for (int bj = 0; bj < 2; ++bj) { const u32x4 b = bx[ai][m][bj];
;                     const f32x4 v0 = acc[ai][bj][m][0] + (f32x4){bflo(b.x), bfhi(b.x), bflo(b.y), bfhi(b.y)}, v1 = acc[ai][bj][m][1] + (f32x4){bflo(b.z), bfhi(b.z), bflo(b.w), bfhi(b.w)};
;                     sq += ((v0[0] * v0[0] + v0[1] * v0[1]) + (v0[2] * v0[2] + v0[3] * v0[3])) + ((v1[0] * v1[0] + v1[1] * v1[1]) + (v1[2] * v1[2] + v1[3] * v1[3]));
;                     u32x4 w; w.x = cvtpk(v0[0], v0[1]); w.y = cvtpk(v0[2], v0[3]); w.z = cvtpk(v1[0], v1[1]); w.w = cvtpk(v1[2], v1[3]);
;                     *(u32x4*)(rp + bj * HALF) = w; }
;                 sqv[ai * 4 + m] = sq; }
	s_nop 0
	v_lshlrev_b32_e32 v54, 16, v154
	v_and_b32_e32 v55, 0xffff0000, v154
	v_lshlrev_b32_e32 v56, 16, v155
	v_and_b32_e32 v57, 0xffff0000, v155
	v_pk_add_f32 v[52:53], v[52:53], v[56:57]
	v_pk_add_f32 v[50:51], v[50:51], v[54:55]
	v_lshlrev_b32_e32 v54, 16, v156
	v_and_b32_e32 v55, 0xffff0000, v156
	v_lshlrev_b32_e32 v56, 16, v157
	v_and_b32_e32 v57, 0xffff0000, v157
	v_pk_add_f32 v[56:57], v[48:49], v[56:57]
	v_pk_add_f32 v[48:49], v[46:47], v[54:55]
	v_mul_f32_e32 v46, v51, v51
	v_mul_f32_e32 v47, v53, v53
	v_fmac_f32_e32 v46, v50, v50
	v_fmac_f32_e32 v47, v52, v52
	v_add_f32_e32 v46, v46, v47
	v_mul_f32_e32 v47, v49, v49
	v_mul_f32_e32 v54, v57, v57
	v_fmac_f32_e32 v47, v48, v48
	v_fmac_f32_e32 v54, v56, v56
	v_add_f32_e32 v47, v47, v54
	v_add_f32_e32 v54, v46, v47
	v_cvt_pk_bf16_f32 v46, v50, v51
	v_cvt_pk_bf16_f32 v47, v52, v53
	v_cvt_pk_bf16_f32 v48, v48, v49
	v_cvt_pk_bf16_f32 v49, v56, v57
	global_store_dwordx4 v[216:217], v[46:49], off
	s_waitcnt vmcnt(15)
	s_nop 0
	v_lshlrev_b32_e32 v46, 16, v150
	v_and_b32_e32 v47, 0xffff0000, v150
	v_lshlrev_b32_e32 v48, 16, v151
	v_and_b32_e32 v49, 0xffff0000, v151
	v_pk_add_f32 v[44:45], v[44:45], v[48:49]
	v_pk_add_f32 v[42:43], v[42:43], v[46:47]
	v_lshlrev_b32_e32 v46, 16, v152
	v_and_b32_e32 v47, 0xffff0000, v152
	v_lshlrev_b32_e32 v48, 16, v153
	v_and_b32_e32 v49, 0xffff0000, v153
	v_pk_add_f32 v[48:49], v[40:41], v[48:49]
	v_pk_add_f32 v[40:41], v[38:39], v[46:47]
	v_mul_f32_e32 v38, v43, v43
	v_mul_f32_e32 v39, v45, v45
	v_fmac_f32_e32 v38, v42, v42
	v_fmac_f32_e32 v39, v44, v44
	v_add_f32_e32 v38, v38, v39
	v_mul_f32_e32 v39, v41, v41
	v_mul_f32_e32 v46, v49, v49
	v_fmac_f32_e32 v39, v40, v40
	v_fmac_f32_e32 v46, v48, v48
	v_add_f32_e32 v39, v39, v46
	v_add_f32_e32 v38, v38, v39
	v_add_f32_e32 v46, v54, v38
	v_cvt_pk_bf16_f32 v38, v42, v43
	v_cvt_pk_bf16_f32 v39, v44, v45
	v_cvt_pk_bf16_f32 v40, v40, v41
	v_cvt_pk_bf16_f32 v41, v48, v49
	global_store_dwordx4 v[216:217], v[38:41], off offset:256
	s_waitcnt vmcnt(15)
	s_nop 0
	v_lshlrev_b32_e32 v38, 16, v146
	v_and_b32_e32 v39, 0xffff0000, v146
	v_lshlrev_b32_e32 v40, 16, v147
	v_and_b32_e32 v41, 0xffff0000, v147
	v_pk_add_f32 v[36:37], v[36:37], v[40:41]
	v_pk_add_f32 v[34:35], v[34:35], v[38:39]
	v_lshlrev_b32_e32 v38, 16, v148
	v_and_b32_e32 v39, 0xffff0000, v148
	v_lshlrev_b32_e32 v40, 16, v149
	v_and_b32_e32 v41, 0xffff0000, v149
	v_pk_add_f32 v[40:41], v[32:33], v[40:41]
	v_pk_add_f32 v[32:33], v[30:31], v[38:39]
	v_mul_f32_e32 v30, v35, v35
	v_mul_f32_e32 v31, v37, v37
	v_fmac_f32_e32 v30, v34, v34
	v_fmac_f32_e32 v31, v36, v36
	v_add_f32_e32 v30, v30, v31
	v_mul_f32_e32 v31, v33, v33
	v_mul_f32_e32 v38, v41, v41
	v_fmac_f32_e32 v31, v32, v32
	v_fmac_f32_e32 v38, v40, v40
	v_add_f32_e32 v31, v31, v38
	v_add_f32_e32 v38, v30, v31
	v_cvt_pk_bf16_f32 v30, v34, v35
	v_cvt_pk_bf16_f32 v31, v36, v37
	v_cvt_pk_bf16_f32 v32, v32, v33
	v_cvt_pk_bf16_f32 v33, v40, v41
	global_store_dwordx4 v[214:215], v[30:33], off
	s_waitcnt vmcnt(15)
	s_nop 0
	v_lshlrev_b32_e32 v30, 16, v142
	v_and_b32_e32 v31, 0xffff0000, v142
	v_lshlrev_b32_e32 v32, 16, v143
	v_and_b32_e32 v33, 0xffff0000, v143
	v_pk_add_f32 v[28:29], v[28:29], v[32:33]
	v_pk_add_f32 v[26:27], v[26:27], v[30:31]
	v_lshlrev_b32_e32 v30, 16, v144
	v_and_b32_e32 v31, 0xffff0000, v144
	v_lshlrev_b32_e32 v32, 16, v145
	v_and_b32_e32 v33, 0xffff0000, v145
	v_pk_add_f32 v[32:33], v[24:25], v[32:33]
	v_pk_add_f32 v[24:25], v[22:23], v[30:31]
	v_mul_f32_e32 v22, v27, v27
	v_mul_f32_e32 v23, v29, v29
	v_fmac_f32_e32 v22, v26, v26
	v_fmac_f32_e32 v23, v28, v28
	v_add_f32_e32 v22, v22, v23
	v_mul_f32_e32 v23, v25, v25
	v_mul_f32_e32 v30, v33, v33
	v_fmac_f32_e32 v23, v24, v24
	v_fmac_f32_e32 v30, v32, v32
	v_add_f32_e32 v23, v23, v30
	v_add_f32_e32 v22, v22, v23
	v_add_f32_e32 v30, v38, v22
	v_cvt_pk_bf16_f32 v22, v26, v27
	v_cvt_pk_bf16_f32 v23, v28, v29
	v_cvt_pk_bf16_f32 v24, v24, v25
	v_cvt_pk_bf16_f32 v25, v32, v33
	global_store_dwordx4 v[214:215], v[22:25], off offset:256
	s_waitcnt vmcnt(15)
; __device__ __forceinline__ unsigned cvtpk(float lo, float hi) { f32x2_t v = {lo, hi}; bf16x2_t b = __builtin_convertvector(v, bf16x2_t); return __builtin_bit_cast(unsigned, b); }
; __device__ __forceinline__ float bflo(unsigned w) { return __uint_as_float(w << 16); }
; __device__ __forceinline__ float bfhi(unsigned w) { return __uint_as_float(w & 0xffff0000u); }
;     __device__ __forceinline__ void operator()(f32x4 (&acc)[2][2][4][2], const Unit& u, int wr, int wc, int fr, int fq) const {
;     ...
;             for (int m = 0; m < 4; ++m) { bf16_t* rp = rp0 + (size_t)(ai * HALF + m * 16) * DM; float sq = 0.f;
; #pragma unroll
;                 for (int bj = 0; bj < 2; ++bj) { const u32x4 b = bx[ai][m][bj];
;                     const f32x4 v0 = acc[ai][bj][m][0] + (f32x4){bflo(b.x), bfhi(b.x), bflo(b.y), bfhi(b.y)}, v1 = acc[ai][bj][m][1] + (f32x4){bflo(b.z), bfhi(b.z), bflo(b.w), bfhi(b.w)};
;                     sq += ((v0[0] * v0[0] + v0[1] * v0[1]) + (v0[2] * v0[2] + v0[3] * v0[3])) + ((v1[0] * v1[0] + v1[1] * v1[1]) + (v1[2] * v1[2] + v1[3] * v1[3]));
;                     u32x4 w; w.x = cvtpk(v0[0], v0[1]); w.y = cvtpk(v0[2], v0[3]); w.z = cvtpk(v1[0], v1[1]); w.w = cvtpk(v1[2], v1[3]);
;                     *(u32x4*)(rp + bj * HALF) = w; }
;                 sqv[ai * 4 + m] = sq; }
; #pragma unroll
;         for (int i = 0; i < 8; ++i) { float s = sqv[i]; s += __shfl_xor(s, 16); s += __shfl_xor(s, 32); sqv[i] = s; }
;         if (fq == 0) {
; #pragma unroll
;             for (int i = 0; i < 8; ++i) red[((i >> 2) * HALF + wr * 64 + (i & 3) * 16 + fr) * 4 + wc] = sqv[i]; }
	s_nop 0
	v_lshlrev_b32_e32 v22, 16, v138
	v_and_b32_e32 v23, 0xffff0000, v138
	v_lshlrev_b32_e32 v24, 16, v139
	v_and_b32_e32 v25, 0xffff0000, v139
	v_pk_add_f32 v[20:21], v[20:21], v[24:25]
	v_pk_add_f32 v[18:19], v[18:19], v[22:23]
	v_lshlrev_b32_e32 v22, 16, v140
	v_and_b32_e32 v23, 0xffff0000, v140
	v_lshlrev_b32_e32 v24, 16, v141
	v_and_b32_e32 v25, 0xffff0000, v141
	v_pk_add_f32 v[24:25], v[12:13], v[24:25]
	v_pk_add_f32 v[12:13], v[10:11], v[22:23]
	v_mul_f32_e32 v10, v19, v19
	v_mul_f32_e32 v11, v21, v21
	v_fmac_f32_e32 v10, v18, v18
	v_fmac_f32_e32 v11, v20, v20
	v_add_f32_e32 v10, v10, v11
	v_mul_f32_e32 v11, v13, v13
	v_mul_f32_e32 v22, v25, v25
	v_fmac_f32_e32 v11, v12, v12
	v_fmac_f32_e32 v22, v24, v24
	v_add_f32_e32 v11, v11, v22
	v_add_f32_e32 v22, v10, v11
	v_cvt_pk_bf16_f32 v10, v18, v19
	v_cvt_pk_bf16_f32 v11, v20, v21
	v_cvt_pk_bf16_f32 v12, v12, v13
	v_cvt_pk_bf16_f32 v13, v24, v25
	global_store_dwordx4 v[212:213], v[10:13], off
	s_waitcnt vmcnt(15)
	s_nop 0
	v_lshlrev_b32_e32 v10, 16, v130
	v_and_b32_e32 v11, 0xffff0000, v130
	v_lshlrev_b32_e32 v12, 16, v131
	v_and_b32_e32 v13, 0xffff0000, v131
	v_pk_add_f32 v[8:9], v[8:9], v[12:13]
	v_pk_add_f32 v[6:7], v[6:7], v[10:11]
	v_lshlrev_b32_e32 v10, 16, v132
	v_and_b32_e32 v11, 0xffff0000, v132
	v_lshlrev_b32_e32 v12, 16, v133
	v_and_b32_e32 v13, 0xffff0000, v133
	v_pk_add_f32 v[12:13], v[4:5], v[12:13]
	v_pk_add_f32 v[4:5], v[2:3], v[10:11]
	v_mul_f32_e32 v2, v7, v7
	v_mul_f32_e32 v3, v9, v9
	v_fmac_f32_e32 v2, v6, v6
	v_fmac_f32_e32 v3, v8, v8
	v_add_f32_e32 v2, v2, v3
	v_mul_f32_e32 v3, v5, v5
	v_mul_f32_e32 v10, v13, v13
	v_fmac_f32_e32 v3, v4, v4
	v_fmac_f32_e32 v10, v12, v12
	v_add_f32_e32 v3, v3, v10
	v_add_f32_e32 v2, v2, v3
	v_add_f32_e32 v20, v22, v2
	v_cvt_pk_bf16_f32 v2, v6, v7
	v_cvt_pk_bf16_f32 v3, v8, v9
	v_cvt_pk_bf16_f32 v4, v4, v5
	v_cvt_pk_bf16_f32 v5, v12, v13
	global_store_dwordx4 v[212:213], v[2:5], off offset:256
	s_nop 1
	v_cndmask_b32_e32 v2, v231, v237, vcc
	v_cmp_lt_i32_e32 vcc, v238, v232
	v_lshlrev_b32_e32 v21, 2, v2
	ds_bpermute_b32 v4, v21, v102
	v_cndmask_b32_e32 v2, v231, v238, vcc
	v_lshlrev_b32_e32 v22, 2, v2
	ds_bpermute_b32 v2, v21, v118
	ds_bpermute_b32 v6, v21, v86
	ds_bpermute_b32 v8, v21, v78
	ds_bpermute_b32 v10, v21, v62
	ds_bpermute_b32 v12, v21, v46
	ds_bpermute_b32 v18, v21, v30
	ds_bpermute_b32 v21, v21, v20
	s_waitcnt lgkmcnt(6)
	v_add_f32_e32 v2, v118, v2
	v_add_f32_e32 v4, v102, v4
	s_waitcnt lgkmcnt(5)
	v_add_f32_e32 v6, v86, v6
	s_waitcnt lgkmcnt(4)
	v_add_f32_e32 v8, v78, v8
	s_waitcnt lgkmcnt(3)
	v_add_f32_e32 v10, v62, v10
	s_waitcnt lgkmcnt(2)
	v_add_f32_e32 v12, v46, v12
	s_waitcnt lgkmcnt(1)
	v_add_f32_e32 v18, v30, v18
	s_waitcnt lgkmcnt(0)
	v_add_f32_e32 v20, v20, v21
	ds_bpermute_b32 v3, v22, v2
	ds_bpermute_b32 v5, v22, v4
	ds_bpermute_b32 v7, v22, v6
	ds_bpermute_b32 v9, v22, v8
	ds_bpermute_b32 v11, v22, v10
	ds_bpermute_b32 v13, v22, v12
	ds_bpermute_b32 v19, v22, v18
	ds_bpermute_b32 v21, v22, v20
	s_and_saveexec_b64 s[18:19], s[40:41]
	s_cbranch_execz .LBB0_963
	s_waitcnt lgkmcnt(6)
	v_add_f32_e32 v4, v4, v5
	v_add_f32_e32 v2, v2, v3
	s_waitcnt lgkmcnt(0)
	v_add_f32_e32 v20, v20, v21
	v_add_f32_e32 v18, v18, v19
	v_add_f32_e32 v12, v12, v13
	v_add_f32_e32 v10, v10, v11
	v_add_f32_e32 v8, v8, v9
	v_add_f32_e32 v6, v6, v7
	ds_write2st64_b32 v245, v2, v4 offset1:1
	ds_write2st64_b32 v245, v6, v8 offset0:2 offset1:3
	ds_write2st64_b32 v246, v10, v12 offset1:1
	ds_write2st64_b32 v246, v18, v20 offset0:2 offset1:3
